# opt42: opt41 + load-segment closing waits merged into one s_waitcnt, compute-segment priority drop moved behind the barrier (8 GEMM loops)
# baseline (speedup 1.0000x reference)
; #define PG8_STAGE(bufoff, gbase, voff) do { _Pragma("unroll") for (int _i = 0; _i < 2; ++_i) \
;         __builtin_amdgcn_global_load_lds((const unsigned*)((const char*)(gbase) + (voff)[_i]), (LAS unsigned*)(lds + (bufoff) + ldsw + _i * 8192), 16, 0, 0); } while (0)
; #define PG8_LDA(dst, b, h) do { _Pragma("unroll") for (int m = 0; m < 4; ++m) _Pragma("unroll") for (int k = 0; k < 2; ++k) dst[m][k] = *(const LAS bf16x8*)(lds + PG8_SA(b, h) + aoff + m * 2048 + k * 1024); } while (0)
; #define PG8_LDB(dst, b, h) do { _Pragma("unroll") for (int n = 0; n < 2; ++n) _Pragma("unroll") for (int k = 0; k < 2; ++k) dst[n][k] = *(const LAS bf16x8*)(lds + PG8_SB(b, h) + boff + n * 2048 + k * 1024); } while (0)
; #define PG8_MMA(ai, bj, At, Bt) do { __builtin_amdgcn_s_setprio(1); _Pragma("unroll") for (int m = 0; m < 4; ++m) _Pragma("unroll") for (int n = 0; n < 2; ++n) _Pragma("unroll") for (int k = 0; k < 2; ++k) \
;         acc[ai][bj][m][n] = __builtin_amdgcn_mfma_f32_16x16x32_bf16(Bt[n][k], At[m][k], acc[ai][bj][m][n], 0, 0, 0); __builtin_amdgcn_s_setprio(0); } while (0)
; #define PG8_WAIT_V(n) asm volatile("s_waitcnt vmcnt(" #n ")" ::: "memory")
; #define PG8_WAIT_L(n) asm volatile("s_waitcnt lgkmcnt(" #n ")" ::: "memory")
; #define PG8_BAR __builtin_amdgcn_s_barrier()
; #define PG8_SCHED __builtin_amdgcn_sched_barrier(0)
; template <class Epi>
; __device__ __forceinline__ void gemm_phase(LAS unsigned char* lds, const Gemm g, const StaticOrder& S, const Epi& E) {
;     ...
;         for (int t = 0; t < nt; t += 2) {
;             const bool last = (t == nt - 2);
;             if constexpr (Epi::HAS_MID) { if (t == nt1) E.mid(acc, cur, wr, wc, fr, fq); }
;             const char* a1 = cA + ((Epi::HAS_MID && t >= nt1) ? dA2 : 0) + (size_t)(t + 1) * kstep;
;             const char* a2 = last ? nA : cA + ((Epi::HAS_MID && t + 2 >= nt1) ? dA2 : 0) + (size_t)(t + 2) * kstep; const char* b2 = last ? nB : cB + ((Epi::HAS_MID && t + 2 >= nt1) ? dB2 : 0) + (size_t)(t + 2) * kstep;
;             const char* a3 = a2 + kstep; const char* b3 = b2 + kstep;
;             PG8_LDB(B0, 0, 0); PG8_LDB(B1, 0, 1); PG8_SCHED; PG8_LDA(At, 0, 0); PG8_STAGE(PG8_SA(1, 1), a1 + hsA, voffA);
;             PG8_WAIT_V(8); PG8_WAIT_L(0); PG8_BAR; PG8_MMA(0, 0, At, B0); PG8_MMA(0, 1, At, B1); PG8_BAR; PG8_SCHED;
.LBB0_214:
	ds_read_b128 v[144:147], v155
	ds_read_b128 v[148:151], v155 offset:1024
	ds_read_b128 v[162:165], v155 offset:2048
	ds_read_b128 v[166:169], v155 offset:3072
	ds_read_b128 v[180:183], v156
	ds_read_b128 v[184:187], v156 offset:1024
	ds_read_b128 v[188:191], v156 offset:2048
	ds_read_b128 v[192:195], v156 offset:3072
	s_add_u32 s38, s58, 0xfffc0080
	s_addc_u32 s39, s59, -1
	s_cmp_eq_u32 s37, 12
	s_cselect_b32 s63, s6, s39
	s_cselect_b32 s62, s7, s38
	s_cselect_b32 s61, s11, s36
	s_cselect_b32 s60, s13, s35
	s_add_i32 m0, s19, 0xc000
	ds_read_b128 v[196:199], v157
	ds_read_b128 v[200:203], v157 offset:1024
	ds_read_b128 v[204:207], v157 offset:2048
	ds_read_b128 v[208:211], v157 offset:3072
	ds_read_b128 v[212:215], v157 offset:4096
	ds_read_b128 v[216:219], v157 offset:5120
	ds_read_b128 v[220:223], v157 offset:6144
	ds_read_b128 v[224:227], v157 offset:7168
	global_load_lds_dwordx4 v136, s[58:59]
	s_add_i32 m0, s19, 0xe000
	s_nop 0
	global_load_lds_dwordx4 v138, s[58:59]
	s_waitcnt vmcnt(8) lgkmcnt(0)

; #define PG8_MMA(ai, bj, At, Bt) do { __builtin_amdgcn_s_setprio(1); _Pragma("unroll") for (int m = 0; m < 4; ++m) _Pragma("unroll") for (int n = 0; n < 2; ++n) _Pragma("unroll") for (int k = 0; k < 2; ++k) \
;         acc[ai][bj][m][n] = __builtin_amdgcn_mfma_f32_16x16x32_bf16(Bt[n][k], At[m][k], acc[ai][bj][m][n], 0, 0, 0); __builtin_amdgcn_s_setprio(0); } while (0)
; #define PG8_WAIT_V(n) asm volatile("s_waitcnt vmcnt(" #n ")" ::: "memory")
; #define PG8_WAIT_L(n) asm volatile("s_waitcnt lgkmcnt(" #n ")" ::: "memory")
; #define PG8_BAR __builtin_amdgcn_s_barrier()
; #define PG8_SCHED __builtin_amdgcn_sched_barrier(0)
; template <class Epi>
; __device__ __forceinline__ void gemm_phase(LAS unsigned char* lds, const Gemm g, const StaticOrder& S, const Epi& E) {
;     ...
;             PG8_WAIT_V(8); PG8_WAIT_L(0); PG8_BAR; PG8_MMA(0, 0, At, B0); PG8_MMA(0, 1, At, B1); PG8_BAR; PG8_SCHED;
	s_setprio 1
	s_barrier

; #define PG8_MMA(ai, bj, At, Bt) do { __builtin_amdgcn_s_setprio(1); _Pragma("unroll") for (int m = 0; m < 4; ++m) _Pragma("unroll") for (int n = 0; n < 2; ++n) _Pragma("unroll") for (int k = 0; k < 2; ++k) \
;         acc[ai][bj][m][n] = __builtin_amdgcn_mfma_f32_16x16x32_bf16(Bt[n][k], At[m][k], acc[ai][bj][m][n], 0, 0, 0); __builtin_amdgcn_s_setprio(0); } while (0)
; #define PG8_WAIT_V(n) asm volatile("s_waitcnt vmcnt(" #n ")" ::: "memory")
; #define PG8_WAIT_L(n) asm volatile("s_waitcnt lgkmcnt(" #n ")" ::: "memory")
; #define PG8_BAR __builtin_amdgcn_s_barrier()
; #define PG8_SCHED __builtin_amdgcn_sched_barrier(0)
; template <class Epi>
; __device__ __forceinline__ void gemm_phase(LAS unsigned char* lds, const Gemm g, const StaticOrder& S, const Epi& E) {
;     ...
;             PG8_WAIT_V(8); PG8_WAIT_L(0); PG8_BAR; PG8_MMA(0, 0, At, B0); PG8_MMA(0, 1, At, B1); PG8_BAR; PG8_SCHED;
	v_mfma_f32_16x16x32_bf16 v[124:127], v[144:147], v[196:199], v[124:127]
	v_mfma_f32_16x16x32_bf16 v[120:123], v[162:165], v[196:199], v[120:123]
	v_mfma_f32_16x16x32_bf16 v[108:111], v[144:147], v[204:207], v[108:111]
	v_mfma_f32_16x16x32_bf16 v[104:107], v[162:165], v[204:207], v[104:107]
	v_mfma_f32_16x16x32_bf16 v[92:95], v[144:147], v[212:215], v[92:95]
	v_mfma_f32_16x16x32_bf16 v[88:91], v[162:165], v[212:215], v[88:91]
	v_mfma_f32_16x16x32_bf16 v[76:79], v[144:147], v[220:223], v[76:79]
	v_mfma_f32_16x16x32_bf16 v[72:75], v[162:165], v[220:223], v[72:75]
	v_mfma_f32_16x16x32_bf16 v[124:127], v[148:151], v[200:203], v[124:127]
	v_mfma_f32_16x16x32_bf16 v[120:123], v[166:169], v[200:203], v[120:123]
	v_mfma_f32_16x16x32_bf16 v[108:111], v[148:151], v[208:211], v[108:111]
	v_mfma_f32_16x16x32_bf16 v[104:107], v[166:169], v[208:211], v[104:107]
	v_mfma_f32_16x16x32_bf16 v[92:95], v[148:151], v[216:219], v[92:95]
	v_mfma_f32_16x16x32_bf16 v[88:91], v[166:169], v[216:219], v[88:91]
	v_mfma_f32_16x16x32_bf16 v[76:79], v[148:151], v[224:227], v[76:79]
	v_mfma_f32_16x16x32_bf16 v[72:75], v[166:169], v[224:227], v[72:75]


; #define PG8_STAGE(bufoff, gbase, voff) do { _Pragma("unroll") for (int _i = 0; _i < 2; ++_i) \
;         __builtin_amdgcn_global_load_lds((const unsigned*)((const char*)(gbase) + (voff)[_i]), (LAS unsigned*)(lds + (bufoff) + ldsw + _i * 8192), 16, 0, 0); } while (0)
; #define PG8_LDA(dst, b, h) do { _Pragma("unroll") for (int m = 0; m < 4; ++m) _Pragma("unroll") for (int k = 0; k < 2; ++k) dst[m][k] = *(const LAS bf16x8*)(lds + PG8_SA(b, h) + aoff + m * 2048 + k * 1024); } while (0)
; #define PG8_MMA(ai, bj, At, Bt) do { __builtin_amdgcn_s_setprio(1); _Pragma("unroll") for (int m = 0; m < 4; ++m) _Pragma("unroll") for (int n = 0; n < 2; ++n) _Pragma("unroll") for (int k = 0; k < 2; ++k) \
;         acc[ai][bj][m][n] = __builtin_amdgcn_mfma_f32_16x16x32_bf16(Bt[n][k], At[m][k], acc[ai][bj][m][n], 0, 0, 0); __builtin_amdgcn_s_setprio(0); } while (0)
; #define PG8_WAIT_V(n) asm volatile("s_waitcnt vmcnt(" #n ")" ::: "memory")
; #define PG8_WAIT_L(n) asm volatile("s_waitcnt lgkmcnt(" #n ")" ::: "memory")
; #define PG8_BAR __builtin_amdgcn_s_barrier()
; #define PG8_SCHED __builtin_amdgcn_sched_barrier(0)
; template <class Epi>
; __device__ __forceinline__ void gemm_phase(LAS unsigned char* lds, const Gemm g, const StaticOrder& S, const Epi& E) {
;     ...
;             PG8_WAIT_V(8); PG8_WAIT_L(0); PG8_BAR; PG8_MMA(0, 0, At, B0); PG8_MMA(0, 1, At, B1); PG8_BAR; PG8_SCHED;
;             PG8_LDA(At, 0, 1); PG8_STAGE(PG8_SB(0, 0), b2, voffB); PG8_STAGE(PG8_SB(0, 1), b2 + hsB, voffB); PG8_STAGE(PG8_SA(0, 0), a2, voffA);
;             PG8_WAIT_V(8); PG8_WAIT_L(0); PG8_BAR; PG8_MMA(1, 0, At, B0); PG8_MMA(1, 1, At, B1); PG8_BAR; PG8_SCHED;
	v_mfma_f32_16x16x32_bf16 v[116:119], v[180:183], v[196:199], v[116:119]
	v_mfma_f32_16x16x32_bf16 v[112:115], v[188:191], v[196:199], v[112:115]
	v_mfma_f32_16x16x32_bf16 v[100:103], v[180:183], v[204:207], v[100:103]
	v_mfma_f32_16x16x32_bf16 v[96:99], v[188:191], v[204:207], v[96:99]
	v_mfma_f32_16x16x32_bf16 v[84:87], v[180:183], v[212:215], v[84:87]
	v_mfma_f32_16x16x32_bf16 v[80:83], v[188:191], v[212:215], v[80:83]
	v_mfma_f32_16x16x32_bf16 v[68:71], v[180:183], v[220:223], v[68:71]
	v_mfma_f32_16x16x32_bf16 v[64:67], v[188:191], v[220:223], v[64:67]
	v_mfma_f32_16x16x32_bf16 v[116:119], v[184:187], v[200:203], v[116:119]
	v_mfma_f32_16x16x32_bf16 v[112:115], v[192:195], v[200:203], v[112:115]
	v_mfma_f32_16x16x32_bf16 v[100:103], v[184:187], v[208:211], v[100:103]
	v_mfma_f32_16x16x32_bf16 v[96:99], v[192:195], v[208:211], v[96:99]
	v_mfma_f32_16x16x32_bf16 v[84:87], v[184:187], v[216:219], v[84:87]
	v_mfma_f32_16x16x32_bf16 v[80:83], v[192:195], v[216:219], v[80:83]
	v_mfma_f32_16x16x32_bf16 v[68:71], v[184:187], v[224:227], v[68:71]
	v_mfma_f32_16x16x32_bf16 v[64:67], v[192:195], v[224:227], v[64:67]
	s_barrier
	s_setprio 0
	s_add_i32 s38, s30, s16
	s_mov_b32 m0, s38
	ds_read_b128 v[196:199], v157 offset:16384
	ds_read_b128 v[200:203], v157 offset:17408
	ds_read_b128 v[204:207], v157 offset:18432
	ds_read_b128 v[208:211], v157 offset:19456
	ds_read_b128 v[212:215], v157 offset:20480
	ds_read_b128 v[216:219], v157 offset:21504
	ds_read_b128 v[220:223], v157 offset:22528
	ds_read_b128 v[224:227], v157 offset:23552
	global_load_lds_dwordx4 v132, s[60:61]
	s_add_i32 m0, s38, 0x2000
	s_add_u32 s38, s60, 0x40000
	s_addc_u32 s39, s61, 0
	s_add_i32 s40, s31, s16
	global_load_lds_dwordx4 v128, s[60:61]
	s_mov_b32 m0, s40
	s_nop 0
	global_load_lds_dwordx4 v132, s[38:39]
	s_add_i32 m0, s40, 0x2000
	s_nop 0
	global_load_lds_dwordx4 v128, s[38:39]
	s_mov_b32 m0, s19
	s_nop 0
	global_load_lds_dwordx4 v134, s[62:63]
	s_mov_b32 m0, s22
	s_nop 0
	global_load_lds_dwordx4 v130, s[62:63]
	s_waitcnt vmcnt(8) lgkmcnt(0)

; #define PG8_MMA(ai, bj, At, Bt) do { __builtin_amdgcn_s_setprio(1); _Pragma("unroll") for (int m = 0; m < 4; ++m) _Pragma("unroll") for (int n = 0; n < 2; ++n) _Pragma("unroll") for (int k = 0; k < 2; ++k) \
;         acc[ai][bj][m][n] = __builtin_amdgcn_mfma_f32_16x16x32_bf16(Bt[n][k], At[m][k], acc[ai][bj][m][n], 0, 0, 0); __builtin_amdgcn_s_setprio(0); } while (0)
; #define PG8_WAIT_V(n) asm volatile("s_waitcnt vmcnt(" #n ")" ::: "memory")
; #define PG8_WAIT_L(n) asm volatile("s_waitcnt lgkmcnt(" #n ")" ::: "memory")
; #define PG8_BAR __builtin_amdgcn_s_barrier()
; #define PG8_SCHED __builtin_amdgcn_sched_barrier(0)
; template <class Epi>
; __device__ __forceinline__ void gemm_phase(LAS unsigned char* lds, const Gemm g, const StaticOrder& S, const Epi& E) {
;     ...
;             PG8_WAIT_V(8); PG8_WAIT_L(0); PG8_BAR; PG8_MMA(1, 0, At, B0); PG8_MMA(1, 1, At, B1); PG8_BAR; PG8_SCHED;
	s_setprio 1
	s_barrier

; #define PG8_MMA(ai, bj, At, Bt) do { __builtin_amdgcn_s_setprio(1); _Pragma("unroll") for (int m = 0; m < 4; ++m) _Pragma("unroll") for (int n = 0; n < 2; ++n) _Pragma("unroll") for (int k = 0; k < 2; ++k) \
;         acc[ai][bj][m][n] = __builtin_amdgcn_mfma_f32_16x16x32_bf16(Bt[n][k], At[m][k], acc[ai][bj][m][n], 0, 0, 0); __builtin_amdgcn_s_setprio(0); } while (0)
; #define PG8_WAIT_V(n) asm volatile("s_waitcnt vmcnt(" #n ")" ::: "memory")
; #define PG8_WAIT_L(n) asm volatile("s_waitcnt lgkmcnt(" #n ")" ::: "memory")
; #define PG8_BAR __builtin_amdgcn_s_barrier()
; #define PG8_SCHED __builtin_amdgcn_sched_barrier(0)
; template <class Epi>
; __device__ __forceinline__ void gemm_phase(LAS unsigned char* lds, const Gemm g, const StaticOrder& S, const Epi& E) {
;     ...
;             PG8_WAIT_V(8); PG8_WAIT_L(0); PG8_BAR; PG8_MMA(1, 0, At, B0); PG8_MMA(1, 1, At, B1); PG8_BAR; PG8_SCHED;
	v_mfma_f32_16x16x32_bf16 v[60:63], v[144:147], v[196:199], v[60:63]
	v_mfma_f32_16x16x32_bf16 v[56:59], v[162:165], v[196:199], v[56:59]
	v_mfma_f32_16x16x32_bf16 v[44:47], v[144:147], v[204:207], v[44:47]
	v_mfma_f32_16x16x32_bf16 v[40:43], v[162:165], v[204:207], v[40:43]
	v_mfma_f32_16x16x32_bf16 v[28:31], v[144:147], v[212:215], v[28:31]
	v_mfma_f32_16x16x32_bf16 v[24:27], v[162:165], v[212:215], v[24:27]
	v_mfma_f32_16x16x32_bf16 v[12:15], v[144:147], v[220:223], v[12:15]
	v_mfma_f32_16x16x32_bf16 v[8:11], v[162:165], v[220:223], v[8:11]
	v_mfma_f32_16x16x32_bf16 v[60:63], v[148:151], v[200:203], v[60:63]
	v_mfma_f32_16x16x32_bf16 v[56:59], v[166:169], v[200:203], v[56:59]
	v_mfma_f32_16x16x32_bf16 v[44:47], v[148:151], v[208:211], v[44:47]
	v_mfma_f32_16x16x32_bf16 v[40:43], v[166:169], v[208:211], v[40:43]
	v_mfma_f32_16x16x32_bf16 v[28:31], v[148:151], v[216:219], v[28:31]
	v_mfma_f32_16x16x32_bf16 v[24:27], v[166:169], v[216:219], v[24:27]
	v_mfma_f32_16x16x32_bf16 v[12:15], v[148:151], v[224:227], v[12:15]
	v_mfma_f32_16x16x32_bf16 v[8:11], v[166:169], v[224:227], v[8:11]


; #define PG8_STAGE(bufoff, gbase, voff) do { _Pragma("unroll") for (int _i = 0; _i < 2; ++_i) \
;         __builtin_amdgcn_global_load_lds((const unsigned*)((const char*)(gbase) + (voff)[_i]), (LAS unsigned*)(lds + (bufoff) + ldsw + _i * 8192), 16, 0, 0); } while (0)
; #define PG8_LDA(dst, b, h) do { _Pragma("unroll") for (int m = 0; m < 4; ++m) _Pragma("unroll") for (int k = 0; k < 2; ++k) dst[m][k] = *(const LAS bf16x8*)(lds + PG8_SA(b, h) + aoff + m * 2048 + k * 1024); } while (0)
; #define PG8_LDB(dst, b, h) do { _Pragma("unroll") for (int n = 0; n < 2; ++n) _Pragma("unroll") for (int k = 0; k < 2; ++k) dst[n][k] = *(const LAS bf16x8*)(lds + PG8_SB(b, h) + boff + n * 2048 + k * 1024); } while (0)
; #define PG8_MMA(ai, bj, At, Bt) do { __builtin_amdgcn_s_setprio(1); _Pragma("unroll") for (int m = 0; m < 4; ++m) _Pragma("unroll") for (int n = 0; n < 2; ++n) _Pragma("unroll") for (int k = 0; k < 2; ++k) \
;         acc[ai][bj][m][n] = __builtin_amdgcn_mfma_f32_16x16x32_bf16(Bt[n][k], At[m][k], acc[ai][bj][m][n], 0, 0, 0); __builtin_amdgcn_s_setprio(0); } while (0)
; #define PG8_WAIT_V(n) asm volatile("s_waitcnt vmcnt(" #n ")" ::: "memory")
; #define PG8_WAIT_L(n) asm volatile("s_waitcnt lgkmcnt(" #n ")" ::: "memory")
; #define PG8_BAR __builtin_amdgcn_s_barrier()
; #define PG8_SCHED __builtin_amdgcn_sched_barrier(0)
; template <class Epi>
; __device__ __forceinline__ void gemm_phase(LAS unsigned char* lds, const Gemm g, const StaticOrder& S, const Epi& E) {
;     ...
;             PG8_WAIT_V(8); PG8_WAIT_L(0); PG8_BAR; PG8_MMA(1, 0, At, B0); PG8_MMA(1, 1, At, B1); PG8_BAR; PG8_SCHED;
;             PG8_LDB(B0, 1, 0); PG8_LDB(B1, 1, 1); PG8_SCHED; PG8_LDA(At, 1, 0); PG8_STAGE(PG8_SA(0, 1), a2 + hsA, voffA);
;             PG8_WAIT_V(8); PG8_WAIT_L(0); PG8_BAR; PG8_MMA(0, 0, At, B0); PG8_MMA(0, 1, At, B1); PG8_BAR; PG8_SCHED;
	v_mfma_f32_16x16x32_bf16 v[52:55], v[180:183], v[196:199], v[52:55]
	v_mfma_f32_16x16x32_bf16 v[48:51], v[188:191], v[196:199], v[48:51]
	v_mfma_f32_16x16x32_bf16 v[36:39], v[180:183], v[204:207], v[36:39]
	v_mfma_f32_16x16x32_bf16 v[32:35], v[188:191], v[204:207], v[32:35]
	v_mfma_f32_16x16x32_bf16 v[20:23], v[180:183], v[212:215], v[20:23]
	v_mfma_f32_16x16x32_bf16 v[16:19], v[188:191], v[212:215], v[16:19]
	v_mfma_f32_16x16x32_bf16 v[4:7], v[180:183], v[220:223], v[4:7]
	v_mfma_f32_16x16x32_bf16 v[0:3], v[188:191], v[220:223], v[0:3]
	v_mfma_f32_16x16x32_bf16 v[52:55], v[184:187], v[200:203], v[52:55]
	v_mfma_f32_16x16x32_bf16 v[48:51], v[192:195], v[200:203], v[48:51]
	v_mfma_f32_16x16x32_bf16 v[36:39], v[184:187], v[208:211], v[36:39]
	v_mfma_f32_16x16x32_bf16 v[32:35], v[192:195], v[208:211], v[32:35]
	v_mfma_f32_16x16x32_bf16 v[20:23], v[184:187], v[216:219], v[20:23]
	v_mfma_f32_16x16x32_bf16 v[16:19], v[192:195], v[216:219], v[16:19]
	v_mfma_f32_16x16x32_bf16 v[4:7], v[184:187], v[224:227], v[4:7]
	v_mfma_f32_16x16x32_bf16 v[0:3], v[192:195], v[224:227], v[0:3]
	s_barrier
	s_setprio 0
	s_add_i32 s40, 0, 0x18000
	v_add_u32_e32 v159, s40, v153
	s_add_i32 s41, 0, 0x1c000
	ds_read_b128 v[144:147], v159
	ds_read_b128 v[148:151], v159 offset:1024
	ds_read_b128 v[162:165], v159 offset:2048
	ds_read_b128 v[166:169], v159 offset:3072
	v_add_u32_e32 v159, s41, v153
	ds_read_b128 v[180:183], v159
	ds_read_b128 v[184:187], v159 offset:1024
	ds_read_b128 v[188:191], v159 offset:2048
	ds_read_b128 v[192:195], v159 offset:3072
	s_add_u32 s38, s62, 0x40000
	s_addc_u32 s39, s63, 0
	s_mov_b32 m0, s23
	ds_read_b128 v[196:199], v157 offset:32768
	ds_read_b128 v[200:203], v157 offset:33792
	ds_read_b128 v[204:207], v157 offset:34816
	ds_read_b128 v[208:211], v157 offset:35840
	ds_read_b128 v[212:215], v157 offset:36864
	ds_read_b128 v[216:219], v157 offset:37888
	ds_read_b128 v[220:223], v157 offset:38912
	ds_read_b128 v[224:227], v157 offset:39936
	global_load_lds_dwordx4 v134, s[38:39]
	s_mov_b32 m0, s24
	s_nop 0
	global_load_lds_dwordx4 v130, s[38:39]
	s_waitcnt vmcnt(8) lgkmcnt(0)

; #define PG8_MMA(ai, bj, At, Bt) do { __builtin_amdgcn_s_setprio(1); _Pragma("unroll") for (int m = 0; m < 4; ++m) _Pragma("unroll") for (int n = 0; n < 2; ++n) _Pragma("unroll") for (int k = 0; k < 2; ++k) \
;         acc[ai][bj][m][n] = __builtin_amdgcn_mfma_f32_16x16x32_bf16(Bt[n][k], At[m][k], acc[ai][bj][m][n], 0, 0, 0); __builtin_amdgcn_s_setprio(0); } while (0)
; #define PG8_WAIT_V(n) asm volatile("s_waitcnt vmcnt(" #n ")" ::: "memory")
; #define PG8_WAIT_L(n) asm volatile("s_waitcnt lgkmcnt(" #n ")" ::: "memory")
; #define PG8_BAR __builtin_amdgcn_s_barrier()
; #define PG8_SCHED __builtin_amdgcn_sched_barrier(0)
; template <class Epi>
; __device__ __forceinline__ void gemm_phase(LAS unsigned char* lds, const Gemm g, const StaticOrder& S, const Epi& E) {
;     ...
;             PG8_WAIT_V(8); PG8_WAIT_L(0); PG8_BAR; PG8_MMA(0, 0, At, B0); PG8_MMA(0, 1, At, B1); PG8_BAR; PG8_SCHED;
	s_setprio 1
	s_barrier

; #define PG8_MMA(ai, bj, At, Bt) do { __builtin_amdgcn_s_setprio(1); _Pragma("unroll") for (int m = 0; m < 4; ++m) _Pragma("unroll") for (int n = 0; n < 2; ++n) _Pragma("unroll") for (int k = 0; k < 2; ++k) \
;         acc[ai][bj][m][n] = __builtin_amdgcn_mfma_f32_16x16x32_bf16(Bt[n][k], At[m][k], acc[ai][bj][m][n], 0, 0, 0); __builtin_amdgcn_s_setprio(0); } while (0)
; #define PG8_WAIT_V(n) asm volatile("s_waitcnt vmcnt(" #n ")" ::: "memory")
; #define PG8_WAIT_L(n) asm volatile("s_waitcnt lgkmcnt(" #n ")" ::: "memory")
; #define PG8_BAR __builtin_amdgcn_s_barrier()
; #define PG8_SCHED __builtin_amdgcn_sched_barrier(0)
; template <class Epi>
; __device__ __forceinline__ void gemm_phase(LAS unsigned char* lds, const Gemm g, const StaticOrder& S, const Epi& E) {
;     ...
;             PG8_WAIT_V(8); PG8_WAIT_L(0); PG8_BAR; PG8_MMA(0, 0, At, B0); PG8_MMA(0, 1, At, B1); PG8_BAR; PG8_SCHED;
	v_mfma_f32_16x16x32_bf16 v[124:127], v[144:147], v[196:199], v[124:127]
	v_mfma_f32_16x16x32_bf16 v[120:123], v[162:165], v[196:199], v[120:123]
	v_mfma_f32_16x16x32_bf16 v[108:111], v[144:147], v[204:207], v[108:111]
	v_mfma_f32_16x16x32_bf16 v[104:107], v[162:165], v[204:207], v[104:107]
	v_mfma_f32_16x16x32_bf16 v[92:95], v[144:147], v[212:215], v[92:95]
	v_mfma_f32_16x16x32_bf16 v[88:91], v[162:165], v[212:215], v[88:91]
	v_mfma_f32_16x16x32_bf16 v[76:79], v[144:147], v[220:223], v[76:79]
	v_mfma_f32_16x16x32_bf16 v[72:75], v[162:165], v[220:223], v[72:75]
	v_mfma_f32_16x16x32_bf16 v[124:127], v[148:151], v[200:203], v[124:127]
	v_mfma_f32_16x16x32_bf16 v[120:123], v[166:169], v[200:203], v[120:123]
	v_mfma_f32_16x16x32_bf16 v[108:111], v[148:151], v[208:211], v[108:111]
	v_mfma_f32_16x16x32_bf16 v[104:107], v[166:169], v[208:211], v[104:107]
	v_mfma_f32_16x16x32_bf16 v[92:95], v[148:151], v[216:219], v[92:95]
	v_mfma_f32_16x16x32_bf16 v[88:91], v[166:169], v[216:219], v[88:91]
	v_mfma_f32_16x16x32_bf16 v[76:79], v[148:151], v[224:227], v[76:79]
	v_mfma_f32_16x16x32_bf16 v[72:75], v[166:169], v[224:227], v[72:75]


; #define PG8_STAGE(bufoff, gbase, voff) do { _Pragma("unroll") for (int _i = 0; _i < 2; ++_i) \
;         __builtin_amdgcn_global_load_lds((const unsigned*)((const char*)(gbase) + (voff)[_i]), (LAS unsigned*)(lds + (bufoff) + ldsw + _i * 8192), 16, 0, 0); } while (0)
; #define PG8_LDA(dst, b, h) do { _Pragma("unroll") for (int m = 0; m < 4; ++m) _Pragma("unroll") for (int k = 0; k < 2; ++k) dst[m][k] = *(const LAS bf16x8*)(lds + PG8_SA(b, h) + aoff + m * 2048 + k * 1024); } while (0)
; #define PG8_MMA(ai, bj, At, Bt) do { __builtin_amdgcn_s_setprio(1); _Pragma("unroll") for (int m = 0; m < 4; ++m) _Pragma("unroll") for (int n = 0; n < 2; ++n) _Pragma("unroll") for (int k = 0; k < 2; ++k) \
;         acc[ai][bj][m][n] = __builtin_amdgcn_mfma_f32_16x16x32_bf16(Bt[n][k], At[m][k], acc[ai][bj][m][n], 0, 0, 0); __builtin_amdgcn_s_setprio(0); } while (0)
; #define PG8_WAIT_V(n) asm volatile("s_waitcnt vmcnt(" #n ")" ::: "memory")
; #define PG8_WAIT_L(n) asm volatile("s_waitcnt lgkmcnt(" #n ")" ::: "memory")
; #define PG8_BAR __builtin_amdgcn_s_barrier()
; #define PG8_SCHED __builtin_amdgcn_sched_barrier(0)
; template <class Epi>
; __device__ __forceinline__ void gemm_phase(LAS unsigned char* lds, const Gemm g, const StaticOrder& S, const Epi& E) {
;     ...
;             PG8_WAIT_V(8); PG8_WAIT_L(0); PG8_BAR; PG8_MMA(0, 0, At, B0); PG8_MMA(0, 1, At, B1); PG8_BAR; PG8_SCHED;
;             PG8_LDA(At, 1, 1); PG8_STAGE(PG8_SB(1, 0), b3, voffB); PG8_STAGE(PG8_SB(1, 1), b3 + hsB, voffB); PG8_STAGE(PG8_SA(1, 0), a3, voffA);
;             PG8_WAIT_V(8); PG8_WAIT_L(0); PG8_BAR; PG8_MMA(1, 0, At, B0); PG8_MMA(1, 1, At, B1); PG8_BAR; PG8_SCHED;
	v_mfma_f32_16x16x32_bf16 v[116:119], v[180:183], v[196:199], v[116:119]
	v_mfma_f32_16x16x32_bf16 v[112:115], v[188:191], v[196:199], v[112:115]
	v_mfma_f32_16x16x32_bf16 v[100:103], v[180:183], v[204:207], v[100:103]
	v_mfma_f32_16x16x32_bf16 v[96:99], v[188:191], v[204:207], v[96:99]
	v_mfma_f32_16x16x32_bf16 v[84:87], v[180:183], v[212:215], v[84:87]
	v_mfma_f32_16x16x32_bf16 v[80:83], v[188:191], v[212:215], v[80:83]
	v_mfma_f32_16x16x32_bf16 v[68:71], v[180:183], v[220:223], v[68:71]
	v_mfma_f32_16x16x32_bf16 v[64:67], v[188:191], v[220:223], v[64:67]
	v_mfma_f32_16x16x32_bf16 v[116:119], v[184:187], v[200:203], v[116:119]
	v_mfma_f32_16x16x32_bf16 v[112:115], v[192:195], v[200:203], v[112:115]
	v_mfma_f32_16x16x32_bf16 v[100:103], v[184:187], v[208:211], v[100:103]
	v_mfma_f32_16x16x32_bf16 v[96:99], v[192:195], v[208:211], v[96:99]
	v_mfma_f32_16x16x32_bf16 v[84:87], v[184:187], v[216:219], v[84:87]
	v_mfma_f32_16x16x32_bf16 v[80:83], v[192:195], v[216:219], v[80:83]
	v_mfma_f32_16x16x32_bf16 v[68:71], v[184:187], v[224:227], v[68:71]
	v_mfma_f32_16x16x32_bf16 v[64:67], v[192:195], v[224:227], v[64:67]
	s_barrier
	s_setprio 0
	s_add_u32 s98, s60, 0x80
	s_addc_u32 s99, s61, 0
	s_add_u32 s100, s62, 0x80
	s_addc_u32 s101, s63, 0
	s_add_i32 s38, s40, s16
	s_mov_b32 m0, s38
	ds_read_b128 v[196:199], v157 offset:49152
	ds_read_b128 v[200:203], v157 offset:50176
	ds_read_b128 v[204:207], v157 offset:51200
	ds_read_b128 v[208:211], v157 offset:52224
	ds_read_b128 v[212:215], v157 offset:53248
	ds_read_b128 v[216:219], v157 offset:54272
	ds_read_b128 v[220:223], v157 offset:55296
	ds_read_b128 v[224:227], v157 offset:56320
	global_load_lds_dwordx4 v132, s[98:99]
	s_add_i32 m0, s38, 0x2000
	s_add_u32 s38, s60, 0x40080
	s_addc_u32 s39, s61, 0
	s_add_i32 s40, s41, s16
	global_load_lds_dwordx4 v128, s[98:99]
	s_mov_b32 m0, s40
	s_nop 0
	global_load_lds_dwordx4 v132, s[38:39]
	s_add_i32 m0, s40, 0x2000
	s_nop 0
	global_load_lds_dwordx4 v128, s[38:39]
	s_mov_b32 m0, s25
	s_nop 0
	global_load_lds_dwordx4 v134, s[100:101]
	s_mov_b32 m0, s26
	s_nop 0
	global_load_lds_dwordx4 v130, s[100:101]
	s_waitcnt vmcnt(8) lgkmcnt(0)

; #define PG8_MMA(ai, bj, At, Bt) do { __builtin_amdgcn_s_setprio(1); _Pragma("unroll") for (int m = 0; m < 4; ++m) _Pragma("unroll") for (int n = 0; n < 2; ++n) _Pragma("unroll") for (int k = 0; k < 2; ++k) \
;         acc[ai][bj][m][n] = __builtin_amdgcn_mfma_f32_16x16x32_bf16(Bt[n][k], At[m][k], acc[ai][bj][m][n], 0, 0, 0); __builtin_amdgcn_s_setprio(0); } while (0)
; #define PG8_WAIT_V(n) asm volatile("s_waitcnt vmcnt(" #n ")" ::: "memory")
; #define PG8_WAIT_L(n) asm volatile("s_waitcnt lgkmcnt(" #n ")" ::: "memory")
; #define PG8_BAR __builtin_amdgcn_s_barrier()
; #define PG8_SCHED __builtin_amdgcn_sched_barrier(0)
; template <class Epi>
; __device__ __forceinline__ void gemm_phase(LAS unsigned char* lds, const Gemm g, const StaticOrder& S, const Epi& E) {
;     ...
;             PG8_WAIT_V(8); PG8_WAIT_L(0); PG8_BAR; PG8_MMA(1, 0, At, B0); PG8_MMA(1, 1, At, B1); PG8_BAR; PG8_SCHED;
	s_setprio 1
	s_barrier

; #define PG8_MMA(ai, bj, At, Bt) do { __builtin_amdgcn_s_setprio(1); _Pragma("unroll") for (int m = 0; m < 4; ++m) _Pragma("unroll") for (int n = 0; n < 2; ++n) _Pragma("unroll") for (int k = 0; k < 2; ++k) \
;         acc[ai][bj][m][n] = __builtin_amdgcn_mfma_f32_16x16x32_bf16(Bt[n][k], At[m][k], acc[ai][bj][m][n], 0, 0, 0); __builtin_amdgcn_s_setprio(0); } while (0)
; #define PG8_WAIT_V(n) asm volatile("s_waitcnt vmcnt(" #n ")" ::: "memory")
; #define PG8_WAIT_L(n) asm volatile("s_waitcnt lgkmcnt(" #n ")" ::: "memory")
; #define PG8_BAR __builtin_amdgcn_s_barrier()
; #define PG8_SCHED __builtin_amdgcn_sched_barrier(0)
; template <class Epi>
; __device__ __forceinline__ void gemm_phase(LAS unsigned char* lds, const Gemm g, const StaticOrder& S, const Epi& E) {
;     ...
;             PG8_WAIT_V(8); PG8_WAIT_L(0); PG8_BAR; PG8_MMA(1, 0, At, B0); PG8_MMA(1, 1, At, B1); PG8_BAR; PG8_SCHED;
	v_mfma_f32_16x16x32_bf16 v[60:63], v[144:147], v[196:199], v[60:63]
	v_mfma_f32_16x16x32_bf16 v[56:59], v[162:165], v[196:199], v[56:59]
	v_mfma_f32_16x16x32_bf16 v[44:47], v[144:147], v[204:207], v[44:47]
	v_mfma_f32_16x16x32_bf16 v[40:43], v[162:165], v[204:207], v[40:43]
	v_mfma_f32_16x16x32_bf16 v[28:31], v[144:147], v[212:215], v[28:31]
	v_mfma_f32_16x16x32_bf16 v[24:27], v[162:165], v[212:215], v[24:27]
	v_mfma_f32_16x16x32_bf16 v[12:15], v[144:147], v[220:223], v[12:15]
	v_mfma_f32_16x16x32_bf16 v[8:11], v[162:165], v[220:223], v[8:11]
	v_mfma_f32_16x16x32_bf16 v[60:63], v[148:151], v[200:203], v[60:63]
	v_mfma_f32_16x16x32_bf16 v[56:59], v[166:169], v[200:203], v[56:59]
	v_mfma_f32_16x16x32_bf16 v[44:47], v[148:151], v[208:211], v[44:47]
	v_mfma_f32_16x16x32_bf16 v[40:43], v[166:169], v[208:211], v[40:43]
	v_mfma_f32_16x16x32_bf16 v[28:31], v[148:151], v[216:219], v[28:31]
	v_mfma_f32_16x16x32_bf16 v[24:27], v[166:169], v[216:219], v[24:27]
	v_mfma_f32_16x16x32_bf16 v[12:15], v[148:151], v[224:227], v[12:15]
	v_mfma_f32_16x16x32_bf16 v[8:11], v[166:169], v[224:227], v[8:11]


; #define PG8_MMA(ai, bj, At, Bt) do { __builtin_amdgcn_s_setprio(1); _Pragma("unroll") for (int m = 0; m < 4; ++m) _Pragma("unroll") for (int n = 0; n < 2; ++n) _Pragma("unroll") for (int k = 0; k < 2; ++k) \
;         acc[ai][bj][m][n] = __builtin_amdgcn_mfma_f32_16x16x32_bf16(Bt[n][k], At[m][k], acc[ai][bj][m][n], 0, 0, 0); __builtin_amdgcn_s_setprio(0); } while (0)
; #define PG8_WAIT_V(n) asm volatile("s_waitcnt vmcnt(" #n ")" ::: "memory")
; #define PG8_WAIT_L(n) asm volatile("s_waitcnt lgkmcnt(" #n ")" ::: "memory")
; #define PG8_BAR __builtin_amdgcn_s_barrier()
; #define PG8_SCHED __builtin_amdgcn_sched_barrier(0)
; template <class Epi>
; __device__ __forceinline__ void gemm_phase(LAS unsigned char* lds, const Gemm g, const StaticOrder& S, const Epi& E) {
;     ...
;             PG8_WAIT_V(8); PG8_WAIT_L(0); PG8_BAR; PG8_MMA(1, 0, At, B0); PG8_MMA(1, 1, At, B1); PG8_BAR; PG8_SCHED;
;         }
;         if (wr == 0) PG8_BAR;
	v_mfma_f32_16x16x32_bf16 v[52:55], v[180:183], v[196:199], v[52:55]
	v_mfma_f32_16x16x32_bf16 v[48:51], v[188:191], v[196:199], v[48:51]
	v_mfma_f32_16x16x32_bf16 v[36:39], v[180:183], v[204:207], v[36:39]
	v_mfma_f32_16x16x32_bf16 v[32:35], v[188:191], v[204:207], v[32:35]
	v_mfma_f32_16x16x32_bf16 v[20:23], v[180:183], v[212:215], v[20:23]
	v_mfma_f32_16x16x32_bf16 v[16:19], v[188:191], v[212:215], v[16:19]
	v_mfma_f32_16x16x32_bf16 v[4:7], v[180:183], v[220:223], v[4:7]
	v_mfma_f32_16x16x32_bf16 v[0:3], v[188:191], v[220:223], v[0:3]
	v_mfma_f32_16x16x32_bf16 v[52:55], v[184:187], v[200:203], v[52:55]
	v_mfma_f32_16x16x32_bf16 v[48:51], v[192:195], v[200:203], v[48:51]
	v_mfma_f32_16x16x32_bf16 v[36:39], v[184:187], v[208:211], v[36:39]
	v_mfma_f32_16x16x32_bf16 v[32:35], v[192:195], v[208:211], v[32:35]
	v_mfma_f32_16x16x32_bf16 v[20:23], v[184:187], v[216:219], v[20:23]
	v_mfma_f32_16x16x32_bf16 v[16:19], v[192:195], v[216:219], v[16:19]
	v_mfma_f32_16x16x32_bf16 v[4:7], v[184:187], v[224:227], v[4:7]
	v_mfma_f32_16x16x32_bf16 v[0:3], v[192:195], v[224:227], v[0:3]
	s_barrier
	s_setprio 0
	s_add_i32 s37, s37, 2
	s_add_u32 s58, s58, 0x100
	s_addc_u32 s59, s59, 0
	s_add_u32 s35, s35, 0x100
	s_addc_u32 s36, s36, 0
	s_cmp_gt_u32 s37, 13
	s_cbranch_scc0 .LBB0_214
	s_and_b64 vcc, exec, s[8:9]
	s_cbranch_vccz .LBB0_217
	s_barrier

; #define PG8_STAGE(bufoff, gbase, voff) do { _Pragma("unroll") for (int _i = 0; _i < 2; ++_i) \
;         __builtin_amdgcn_global_load_lds((const unsigned*)((const char*)(gbase) + (voff)[_i]), (LAS unsigned*)(lds + (bufoff) + ldsw + _i * 8192), 16, 0, 0); } while (0)
; #define PG8_LDA(dst, b, h) do { _Pragma("unroll") for (int m = 0; m < 4; ++m) _Pragma("unroll") for (int k = 0; k < 2; ++k) dst[m][k] = *(const LAS bf16x8*)(lds + PG8_SA(b, h) + aoff + m * 2048 + k * 1024); } while (0)
; #define PG8_LDB(dst, b, h) do { _Pragma("unroll") for (int n = 0; n < 2; ++n) _Pragma("unroll") for (int k = 0; k < 2; ++k) dst[n][k] = *(const LAS bf16x8*)(lds + PG8_SB(b, h) + boff + n * 2048 + k * 1024); } while (0)
; #define PG8_MMA(ai, bj, At, Bt) do { __builtin_amdgcn_s_setprio(1); _Pragma("unroll") for (int m = 0; m < 4; ++m) _Pragma("unroll") for (int n = 0; n < 2; ++n) _Pragma("unroll") for (int k = 0; k < 2; ++k) \
;         acc[ai][bj][m][n] = __builtin_amdgcn_mfma_f32_16x16x32_bf16(Bt[n][k], At[m][k], acc[ai][bj][m][n], 0, 0, 0); __builtin_amdgcn_s_setprio(0); } while (0)
; #define PG8_WAIT_V(n) asm volatile("s_waitcnt vmcnt(" #n ")" ::: "memory")
; #define PG8_WAIT_L(n) asm volatile("s_waitcnt lgkmcnt(" #n ")" ::: "memory")
; #define PG8_BAR __builtin_amdgcn_s_barrier()
; #define PG8_SCHED __builtin_amdgcn_sched_barrier(0)
; template <class Epi>
; __device__ __forceinline__ void gemm_phase(LAS unsigned char* lds, const Gemm g, const StaticOrder& S, const Epi& E) {
;     ...
;         for (int t = 0; t < nt; t += 2) {
;             const bool last = (t == nt - 2);
;             if constexpr (Epi::HAS_MID) { if (t == nt1) E.mid(acc, cur, wr, wc, fr, fq); }
;             const char* a1 = cA + ((Epi::HAS_MID && t >= nt1) ? dA2 : 0) + (size_t)(t + 1) * kstep;
;             const char* a2 = last ? nA : cA + ((Epi::HAS_MID && t + 2 >= nt1) ? dA2 : 0) + (size_t)(t + 2) * kstep; const char* b2 = last ? nB : cB + ((Epi::HAS_MID && t + 2 >= nt1) ? dB2 : 0) + (size_t)(t + 2) * kstep;
;             const char* a3 = a2 + kstep; const char* b3 = b2 + kstep;
;             PG8_LDB(B0, 0, 0); PG8_LDB(B1, 0, 1); PG8_SCHED; PG8_LDA(At, 0, 0); PG8_STAGE(PG8_SA(1, 1), a1 + hsA, voffA);
;             PG8_WAIT_V(8); PG8_WAIT_L(0); PG8_BAR; PG8_MMA(0, 0, At, B0); PG8_MMA(0, 1, At, B1); PG8_BAR; PG8_SCHED;
.LBB0_296:
	ds_read_b128 v[144:147], v157
	ds_read_b128 v[148:151], v157 offset:1024
	ds_read_b128 v[164:167], v157 offset:2048
	ds_read_b128 v[168:171], v157 offset:3072
	ds_read_b128 v[180:183], v158
	ds_read_b128 v[184:187], v158 offset:1024
	ds_read_b128 v[188:191], v158 offset:2048
	ds_read_b128 v[192:195], v158 offset:3072
	s_add_u32 s60, s12, 0x100
	s_addc_u32 s61, s13, 0
	s_cmp_eq_u32 s34, 40
	s_cselect_b32 s65, s1, s61
	s_cselect_b32 s64, s0, s60
	s_cselect_b32 s63, s59, s7
	s_cselect_b32 s62, s58, s6
	s_add_i32 m0, s5, 0xc000
	ds_read_b128 v[196:199], v159
	ds_read_b128 v[200:203], v159 offset:1024
	ds_read_b128 v[204:207], v159 offset:2048
	ds_read_b128 v[208:211], v159 offset:3072
	ds_read_b128 v[212:215], v159 offset:4096
	ds_read_b128 v[216:219], v159 offset:5120
	ds_read_b128 v[220:223], v159 offset:6144
	ds_read_b128 v[224:227], v159 offset:7168
	global_load_lds_dwordx4 v136, s[12:13]
	s_add_i32 m0, s5, 0xe000
	s_nop 0
	global_load_lds_dwordx4 v138, s[12:13]
	s_waitcnt vmcnt(8) lgkmcnt(0)

; #define PG8_MMA(ai, bj, At, Bt) do { __builtin_amdgcn_s_setprio(1); _Pragma("unroll") for (int m = 0; m < 4; ++m) _Pragma("unroll") for (int n = 0; n < 2; ++n) _Pragma("unroll") for (int k = 0; k < 2; ++k) \
;         acc[ai][bj][m][n] = __builtin_amdgcn_mfma_f32_16x16x32_bf16(Bt[n][k], At[m][k], acc[ai][bj][m][n], 0, 0, 0); __builtin_amdgcn_s_setprio(0); } while (0)
; #define PG8_WAIT_V(n) asm volatile("s_waitcnt vmcnt(" #n ")" ::: "memory")
; #define PG8_WAIT_L(n) asm volatile("s_waitcnt lgkmcnt(" #n ")" ::: "memory")
; #define PG8_BAR __builtin_amdgcn_s_barrier()
; #define PG8_SCHED __builtin_amdgcn_sched_barrier(0)
; template <class Epi>
; __device__ __forceinline__ void gemm_phase(LAS unsigned char* lds, const Gemm g, const StaticOrder& S, const Epi& E) {
;     ...
;             PG8_WAIT_V(8); PG8_WAIT_L(0); PG8_BAR; PG8_MMA(0, 0, At, B0); PG8_MMA(0, 1, At, B1); PG8_BAR; PG8_SCHED;
	s_setprio 1
	s_barrier

; #define PG8_MMA(ai, bj, At, Bt) do { __builtin_amdgcn_s_setprio(1); _Pragma("unroll") for (int m = 0; m < 4; ++m) _Pragma("unroll") for (int n = 0; n < 2; ++n) _Pragma("unroll") for (int k = 0; k < 2; ++k) \
;         acc[ai][bj][m][n] = __builtin_amdgcn_mfma_f32_16x16x32_bf16(Bt[n][k], At[m][k], acc[ai][bj][m][n], 0, 0, 0); __builtin_amdgcn_s_setprio(0); } while (0)
; #define PG8_WAIT_V(n) asm volatile("s_waitcnt vmcnt(" #n ")" ::: "memory")
; #define PG8_WAIT_L(n) asm volatile("s_waitcnt lgkmcnt(" #n ")" ::: "memory")
; #define PG8_BAR __builtin_amdgcn_s_barrier()
; #define PG8_SCHED __builtin_amdgcn_sched_barrier(0)
; template <class Epi>
; __device__ __forceinline__ void gemm_phase(LAS unsigned char* lds, const Gemm g, const StaticOrder& S, const Epi& E) {
;     ...
;             PG8_WAIT_V(8); PG8_WAIT_L(0); PG8_BAR; PG8_MMA(0, 0, At, B0); PG8_MMA(0, 1, At, B1); PG8_BAR; PG8_SCHED;
	v_mfma_f32_16x16x32_bf16 v[124:127], v[144:147], v[196:199], v[124:127]
	v_mfma_f32_16x16x32_bf16 v[120:123], v[164:167], v[196:199], v[120:123]
	v_mfma_f32_16x16x32_bf16 v[108:111], v[144:147], v[204:207], v[108:111]
	v_mfma_f32_16x16x32_bf16 v[104:107], v[164:167], v[204:207], v[104:107]
	v_mfma_f32_16x16x32_bf16 v[92:95], v[144:147], v[212:215], v[92:95]
	v_mfma_f32_16x16x32_bf16 v[88:91], v[164:167], v[212:215], v[88:91]
	v_mfma_f32_16x16x32_bf16 v[76:79], v[144:147], v[220:223], v[76:79]
	v_mfma_f32_16x16x32_bf16 v[72:75], v[164:167], v[220:223], v[72:75]
	v_mfma_f32_16x16x32_bf16 v[124:127], v[148:151], v[200:203], v[124:127]
	v_mfma_f32_16x16x32_bf16 v[120:123], v[168:171], v[200:203], v[120:123]
	v_mfma_f32_16x16x32_bf16 v[108:111], v[148:151], v[208:211], v[108:111]
	v_mfma_f32_16x16x32_bf16 v[104:107], v[168:171], v[208:211], v[104:107]
	v_mfma_f32_16x16x32_bf16 v[92:95], v[148:151], v[216:219], v[92:95]
	v_mfma_f32_16x16x32_bf16 v[88:91], v[168:171], v[216:219], v[88:91]
	v_mfma_f32_16x16x32_bf16 v[76:79], v[148:151], v[224:227], v[76:79]
	v_mfma_f32_16x16x32_bf16 v[72:75], v[168:171], v[224:227], v[72:75]


; #define PG8_STAGE(bufoff, gbase, voff) do { _Pragma("unroll") for (int _i = 0; _i < 2; ++_i) \
;         __builtin_amdgcn_global_load_lds((const unsigned*)((const char*)(gbase) + (voff)[_i]), (LAS unsigned*)(lds + (bufoff) + ldsw + _i * 8192), 16, 0, 0); } while (0)
; #define PG8_LDA(dst, b, h) do { _Pragma("unroll") for (int m = 0; m < 4; ++m) _Pragma("unroll") for (int k = 0; k < 2; ++k) dst[m][k] = *(const LAS bf16x8*)(lds + PG8_SA(b, h) + aoff + m * 2048 + k * 1024); } while (0)
; #define PG8_MMA(ai, bj, At, Bt) do { __builtin_amdgcn_s_setprio(1); _Pragma("unroll") for (int m = 0; m < 4; ++m) _Pragma("unroll") for (int n = 0; n < 2; ++n) _Pragma("unroll") for (int k = 0; k < 2; ++k) \
;         acc[ai][bj][m][n] = __builtin_amdgcn_mfma_f32_16x16x32_bf16(Bt[n][k], At[m][k], acc[ai][bj][m][n], 0, 0, 0); __builtin_amdgcn_s_setprio(0); } while (0)
; #define PG8_WAIT_V(n) asm volatile("s_waitcnt vmcnt(" #n ")" ::: "memory")
; #define PG8_WAIT_L(n) asm volatile("s_waitcnt lgkmcnt(" #n ")" ::: "memory")
; #define PG8_BAR __builtin_amdgcn_s_barrier()
; #define PG8_SCHED __builtin_amdgcn_sched_barrier(0)
; template <class Epi>
; __device__ __forceinline__ void gemm_phase(LAS unsigned char* lds, const Gemm g, const StaticOrder& S, const Epi& E) {
;     ...
;             PG8_WAIT_V(8); PG8_WAIT_L(0); PG8_BAR; PG8_MMA(0, 0, At, B0); PG8_MMA(0, 1, At, B1); PG8_BAR; PG8_SCHED;
;             PG8_LDA(At, 0, 1); PG8_STAGE(PG8_SB(0, 0), b2, voffB); PG8_STAGE(PG8_SB(0, 1), b2 + hsB, voffB); PG8_STAGE(PG8_SA(0, 0), a2, voffA);
;             PG8_WAIT_V(8); PG8_WAIT_L(0); PG8_BAR; PG8_MMA(1, 0, At, B0); PG8_MMA(1, 1, At, B1); PG8_BAR; PG8_SCHED;
	v_mfma_f32_16x16x32_bf16 v[116:119], v[180:183], v[196:199], v[116:119]
	v_mfma_f32_16x16x32_bf16 v[112:115], v[188:191], v[196:199], v[112:115]
	v_mfma_f32_16x16x32_bf16 v[100:103], v[180:183], v[204:207], v[100:103]
	v_mfma_f32_16x16x32_bf16 v[96:99], v[188:191], v[204:207], v[96:99]
	v_mfma_f32_16x16x32_bf16 v[84:87], v[180:183], v[212:215], v[84:87]
	v_mfma_f32_16x16x32_bf16 v[80:83], v[188:191], v[212:215], v[80:83]
	v_mfma_f32_16x16x32_bf16 v[68:71], v[180:183], v[220:223], v[68:71]
	v_mfma_f32_16x16x32_bf16 v[64:67], v[188:191], v[220:223], v[64:67]
	v_mfma_f32_16x16x32_bf16 v[116:119], v[184:187], v[200:203], v[116:119]
	v_mfma_f32_16x16x32_bf16 v[112:115], v[192:195], v[200:203], v[112:115]
	v_mfma_f32_16x16x32_bf16 v[100:103], v[184:187], v[208:211], v[100:103]
	v_mfma_f32_16x16x32_bf16 v[96:99], v[192:195], v[208:211], v[96:99]
	v_mfma_f32_16x16x32_bf16 v[84:87], v[184:187], v[216:219], v[84:87]
	v_mfma_f32_16x16x32_bf16 v[80:83], v[192:195], v[216:219], v[80:83]
	v_mfma_f32_16x16x32_bf16 v[68:71], v[184:187], v[224:227], v[68:71]
	v_mfma_f32_16x16x32_bf16 v[64:67], v[192:195], v[224:227], v[64:67]
	s_barrier
	s_setprio 0
	s_add_i32 s12, s27, s4
	s_mov_b32 m0, s12
	ds_read_b128 v[196:199], v159 offset:16384
	ds_read_b128 v[200:203], v159 offset:17408
	ds_read_b128 v[204:207], v159 offset:18432
	ds_read_b128 v[208:211], v159 offset:19456
	ds_read_b128 v[212:215], v159 offset:20480
	ds_read_b128 v[216:219], v159 offset:21504
	ds_read_b128 v[220:223], v159 offset:22528
	ds_read_b128 v[224:227], v159 offset:23552
	global_load_lds_dwordx4 v130, s[62:63]
	s_add_i32 m0, s12, 0x2000
	s_add_u32 s12, s62, 0xb0000
	s_addc_u32 s13, s63, 0
	s_add_i32 s35, s28, s4
	global_load_lds_dwordx4 v134, s[62:63]
	s_mov_b32 m0, s35
	s_nop 0
	global_load_lds_dwordx4 v130, s[12:13]
	s_add_i32 m0, s35, 0x2000
	s_nop 0
	global_load_lds_dwordx4 v134, s[12:13]
	s_mov_b32 m0, s5
	s_nop 0
	global_load_lds_dwordx4 v128, s[64:65]
	s_mov_b32 m0, s16
	s_nop 0
	global_load_lds_dwordx4 v132, s[64:65]
	s_waitcnt vmcnt(8) lgkmcnt(0)

; #define PG8_MMA(ai, bj, At, Bt) do { __builtin_amdgcn_s_setprio(1); _Pragma("unroll") for (int m = 0; m < 4; ++m) _Pragma("unroll") for (int n = 0; n < 2; ++n) _Pragma("unroll") for (int k = 0; k < 2; ++k) \
;         acc[ai][bj][m][n] = __builtin_amdgcn_mfma_f32_16x16x32_bf16(Bt[n][k], At[m][k], acc[ai][bj][m][n], 0, 0, 0); __builtin_amdgcn_s_setprio(0); } while (0)
; #define PG8_WAIT_V(n) asm volatile("s_waitcnt vmcnt(" #n ")" ::: "memory")
; #define PG8_WAIT_L(n) asm volatile("s_waitcnt lgkmcnt(" #n ")" ::: "memory")
; #define PG8_BAR __builtin_amdgcn_s_barrier()
; #define PG8_SCHED __builtin_amdgcn_sched_barrier(0)
; template <class Epi>
; __device__ __forceinline__ void gemm_phase(LAS unsigned char* lds, const Gemm g, const StaticOrder& S, const Epi& E) {
;     ...
;             PG8_WAIT_V(8); PG8_WAIT_L(0); PG8_BAR; PG8_MMA(1, 0, At, B0); PG8_MMA(1, 1, At, B1); PG8_BAR; PG8_SCHED;
	s_setprio 1
	s_barrier

; #define PG8_MMA(ai, bj, At, Bt) do { __builtin_amdgcn_s_setprio(1); _Pragma("unroll") for (int m = 0; m < 4; ++m) _Pragma("unroll") for (int n = 0; n < 2; ++n) _Pragma("unroll") for (int k = 0; k < 2; ++k) \
;         acc[ai][bj][m][n] = __builtin_amdgcn_mfma_f32_16x16x32_bf16(Bt[n][k], At[m][k], acc[ai][bj][m][n], 0, 0, 0); __builtin_amdgcn_s_setprio(0); } while (0)
; #define PG8_WAIT_V(n) asm volatile("s_waitcnt vmcnt(" #n ")" ::: "memory")
; #define PG8_WAIT_L(n) asm volatile("s_waitcnt lgkmcnt(" #n ")" ::: "memory")
; #define PG8_BAR __builtin_amdgcn_s_barrier()
; #define PG8_SCHED __builtin_amdgcn_sched_barrier(0)
; template <class Epi>
; __device__ __forceinline__ void gemm_phase(LAS unsigned char* lds, const Gemm g, const StaticOrder& S, const Epi& E) {
;     ...
;             PG8_WAIT_V(8); PG8_WAIT_L(0); PG8_BAR; PG8_MMA(1, 0, At, B0); PG8_MMA(1, 1, At, B1); PG8_BAR; PG8_SCHED;
	v_mfma_f32_16x16x32_bf16 v[60:63], v[144:147], v[196:199], v[60:63]
	v_mfma_f32_16x16x32_bf16 v[56:59], v[164:167], v[196:199], v[56:59]
	v_mfma_f32_16x16x32_bf16 v[44:47], v[144:147], v[204:207], v[44:47]
	v_mfma_f32_16x16x32_bf16 v[40:43], v[164:167], v[204:207], v[40:43]
	v_mfma_f32_16x16x32_bf16 v[28:31], v[144:147], v[212:215], v[28:31]
	v_mfma_f32_16x16x32_bf16 v[24:27], v[164:167], v[212:215], v[24:27]
	v_mfma_f32_16x16x32_bf16 v[12:15], v[144:147], v[220:223], v[12:15]
	v_mfma_f32_16x16x32_bf16 v[8:11], v[164:167], v[220:223], v[8:11]
	v_mfma_f32_16x16x32_bf16 v[60:63], v[148:151], v[200:203], v[60:63]
	v_mfma_f32_16x16x32_bf16 v[56:59], v[168:171], v[200:203], v[56:59]
	v_mfma_f32_16x16x32_bf16 v[44:47], v[148:151], v[208:211], v[44:47]
	v_mfma_f32_16x16x32_bf16 v[40:43], v[168:171], v[208:211], v[40:43]
	v_mfma_f32_16x16x32_bf16 v[28:31], v[148:151], v[216:219], v[28:31]
	v_mfma_f32_16x16x32_bf16 v[24:27], v[168:171], v[216:219], v[24:27]
	v_mfma_f32_16x16x32_bf16 v[12:15], v[148:151], v[224:227], v[12:15]
	v_mfma_f32_16x16x32_bf16 v[8:11], v[168:171], v[224:227], v[8:11]


; #define PG8_STAGE(bufoff, gbase, voff) do { _Pragma("unroll") for (int _i = 0; _i < 2; ++_i) \
;         __builtin_amdgcn_global_load_lds((const unsigned*)((const char*)(gbase) + (voff)[_i]), (LAS unsigned*)(lds + (bufoff) + ldsw + _i * 8192), 16, 0, 0); } while (0)
; #define PG8_LDA(dst, b, h) do { _Pragma("unroll") for (int m = 0; m < 4; ++m) _Pragma("unroll") for (int k = 0; k < 2; ++k) dst[m][k] = *(const LAS bf16x8*)(lds + PG8_SA(b, h) + aoff + m * 2048 + k * 1024); } while (0)
; #define PG8_LDB(dst, b, h) do { _Pragma("unroll") for (int n = 0; n < 2; ++n) _Pragma("unroll") for (int k = 0; k < 2; ++k) dst[n][k] = *(const LAS bf16x8*)(lds + PG8_SB(b, h) + boff + n * 2048 + k * 1024); } while (0)
; #define PG8_MMA(ai, bj, At, Bt) do { __builtin_amdgcn_s_setprio(1); _Pragma("unroll") for (int m = 0; m < 4; ++m) _Pragma("unroll") for (int n = 0; n < 2; ++n) _Pragma("unroll") for (int k = 0; k < 2; ++k) \
;         acc[ai][bj][m][n] = __builtin_amdgcn_mfma_f32_16x16x32_bf16(Bt[n][k], At[m][k], acc[ai][bj][m][n], 0, 0, 0); __builtin_amdgcn_s_setprio(0); } while (0)
; #define PG8_WAIT_V(n) asm volatile("s_waitcnt vmcnt(" #n ")" ::: "memory")
; #define PG8_WAIT_L(n) asm volatile("s_waitcnt lgkmcnt(" #n ")" ::: "memory")
; #define PG8_BAR __builtin_amdgcn_s_barrier()
; #define PG8_SCHED __builtin_amdgcn_sched_barrier(0)
; template <class Epi>
; __device__ __forceinline__ void gemm_phase(LAS unsigned char* lds, const Gemm g, const StaticOrder& S, const Epi& E) {
;     ...
;             PG8_WAIT_V(8); PG8_WAIT_L(0); PG8_BAR; PG8_MMA(1, 0, At, B0); PG8_MMA(1, 1, At, B1); PG8_BAR; PG8_SCHED;
;             PG8_LDB(B0, 1, 0); PG8_LDB(B1, 1, 1); PG8_SCHED; PG8_LDA(At, 1, 0); PG8_STAGE(PG8_SA(0, 1), a2 + hsA, voffA);
;             PG8_WAIT_V(8); PG8_WAIT_L(0); PG8_BAR; PG8_MMA(0, 0, At, B0); PG8_MMA(0, 1, At, B1); PG8_BAR; PG8_SCHED;
	v_mfma_f32_16x16x32_bf16 v[52:55], v[180:183], v[196:199], v[52:55]
	v_mfma_f32_16x16x32_bf16 v[48:51], v[188:191], v[196:199], v[48:51]
	v_mfma_f32_16x16x32_bf16 v[36:39], v[180:183], v[204:207], v[36:39]
	v_mfma_f32_16x16x32_bf16 v[32:35], v[188:191], v[204:207], v[32:35]
	v_mfma_f32_16x16x32_bf16 v[20:23], v[180:183], v[212:215], v[20:23]
	v_mfma_f32_16x16x32_bf16 v[16:19], v[188:191], v[212:215], v[16:19]
	v_mfma_f32_16x16x32_bf16 v[4:7], v[180:183], v[220:223], v[4:7]
	v_mfma_f32_16x16x32_bf16 v[0:3], v[188:191], v[220:223], v[0:3]
	v_mfma_f32_16x16x32_bf16 v[52:55], v[184:187], v[200:203], v[52:55]
	v_mfma_f32_16x16x32_bf16 v[48:51], v[192:195], v[200:203], v[48:51]
	v_mfma_f32_16x16x32_bf16 v[36:39], v[184:187], v[208:211], v[36:39]
	v_mfma_f32_16x16x32_bf16 v[32:35], v[192:195], v[208:211], v[32:35]
	v_mfma_f32_16x16x32_bf16 v[20:23], v[184:187], v[216:219], v[20:23]
	v_mfma_f32_16x16x32_bf16 v[16:19], v[192:195], v[216:219], v[16:19]
	v_mfma_f32_16x16x32_bf16 v[4:7], v[184:187], v[224:227], v[4:7]
	v_mfma_f32_16x16x32_bf16 v[0:3], v[192:195], v[224:227], v[0:3]
	s_barrier
	s_setprio 0
	s_add_i32 s35, 0, 0x18000
	v_add_u32_e32 v163, s35, v155
	s_add_i32 s36, 0, 0x1c000
	ds_read_b128 v[144:147], v163
	ds_read_b128 v[148:151], v163 offset:1024
	ds_read_b128 v[164:167], v163 offset:2048
	ds_read_b128 v[168:171], v163 offset:3072
	v_add_u32_e32 v163, s36, v155
	ds_read_b128 v[180:183], v163
	ds_read_b128 v[184:187], v163 offset:1024
	ds_read_b128 v[188:191], v163 offset:2048
	ds_read_b128 v[192:195], v163 offset:3072
	s_add_u32 s12, s64, 0xb0000
	s_addc_u32 s13, s65, 0
	s_mov_b32 m0, s17
	ds_read_b128 v[196:199], v159 offset:32768
	ds_read_b128 v[200:203], v159 offset:33792
	ds_read_b128 v[204:207], v159 offset:34816
	ds_read_b128 v[208:211], v159 offset:35840
	ds_read_b128 v[212:215], v159 offset:36864
	ds_read_b128 v[216:219], v159 offset:37888
	ds_read_b128 v[220:223], v159 offset:38912
	ds_read_b128 v[224:227], v159 offset:39936
	global_load_lds_dwordx4 v128, s[12:13]
	s_mov_b32 m0, s18
	s_nop 0
	global_load_lds_dwordx4 v132, s[12:13]
	s_waitcnt vmcnt(8) lgkmcnt(0)

; #define PG8_MMA(ai, bj, At, Bt) do { __builtin_amdgcn_s_setprio(1); _Pragma("unroll") for (int m = 0; m < 4; ++m) _Pragma("unroll") for (int n = 0; n < 2; ++n) _Pragma("unroll") for (int k = 0; k < 2; ++k) \
;         acc[ai][bj][m][n] = __builtin_amdgcn_mfma_f32_16x16x32_bf16(Bt[n][k], At[m][k], acc[ai][bj][m][n], 0, 0, 0); __builtin_amdgcn_s_setprio(0); } while (0)
; #define PG8_WAIT_V(n) asm volatile("s_waitcnt vmcnt(" #n ")" ::: "memory")
; #define PG8_WAIT_L(n) asm volatile("s_waitcnt lgkmcnt(" #n ")" ::: "memory")
; #define PG8_BAR __builtin_amdgcn_s_barrier()
; #define PG8_SCHED __builtin_amdgcn_sched_barrier(0)
; template <class Epi>
; __device__ __forceinline__ void gemm_phase(LAS unsigned char* lds, const Gemm g, const StaticOrder& S, const Epi& E) {
;     ...
;             PG8_WAIT_V(8); PG8_WAIT_L(0); PG8_BAR; PG8_MMA(0, 0, At, B0); PG8_MMA(0, 1, At, B1); PG8_BAR; PG8_SCHED;
	s_setprio 1
	s_barrier

; #define PG8_MMA(ai, bj, At, Bt) do { __builtin_amdgcn_s_setprio(1); _Pragma("unroll") for (int m = 0; m < 4; ++m) _Pragma("unroll") for (int n = 0; n < 2; ++n) _Pragma("unroll") for (int k = 0; k < 2; ++k) \
;         acc[ai][bj][m][n] = __builtin_amdgcn_mfma_f32_16x16x32_bf16(Bt[n][k], At[m][k], acc[ai][bj][m][n], 0, 0, 0); __builtin_amdgcn_s_setprio(0); } while (0)
; #define PG8_WAIT_V(n) asm volatile("s_waitcnt vmcnt(" #n ")" ::: "memory")
; #define PG8_WAIT_L(n) asm volatile("s_waitcnt lgkmcnt(" #n ")" ::: "memory")
; #define PG8_BAR __builtin_amdgcn_s_barrier()
; #define PG8_SCHED __builtin_amdgcn_sched_barrier(0)
; template <class Epi>
; __device__ __forceinline__ void gemm_phase(LAS unsigned char* lds, const Gemm g, const StaticOrder& S, const Epi& E) {
;     ...
;             PG8_WAIT_V(8); PG8_WAIT_L(0); PG8_BAR; PG8_MMA(0, 0, At, B0); PG8_MMA(0, 1, At, B1); PG8_BAR; PG8_SCHED;
	v_mfma_f32_16x16x32_bf16 v[124:127], v[144:147], v[196:199], v[124:127]
	v_mfma_f32_16x16x32_bf16 v[120:123], v[164:167], v[196:199], v[120:123]
	v_mfma_f32_16x16x32_bf16 v[108:111], v[144:147], v[204:207], v[108:111]
	v_mfma_f32_16x16x32_bf16 v[104:107], v[164:167], v[204:207], v[104:107]
	v_mfma_f32_16x16x32_bf16 v[92:95], v[144:147], v[212:215], v[92:95]
	v_mfma_f32_16x16x32_bf16 v[88:91], v[164:167], v[212:215], v[88:91]
	v_mfma_f32_16x16x32_bf16 v[76:79], v[144:147], v[220:223], v[76:79]
	v_mfma_f32_16x16x32_bf16 v[72:75], v[164:167], v[220:223], v[72:75]
	v_mfma_f32_16x16x32_bf16 v[124:127], v[148:151], v[200:203], v[124:127]
	v_mfma_f32_16x16x32_bf16 v[120:123], v[168:171], v[200:203], v[120:123]
	v_mfma_f32_16x16x32_bf16 v[108:111], v[148:151], v[208:211], v[108:111]
	v_mfma_f32_16x16x32_bf16 v[104:107], v[168:171], v[208:211], v[104:107]
	v_mfma_f32_16x16x32_bf16 v[92:95], v[148:151], v[216:219], v[92:95]
	v_mfma_f32_16x16x32_bf16 v[88:91], v[168:171], v[216:219], v[88:91]
	v_mfma_f32_16x16x32_bf16 v[76:79], v[148:151], v[224:227], v[76:79]
	v_mfma_f32_16x16x32_bf16 v[72:75], v[168:171], v[224:227], v[72:75]


; #define PG8_STAGE(bufoff, gbase, voff) do { _Pragma("unroll") for (int _i = 0; _i < 2; ++_i) \
;         __builtin_amdgcn_global_load_lds((const unsigned*)((const char*)(gbase) + (voff)[_i]), (LAS unsigned*)(lds + (bufoff) + ldsw + _i * 8192), 16, 0, 0); } while (0)
; #define PG8_LDA(dst, b, h) do { _Pragma("unroll") for (int m = 0; m < 4; ++m) _Pragma("unroll") for (int k = 0; k < 2; ++k) dst[m][k] = *(const LAS bf16x8*)(lds + PG8_SA(b, h) + aoff + m * 2048 + k * 1024); } while (0)
; #define PG8_MMA(ai, bj, At, Bt) do { __builtin_amdgcn_s_setprio(1); _Pragma("unroll") for (int m = 0; m < 4; ++m) _Pragma("unroll") for (int n = 0; n < 2; ++n) _Pragma("unroll") for (int k = 0; k < 2; ++k) \
;         acc[ai][bj][m][n] = __builtin_amdgcn_mfma_f32_16x16x32_bf16(Bt[n][k], At[m][k], acc[ai][bj][m][n], 0, 0, 0); __builtin_amdgcn_s_setprio(0); } while (0)
; #define PG8_WAIT_V(n) asm volatile("s_waitcnt vmcnt(" #n ")" ::: "memory")
; #define PG8_WAIT_L(n) asm volatile("s_waitcnt lgkmcnt(" #n ")" ::: "memory")
; #define PG8_BAR __builtin_amdgcn_s_barrier()
; #define PG8_SCHED __builtin_amdgcn_sched_barrier(0)
; template <class Epi>
; __device__ __forceinline__ void gemm_phase(LAS unsigned char* lds, const Gemm g, const StaticOrder& S, const Epi& E) {
;     ...
;             PG8_WAIT_V(8); PG8_WAIT_L(0); PG8_BAR; PG8_MMA(0, 0, At, B0); PG8_MMA(0, 1, At, B1); PG8_BAR; PG8_SCHED;
;             PG8_LDA(At, 1, 1); PG8_STAGE(PG8_SB(1, 0), b3, voffB); PG8_STAGE(PG8_SB(1, 1), b3 + hsB, voffB); PG8_STAGE(PG8_SA(1, 0), a3, voffA);
;             PG8_WAIT_V(8); PG8_WAIT_L(0); PG8_BAR; PG8_MMA(1, 0, At, B0); PG8_MMA(1, 1, At, B1); PG8_BAR; PG8_SCHED;
	v_mfma_f32_16x16x32_bf16 v[116:119], v[180:183], v[196:199], v[116:119]
	v_mfma_f32_16x16x32_bf16 v[112:115], v[188:191], v[196:199], v[112:115]
	v_mfma_f32_16x16x32_bf16 v[100:103], v[180:183], v[204:207], v[100:103]
	v_mfma_f32_16x16x32_bf16 v[96:99], v[188:191], v[204:207], v[96:99]
	v_mfma_f32_16x16x32_bf16 v[84:87], v[180:183], v[212:215], v[84:87]
	v_mfma_f32_16x16x32_bf16 v[80:83], v[188:191], v[212:215], v[80:83]
	v_mfma_f32_16x16x32_bf16 v[68:71], v[180:183], v[220:223], v[68:71]
	v_mfma_f32_16x16x32_bf16 v[64:67], v[188:191], v[220:223], v[64:67]
	v_mfma_f32_16x16x32_bf16 v[116:119], v[184:187], v[200:203], v[116:119]
	v_mfma_f32_16x16x32_bf16 v[112:115], v[192:195], v[200:203], v[112:115]
	v_mfma_f32_16x16x32_bf16 v[100:103], v[184:187], v[208:211], v[100:103]
	v_mfma_f32_16x16x32_bf16 v[96:99], v[192:195], v[208:211], v[96:99]
	v_mfma_f32_16x16x32_bf16 v[84:87], v[184:187], v[216:219], v[84:87]
	v_mfma_f32_16x16x32_bf16 v[80:83], v[192:195], v[216:219], v[80:83]
	v_mfma_f32_16x16x32_bf16 v[68:71], v[184:187], v[224:227], v[68:71]
	v_mfma_f32_16x16x32_bf16 v[64:67], v[192:195], v[224:227], v[64:67]
	s_barrier
	s_setprio 0
	s_add_u32 s98, s62, 0x80
	s_addc_u32 s99, s63, 0
	s_add_u32 s100, s64, 0x80
	s_addc_u32 s101, s65, 0
	s_add_i32 s12, s35, s4
	s_mov_b32 m0, s12
	ds_read_b128 v[196:199], v159 offset:49152
	ds_read_b128 v[200:203], v159 offset:50176
	ds_read_b128 v[204:207], v159 offset:51200
	ds_read_b128 v[208:211], v159 offset:52224
	ds_read_b128 v[212:215], v159 offset:53248
	ds_read_b128 v[216:219], v159 offset:54272
	ds_read_b128 v[220:223], v159 offset:55296
	ds_read_b128 v[224:227], v159 offset:56320
	global_load_lds_dwordx4 v130, s[98:99]
	s_add_i32 m0, s12, 0x2000
	s_add_u32 s12, s62, 0xb0080
	s_addc_u32 s13, s63, 0
	s_add_i32 s35, s36, s4
	global_load_lds_dwordx4 v134, s[98:99]
	s_mov_b32 m0, s35
	s_nop 0
	global_load_lds_dwordx4 v130, s[12:13]
	s_add_i32 m0, s35, 0x2000
	s_nop 0
	global_load_lds_dwordx4 v134, s[12:13]
	s_mov_b32 m0, s22
	s_nop 0
	global_load_lds_dwordx4 v128, s[100:101]
	s_mov_b32 m0, s23
	s_nop 0
	global_load_lds_dwordx4 v132, s[100:101]
	s_waitcnt vmcnt(8) lgkmcnt(0)

; #define PG8_MMA(ai, bj, At, Bt) do { __builtin_amdgcn_s_setprio(1); _Pragma("unroll") for (int m = 0; m < 4; ++m) _Pragma("unroll") for (int n = 0; n < 2; ++n) _Pragma("unroll") for (int k = 0; k < 2; ++k) \
;         acc[ai][bj][m][n] = __builtin_amdgcn_mfma_f32_16x16x32_bf16(Bt[n][k], At[m][k], acc[ai][bj][m][n], 0, 0, 0); __builtin_amdgcn_s_setprio(0); } while (0)
; #define PG8_WAIT_V(n) asm volatile("s_waitcnt vmcnt(" #n ")" ::: "memory")
; #define PG8_WAIT_L(n) asm volatile("s_waitcnt lgkmcnt(" #n ")" ::: "memory")
; #define PG8_BAR __builtin_amdgcn_s_barrier()
; #define PG8_SCHED __builtin_amdgcn_sched_barrier(0)
; template <class Epi>
; __device__ __forceinline__ void gemm_phase(LAS unsigned char* lds, const Gemm g, const StaticOrder& S, const Epi& E) {
;     ...
;             PG8_WAIT_V(8); PG8_WAIT_L(0); PG8_BAR; PG8_MMA(1, 0, At, B0); PG8_MMA(1, 1, At, B1); PG8_BAR; PG8_SCHED;
	s_setprio 1
	s_barrier

; #define PG8_MMA(ai, bj, At, Bt) do { __builtin_amdgcn_s_setprio(1); _Pragma("unroll") for (int m = 0; m < 4; ++m) _Pragma("unroll") for (int n = 0; n < 2; ++n) _Pragma("unroll") for (int k = 0; k < 2; ++k) \
;         acc[ai][bj][m][n] = __builtin_amdgcn_mfma_f32_16x16x32_bf16(Bt[n][k], At[m][k], acc[ai][bj][m][n], 0, 0, 0); __builtin_amdgcn_s_setprio(0); } while (0)
; #define PG8_WAIT_V(n) asm volatile("s_waitcnt vmcnt(" #n ")" ::: "memory")
; #define PG8_WAIT_L(n) asm volatile("s_waitcnt lgkmcnt(" #n ")" ::: "memory")
; #define PG8_BAR __builtin_amdgcn_s_barrier()
; #define PG8_SCHED __builtin_amdgcn_sched_barrier(0)
; template <class Epi>
; __device__ __forceinline__ void gemm_phase(LAS unsigned char* lds, const Gemm g, const StaticOrder& S, const Epi& E) {
;     ...
;             PG8_WAIT_V(8); PG8_WAIT_L(0); PG8_BAR; PG8_MMA(1, 0, At, B0); PG8_MMA(1, 1, At, B1); PG8_BAR; PG8_SCHED;
	v_mfma_f32_16x16x32_bf16 v[60:63], v[144:147], v[196:199], v[60:63]
	v_mfma_f32_16x16x32_bf16 v[56:59], v[164:167], v[196:199], v[56:59]
	v_mfma_f32_16x16x32_bf16 v[44:47], v[144:147], v[204:207], v[44:47]
	v_mfma_f32_16x16x32_bf16 v[40:43], v[164:167], v[204:207], v[40:43]
	v_mfma_f32_16x16x32_bf16 v[28:31], v[144:147], v[212:215], v[28:31]
	v_mfma_f32_16x16x32_bf16 v[24:27], v[164:167], v[212:215], v[24:27]
	v_mfma_f32_16x16x32_bf16 v[12:15], v[144:147], v[220:223], v[12:15]
	v_mfma_f32_16x16x32_bf16 v[8:11], v[164:167], v[220:223], v[8:11]
	v_mfma_f32_16x16x32_bf16 v[60:63], v[148:151], v[200:203], v[60:63]
	v_mfma_f32_16x16x32_bf16 v[56:59], v[168:171], v[200:203], v[56:59]
	v_mfma_f32_16x16x32_bf16 v[44:47], v[148:151], v[208:211], v[44:47]
	v_mfma_f32_16x16x32_bf16 v[40:43], v[168:171], v[208:211], v[40:43]
	v_mfma_f32_16x16x32_bf16 v[28:31], v[148:151], v[216:219], v[28:31]
	v_mfma_f32_16x16x32_bf16 v[24:27], v[168:171], v[216:219], v[24:27]
	v_mfma_f32_16x16x32_bf16 v[12:15], v[148:151], v[224:227], v[12:15]
	v_mfma_f32_16x16x32_bf16 v[8:11], v[168:171], v[224:227], v[8:11]


; #define PG8_MMA(ai, bj, At, Bt) do { __builtin_amdgcn_s_setprio(1); _Pragma("unroll") for (int m = 0; m < 4; ++m) _Pragma("unroll") for (int n = 0; n < 2; ++n) _Pragma("unroll") for (int k = 0; k < 2; ++k) \
;         acc[ai][bj][m][n] = __builtin_amdgcn_mfma_f32_16x16x32_bf16(Bt[n][k], At[m][k], acc[ai][bj][m][n], 0, 0, 0); __builtin_amdgcn_s_setprio(0); } while (0)
; #define PG8_WAIT_V(n) asm volatile("s_waitcnt vmcnt(" #n ")" ::: "memory")
; #define PG8_WAIT_L(n) asm volatile("s_waitcnt lgkmcnt(" #n ")" ::: "memory")
; #define PG8_BAR __builtin_amdgcn_s_barrier()
; #define PG8_SCHED __builtin_amdgcn_sched_barrier(0)
; template <class Epi>
; __device__ __forceinline__ void gemm_phase(LAS unsigned char* lds, const Gemm g, const StaticOrder& S, const Epi& E) {
;     ...
;             PG8_WAIT_V(8); PG8_WAIT_L(0); PG8_BAR; PG8_MMA(1, 0, At, B0); PG8_MMA(1, 1, At, B1); PG8_BAR; PG8_SCHED;
;         }
;         if (wr == 0) PG8_BAR;
	v_mfma_f32_16x16x32_bf16 v[52:55], v[180:183], v[196:199], v[52:55]
	v_mfma_f32_16x16x32_bf16 v[48:51], v[188:191], v[196:199], v[48:51]
	v_mfma_f32_16x16x32_bf16 v[36:39], v[180:183], v[204:207], v[36:39]
	v_mfma_f32_16x16x32_bf16 v[32:35], v[188:191], v[204:207], v[32:35]
	v_mfma_f32_16x16x32_bf16 v[20:23], v[180:183], v[212:215], v[20:23]
	v_mfma_f32_16x16x32_bf16 v[16:19], v[188:191], v[212:215], v[16:19]
	v_mfma_f32_16x16x32_bf16 v[4:7], v[180:183], v[220:223], v[4:7]
	v_mfma_f32_16x16x32_bf16 v[0:3], v[188:191], v[220:223], v[0:3]
	v_mfma_f32_16x16x32_bf16 v[52:55], v[184:187], v[200:203], v[52:55]
	v_mfma_f32_16x16x32_bf16 v[48:51], v[192:195], v[200:203], v[48:51]
	v_mfma_f32_16x16x32_bf16 v[36:39], v[184:187], v[208:211], v[36:39]
	v_mfma_f32_16x16x32_bf16 v[32:35], v[192:195], v[208:211], v[32:35]
	v_mfma_f32_16x16x32_bf16 v[20:23], v[184:187], v[216:219], v[20:23]
	v_mfma_f32_16x16x32_bf16 v[16:19], v[192:195], v[216:219], v[16:19]
	v_mfma_f32_16x16x32_bf16 v[4:7], v[184:187], v[224:227], v[4:7]
	v_mfma_f32_16x16x32_bf16 v[0:3], v[192:195], v[224:227], v[0:3]
	s_barrier
	s_setprio 0
	s_add_i32 s34, s34, 2
	s_add_u32 s6, s6, 0x100
	s_addc_u32 s7, s7, 0
	s_cmp_gt_u32 s34, 41
	s_mov_b64 s[12:13], s[60:61]
	s_cbranch_scc0 .LBB0_296
	s_and_b64 vcc, exec, s[42:43]
	s_cbranch_vccz .LBB0_299
	s_barrier

; #define PG8_STAGE(bufoff, gbase, voff) do { _Pragma("unroll") for (int _i = 0; _i < 2; ++_i) \
;         __builtin_amdgcn_global_load_lds((const unsigned*)((const char*)(gbase) + (voff)[_i]), (LAS unsigned*)(lds + (bufoff) + ldsw + _i * 8192), 16, 0, 0); } while (0)
; #define PG8_LDA(dst, b, h) do { _Pragma("unroll") for (int m = 0; m < 4; ++m) _Pragma("unroll") for (int k = 0; k < 2; ++k) dst[m][k] = *(const LAS bf16x8*)(lds + PG8_SA(b, h) + aoff + m * 2048 + k * 1024); } while (0)
; #define PG8_LDB(dst, b, h) do { _Pragma("unroll") for (int n = 0; n < 2; ++n) _Pragma("unroll") for (int k = 0; k < 2; ++k) dst[n][k] = *(const LAS bf16x8*)(lds + PG8_SB(b, h) + boff + n * 2048 + k * 1024); } while (0)
; #define PG8_MMA(ai, bj, At, Bt) do { __builtin_amdgcn_s_setprio(1); _Pragma("unroll") for (int m = 0; m < 4; ++m) _Pragma("unroll") for (int n = 0; n < 2; ++n) _Pragma("unroll") for (int k = 0; k < 2; ++k) \
;         acc[ai][bj][m][n] = __builtin_amdgcn_mfma_f32_16x16x32_bf16(Bt[n][k], At[m][k], acc[ai][bj][m][n], 0, 0, 0); __builtin_amdgcn_s_setprio(0); } while (0)
; #define PG8_WAIT_V(n) asm volatile("s_waitcnt vmcnt(" #n ")" ::: "memory")
; #define PG8_WAIT_L(n) asm volatile("s_waitcnt lgkmcnt(" #n ")" ::: "memory")
; #define PG8_BAR __builtin_amdgcn_s_barrier()
; #define PG8_SCHED __builtin_amdgcn_sched_barrier(0)
; template <class Epi>
; __device__ __forceinline__ void gemm_phase(LAS unsigned char* lds, const Gemm g, const StaticOrder& S, const Epi& E) {
;     ...
;         for (int t = 0; t < nt; t += 2) {
;             const bool last = (t == nt - 2);
;             if constexpr (Epi::HAS_MID) { if (t == nt1) E.mid(acc, cur, wr, wc, fr, fq); }
;             const char* a1 = cA + ((Epi::HAS_MID && t >= nt1) ? dA2 : 0) + (size_t)(t + 1) * kstep;
;             const char* a2 = last ? nA : cA + ((Epi::HAS_MID && t + 2 >= nt1) ? dA2 : 0) + (size_t)(t + 2) * kstep; const char* b2 = last ? nB : cB + ((Epi::HAS_MID && t + 2 >= nt1) ? dB2 : 0) + (size_t)(t + 2) * kstep;
;             const char* a3 = a2 + kstep; const char* b3 = b2 + kstep;
;             PG8_LDB(B0, 0, 0); PG8_LDB(B1, 0, 1); PG8_SCHED; PG8_LDA(At, 0, 0); PG8_STAGE(PG8_SA(1, 1), a1 + hsA, voffA);
;             PG8_WAIT_V(8); PG8_WAIT_L(0); PG8_BAR; PG8_MMA(0, 0, At, B0); PG8_MMA(0, 1, At, B1); PG8_BAR; PG8_SCHED;
.LBB0_414:
	ds_read_b128 v[152:155], v167
	ds_read_b128 v[156:159], v167 offset:1024
	ds_read_b128 v[162:165], v167 offset:2048
	ds_read_b128 v[180:183], v167 offset:3072
	ds_read_b128 v[184:187], v168
	ds_read_b128 v[188:191], v168 offset:1024
	ds_read_b128 v[192:195], v168 offset:2048
	ds_read_b128 v[196:199], v168 offset:3072
	s_add_u32 s12, s10, 0xfffc0080
	s_addc_u32 s13, s11, -1
	s_cmp_eq_u32 s17, 12
	s_cselect_b32 s87, s0, s13
	s_cselect_b32 s86, s2, s12
	s_cselect_b32 s13, s3, s15
	s_cselect_b32 s12, s6, s7
	s_add_i32 m0, s5, 0xc000
	ds_read_b128 v[200:203], v169
	ds_read_b128 v[204:207], v169 offset:1024
	ds_read_b128 v[208:211], v169 offset:2048
	ds_read_b128 v[212:215], v169 offset:3072
	ds_read_b128 v[216:219], v169 offset:4096
	ds_read_b128 v[220:223], v169 offset:5120
	ds_read_b128 v[224:227], v169 offset:6144
	ds_read_b128 v[228:231], v169 offset:7168
	global_load_lds_dwordx4 v144, s[10:11]
	s_add_i32 m0, s5, 0xe000
	s_nop 0
	global_load_lds_dwordx4 v146, s[10:11]
	s_waitcnt vmcnt(8) lgkmcnt(0)

; #define PG8_MMA(ai, bj, At, Bt) do { __builtin_amdgcn_s_setprio(1); _Pragma("unroll") for (int m = 0; m < 4; ++m) _Pragma("unroll") for (int n = 0; n < 2; ++n) _Pragma("unroll") for (int k = 0; k < 2; ++k) \
;         acc[ai][bj][m][n] = __builtin_amdgcn_mfma_f32_16x16x32_bf16(Bt[n][k], At[m][k], acc[ai][bj][m][n], 0, 0, 0); __builtin_amdgcn_s_setprio(0); } while (0)
; #define PG8_WAIT_V(n) asm volatile("s_waitcnt vmcnt(" #n ")" ::: "memory")
; #define PG8_WAIT_L(n) asm volatile("s_waitcnt lgkmcnt(" #n ")" ::: "memory")
; #define PG8_BAR __builtin_amdgcn_s_barrier()
; #define PG8_SCHED __builtin_amdgcn_sched_barrier(0)
; template <class Epi>
; __device__ __forceinline__ void gemm_phase(LAS unsigned char* lds, const Gemm g, const StaticOrder& S, const Epi& E) {
;     ...
;             PG8_WAIT_V(8); PG8_WAIT_L(0); PG8_BAR; PG8_MMA(0, 0, At, B0); PG8_MMA(0, 1, At, B1); PG8_BAR; PG8_SCHED;
	s_setprio 1
	s_barrier

; #define PG8_MMA(ai, bj, At, Bt) do { __builtin_amdgcn_s_setprio(1); _Pragma("unroll") for (int m = 0; m < 4; ++m) _Pragma("unroll") for (int n = 0; n < 2; ++n) _Pragma("unroll") for (int k = 0; k < 2; ++k) \
;         acc[ai][bj][m][n] = __builtin_amdgcn_mfma_f32_16x16x32_bf16(Bt[n][k], At[m][k], acc[ai][bj][m][n], 0, 0, 0); __builtin_amdgcn_s_setprio(0); } while (0)
; #define PG8_WAIT_V(n) asm volatile("s_waitcnt vmcnt(" #n ")" ::: "memory")
; #define PG8_WAIT_L(n) asm volatile("s_waitcnt lgkmcnt(" #n ")" ::: "memory")
; #define PG8_BAR __builtin_amdgcn_s_barrier()
; #define PG8_SCHED __builtin_amdgcn_sched_barrier(0)
; template <class Epi>
; __device__ __forceinline__ void gemm_phase(LAS unsigned char* lds, const Gemm g, const StaticOrder& S, const Epi& E) {
;     ...
;             PG8_WAIT_V(8); PG8_WAIT_L(0); PG8_BAR; PG8_MMA(0, 0, At, B0); PG8_MMA(0, 1, At, B1); PG8_BAR; PG8_SCHED;
	v_mfma_f32_16x16x32_bf16 v[124:127], v[152:155], v[200:203], v[124:127]
	v_mfma_f32_16x16x32_bf16 v[120:123], v[162:165], v[200:203], v[120:123]
	v_mfma_f32_16x16x32_bf16 v[108:111], v[152:155], v[208:211], v[108:111]
	v_mfma_f32_16x16x32_bf16 v[104:107], v[162:165], v[208:211], v[104:107]
	v_mfma_f32_16x16x32_bf16 v[92:95], v[152:155], v[216:219], v[92:95]
	v_mfma_f32_16x16x32_bf16 v[88:91], v[162:165], v[216:219], v[88:91]
	v_mfma_f32_16x16x32_bf16 v[76:79], v[152:155], v[224:227], v[76:79]
	v_mfma_f32_16x16x32_bf16 v[72:75], v[162:165], v[224:227], v[72:75]
	v_mfma_f32_16x16x32_bf16 v[124:127], v[156:159], v[204:207], v[124:127]
	v_mfma_f32_16x16x32_bf16 v[120:123], v[180:183], v[204:207], v[120:123]
	v_mfma_f32_16x16x32_bf16 v[108:111], v[156:159], v[212:215], v[108:111]
	v_mfma_f32_16x16x32_bf16 v[104:107], v[180:183], v[212:215], v[104:107]
	v_mfma_f32_16x16x32_bf16 v[92:95], v[156:159], v[220:223], v[92:95]
	v_mfma_f32_16x16x32_bf16 v[88:91], v[180:183], v[220:223], v[88:91]
	v_mfma_f32_16x16x32_bf16 v[76:79], v[156:159], v[228:231], v[76:79]
	v_mfma_f32_16x16x32_bf16 v[72:75], v[180:183], v[228:231], v[72:75]


; #define PG8_STAGE(bufoff, gbase, voff) do { _Pragma("unroll") for (int _i = 0; _i < 2; ++_i) \
;         __builtin_amdgcn_global_load_lds((const unsigned*)((const char*)(gbase) + (voff)[_i]), (LAS unsigned*)(lds + (bufoff) + ldsw + _i * 8192), 16, 0, 0); } while (0)
; #define PG8_LDA(dst, b, h) do { _Pragma("unroll") for (int m = 0; m < 4; ++m) _Pragma("unroll") for (int k = 0; k < 2; ++k) dst[m][k] = *(const LAS bf16x8*)(lds + PG8_SA(b, h) + aoff + m * 2048 + k * 1024); } while (0)
; #define PG8_MMA(ai, bj, At, Bt) do { __builtin_amdgcn_s_setprio(1); _Pragma("unroll") for (int m = 0; m < 4; ++m) _Pragma("unroll") for (int n = 0; n < 2; ++n) _Pragma("unroll") for (int k = 0; k < 2; ++k) \
;         acc[ai][bj][m][n] = __builtin_amdgcn_mfma_f32_16x16x32_bf16(Bt[n][k], At[m][k], acc[ai][bj][m][n], 0, 0, 0); __builtin_amdgcn_s_setprio(0); } while (0)
; #define PG8_WAIT_V(n) asm volatile("s_waitcnt vmcnt(" #n ")" ::: "memory")
; #define PG8_WAIT_L(n) asm volatile("s_waitcnt lgkmcnt(" #n ")" ::: "memory")
; #define PG8_BAR __builtin_amdgcn_s_barrier()
; #define PG8_SCHED __builtin_amdgcn_sched_barrier(0)
; template <class Epi>
; __device__ __forceinline__ void gemm_phase(LAS unsigned char* lds, const Gemm g, const StaticOrder& S, const Epi& E) {
;     ...
;             PG8_WAIT_V(8); PG8_WAIT_L(0); PG8_BAR; PG8_MMA(0, 0, At, B0); PG8_MMA(0, 1, At, B1); PG8_BAR; PG8_SCHED;
;             PG8_LDA(At, 0, 1); PG8_STAGE(PG8_SB(0, 0), b2, voffB); PG8_STAGE(PG8_SB(0, 1), b2 + hsB, voffB); PG8_STAGE(PG8_SA(0, 0), a2, voffA);
;             PG8_WAIT_V(8); PG8_WAIT_L(0); PG8_BAR; PG8_MMA(1, 0, At, B0); PG8_MMA(1, 1, At, B1); PG8_BAR; PG8_SCHED;
	v_mfma_f32_16x16x32_bf16 v[116:119], v[184:187], v[200:203], v[116:119]
	v_mfma_f32_16x16x32_bf16 v[112:115], v[192:195], v[200:203], v[112:115]
	v_mfma_f32_16x16x32_bf16 v[100:103], v[184:187], v[208:211], v[100:103]
	v_mfma_f32_16x16x32_bf16 v[96:99], v[192:195], v[208:211], v[96:99]
	v_mfma_f32_16x16x32_bf16 v[84:87], v[184:187], v[216:219], v[84:87]
	v_mfma_f32_16x16x32_bf16 v[80:83], v[192:195], v[216:219], v[80:83]
	v_mfma_f32_16x16x32_bf16 v[68:71], v[184:187], v[224:227], v[68:71]
	v_mfma_f32_16x16x32_bf16 v[64:67], v[192:195], v[224:227], v[64:67]
	v_mfma_f32_16x16x32_bf16 v[116:119], v[188:191], v[204:207], v[116:119]
	v_mfma_f32_16x16x32_bf16 v[112:115], v[196:199], v[204:207], v[112:115]
	v_mfma_f32_16x16x32_bf16 v[100:103], v[188:191], v[212:215], v[100:103]
	v_mfma_f32_16x16x32_bf16 v[96:99], v[196:199], v[212:215], v[96:99]
	v_mfma_f32_16x16x32_bf16 v[84:87], v[188:191], v[220:223], v[84:87]
	v_mfma_f32_16x16x32_bf16 v[80:83], v[196:199], v[220:223], v[80:83]
	v_mfma_f32_16x16x32_bf16 v[68:71], v[188:191], v[228:231], v[68:71]
	v_mfma_f32_16x16x32_bf16 v[64:67], v[196:199], v[228:231], v[64:67]
	s_barrier
	s_setprio 0
	s_add_i32 s19, s65, s4
	s_mov_b32 m0, s19
	ds_read_b128 v[200:203], v169 offset:16384
	ds_read_b128 v[204:207], v169 offset:17408
	ds_read_b128 v[208:211], v169 offset:18432
	ds_read_b128 v[212:215], v169 offset:19456
	ds_read_b128 v[216:219], v169 offset:20480
	ds_read_b128 v[220:223], v169 offset:21504
	ds_read_b128 v[224:227], v169 offset:22528
	ds_read_b128 v[228:231], v169 offset:23552
	global_load_lds_dwordx4 v130, s[12:13]
	s_add_i32 m0, s19, 0x2000
	s_add_u32 s24, s12, 0x40000
	s_addc_u32 s25, s13, 0
	s_add_i32 s19, s76, s4
	global_load_lds_dwordx4 v134, s[12:13]
	s_mov_b32 m0, s19
	s_nop 0
	global_load_lds_dwordx4 v130, s[24:25]
	s_add_i32 m0, s19, 0x2000
	s_nop 0
	global_load_lds_dwordx4 v134, s[24:25]
	s_mov_b32 m0, s5
	s_nop 0
	global_load_lds_dwordx4 v128, s[86:87]
	s_mov_b32 m0, s62
	s_nop 0
	global_load_lds_dwordx4 v132, s[86:87]
	s_waitcnt vmcnt(8) lgkmcnt(0)

; #define PG8_MMA(ai, bj, At, Bt) do { __builtin_amdgcn_s_setprio(1); _Pragma("unroll") for (int m = 0; m < 4; ++m) _Pragma("unroll") for (int n = 0; n < 2; ++n) _Pragma("unroll") for (int k = 0; k < 2; ++k) \
;         acc[ai][bj][m][n] = __builtin_amdgcn_mfma_f32_16x16x32_bf16(Bt[n][k], At[m][k], acc[ai][bj][m][n], 0, 0, 0); __builtin_amdgcn_s_setprio(0); } while (0)
; #define PG8_WAIT_V(n) asm volatile("s_waitcnt vmcnt(" #n ")" ::: "memory")
; #define PG8_WAIT_L(n) asm volatile("s_waitcnt lgkmcnt(" #n ")" ::: "memory")
; #define PG8_BAR __builtin_amdgcn_s_barrier()
; #define PG8_SCHED __builtin_amdgcn_sched_barrier(0)
; template <class Epi>
; __device__ __forceinline__ void gemm_phase(LAS unsigned char* lds, const Gemm g, const StaticOrder& S, const Epi& E) {
;     ...
;             PG8_WAIT_V(8); PG8_WAIT_L(0); PG8_BAR; PG8_MMA(1, 0, At, B0); PG8_MMA(1, 1, At, B1); PG8_BAR; PG8_SCHED;
	s_setprio 1
	s_barrier

; #define PG8_MMA(ai, bj, At, Bt) do { __builtin_amdgcn_s_setprio(1); _Pragma("unroll") for (int m = 0; m < 4; ++m) _Pragma("unroll") for (int n = 0; n < 2; ++n) _Pragma("unroll") for (int k = 0; k < 2; ++k) \
;         acc[ai][bj][m][n] = __builtin_amdgcn_mfma_f32_16x16x32_bf16(Bt[n][k], At[m][k], acc[ai][bj][m][n], 0, 0, 0); __builtin_amdgcn_s_setprio(0); } while (0)
; #define PG8_WAIT_V(n) asm volatile("s_waitcnt vmcnt(" #n ")" ::: "memory")
; #define PG8_WAIT_L(n) asm volatile("s_waitcnt lgkmcnt(" #n ")" ::: "memory")
; #define PG8_BAR __builtin_amdgcn_s_barrier()
; #define PG8_SCHED __builtin_amdgcn_sched_barrier(0)
; template <class Epi>
; __device__ __forceinline__ void gemm_phase(LAS unsigned char* lds, const Gemm g, const StaticOrder& S, const Epi& E) {
;     ...
;             PG8_WAIT_V(8); PG8_WAIT_L(0); PG8_BAR; PG8_MMA(1, 0, At, B0); PG8_MMA(1, 1, At, B1); PG8_BAR; PG8_SCHED;
	v_mfma_f32_16x16x32_bf16 v[60:63], v[152:155], v[200:203], v[60:63]
	v_mfma_f32_16x16x32_bf16 v[56:59], v[162:165], v[200:203], v[56:59]
	v_mfma_f32_16x16x32_bf16 v[44:47], v[152:155], v[208:211], v[44:47]
	v_mfma_f32_16x16x32_bf16 v[40:43], v[162:165], v[208:211], v[40:43]
	v_mfma_f32_16x16x32_bf16 v[28:31], v[152:155], v[216:219], v[28:31]
	v_mfma_f32_16x16x32_bf16 v[24:27], v[162:165], v[216:219], v[24:27]
	v_mfma_f32_16x16x32_bf16 v[12:15], v[152:155], v[224:227], v[12:15]
	v_mfma_f32_16x16x32_bf16 v[8:11], v[162:165], v[224:227], v[8:11]
	v_mfma_f32_16x16x32_bf16 v[60:63], v[156:159], v[204:207], v[60:63]
	v_mfma_f32_16x16x32_bf16 v[56:59], v[180:183], v[204:207], v[56:59]
	v_mfma_f32_16x16x32_bf16 v[44:47], v[156:159], v[212:215], v[44:47]
	v_mfma_f32_16x16x32_bf16 v[40:43], v[180:183], v[212:215], v[40:43]
	v_mfma_f32_16x16x32_bf16 v[28:31], v[156:159], v[220:223], v[28:31]
	v_mfma_f32_16x16x32_bf16 v[24:27], v[180:183], v[220:223], v[24:27]
	v_mfma_f32_16x16x32_bf16 v[12:15], v[156:159], v[228:231], v[12:15]
	v_mfma_f32_16x16x32_bf16 v[8:11], v[180:183], v[228:231], v[8:11]


; #define PG8_STAGE(bufoff, gbase, voff) do { _Pragma("unroll") for (int _i = 0; _i < 2; ++_i) \
;         __builtin_amdgcn_global_load_lds((const unsigned*)((const char*)(gbase) + (voff)[_i]), (LAS unsigned*)(lds + (bufoff) + ldsw + _i * 8192), 16, 0, 0); } while (0)
; #define PG8_LDA(dst, b, h) do { _Pragma("unroll") for (int m = 0; m < 4; ++m) _Pragma("unroll") for (int k = 0; k < 2; ++k) dst[m][k] = *(const LAS bf16x8*)(lds + PG8_SA(b, h) + aoff + m * 2048 + k * 1024); } while (0)
; #define PG8_LDB(dst, b, h) do { _Pragma("unroll") for (int n = 0; n < 2; ++n) _Pragma("unroll") for (int k = 0; k < 2; ++k) dst[n][k] = *(const LAS bf16x8*)(lds + PG8_SB(b, h) + boff + n * 2048 + k * 1024); } while (0)
; #define PG8_MMA(ai, bj, At, Bt) do { __builtin_amdgcn_s_setprio(1); _Pragma("unroll") for (int m = 0; m < 4; ++m) _Pragma("unroll") for (int n = 0; n < 2; ++n) _Pragma("unroll") for (int k = 0; k < 2; ++k) \
;         acc[ai][bj][m][n] = __builtin_amdgcn_mfma_f32_16x16x32_bf16(Bt[n][k], At[m][k], acc[ai][bj][m][n], 0, 0, 0); __builtin_amdgcn_s_setprio(0); } while (0)
; #define PG8_WAIT_V(n) asm volatile("s_waitcnt vmcnt(" #n ")" ::: "memory")
; #define PG8_WAIT_L(n) asm volatile("s_waitcnt lgkmcnt(" #n ")" ::: "memory")
; #define PG8_BAR __builtin_amdgcn_s_barrier()
; #define PG8_SCHED __builtin_amdgcn_sched_barrier(0)
; template <class Epi>
; __device__ __forceinline__ void gemm_phase(LAS unsigned char* lds, const Gemm g, const StaticOrder& S, const Epi& E) {
;     ...
;             PG8_WAIT_V(8); PG8_WAIT_L(0); PG8_BAR; PG8_MMA(1, 0, At, B0); PG8_MMA(1, 1, At, B1); PG8_BAR; PG8_SCHED;
;             PG8_LDB(B0, 1, 0); PG8_LDB(B1, 1, 1); PG8_SCHED; PG8_LDA(At, 1, 0); PG8_STAGE(PG8_SA(0, 1), a2 + hsA, voffA);
;             PG8_WAIT_V(8); PG8_WAIT_L(0); PG8_BAR; PG8_MMA(0, 0, At, B0); PG8_MMA(0, 1, At, B1); PG8_BAR; PG8_SCHED;
	v_mfma_f32_16x16x32_bf16 v[52:55], v[184:187], v[200:203], v[52:55]
	v_mfma_f32_16x16x32_bf16 v[48:51], v[192:195], v[200:203], v[48:51]
	v_mfma_f32_16x16x32_bf16 v[36:39], v[184:187], v[208:211], v[36:39]
	v_mfma_f32_16x16x32_bf16 v[32:35], v[192:195], v[208:211], v[32:35]
	v_mfma_f32_16x16x32_bf16 v[20:23], v[184:187], v[216:219], v[20:23]
	v_mfma_f32_16x16x32_bf16 v[16:19], v[192:195], v[216:219], v[16:19]
	v_mfma_f32_16x16x32_bf16 v[4:7], v[184:187], v[224:227], v[4:7]
	v_mfma_f32_16x16x32_bf16 v[0:3], v[192:195], v[224:227], v[0:3]
	v_mfma_f32_16x16x32_bf16 v[52:55], v[188:191], v[204:207], v[52:55]
	v_mfma_f32_16x16x32_bf16 v[48:51], v[196:199], v[204:207], v[48:51]
	v_mfma_f32_16x16x32_bf16 v[36:39], v[188:191], v[212:215], v[36:39]
	v_mfma_f32_16x16x32_bf16 v[32:35], v[196:199], v[212:215], v[32:35]
	v_mfma_f32_16x16x32_bf16 v[20:23], v[188:191], v[220:223], v[20:23]
	v_mfma_f32_16x16x32_bf16 v[16:19], v[196:199], v[220:223], v[16:19]
	v_mfma_f32_16x16x32_bf16 v[4:7], v[188:191], v[228:231], v[4:7]
	v_mfma_f32_16x16x32_bf16 v[0:3], v[196:199], v[228:231], v[0:3]
	s_barrier
	s_setprio 0
	s_add_i32 s19, 0, 0x18000
	v_add_u32_e32 v136, s19, v166
	s_add_i32 s22, 0, 0x1c000
	ds_read_b128 v[152:155], v136
	ds_read_b128 v[156:159], v136 offset:1024
	ds_read_b128 v[162:165], v136 offset:2048
	ds_read_b128 v[180:183], v136 offset:3072
	v_add_u32_e32 v136, s22, v166
	ds_read_b128 v[184:187], v136
	ds_read_b128 v[188:191], v136 offset:1024
	ds_read_b128 v[192:195], v136 offset:2048
	ds_read_b128 v[196:199], v136 offset:3072
	s_add_u32 s24, s86, 0x40000
	s_addc_u32 s25, s87, 0
	s_mov_b32 m0, s63
	ds_read_b128 v[200:203], v169 offset:32768
	ds_read_b128 v[204:207], v169 offset:33792
	ds_read_b128 v[208:211], v169 offset:34816
	ds_read_b128 v[212:215], v169 offset:35840
	ds_read_b128 v[216:219], v169 offset:36864
	ds_read_b128 v[220:223], v169 offset:37888
	ds_read_b128 v[224:227], v169 offset:38912
	ds_read_b128 v[228:231], v169 offset:39936
	global_load_lds_dwordx4 v128, s[24:25]
	s_mov_b32 m0, s74
	s_nop 0
	global_load_lds_dwordx4 v132, s[24:25]
	s_waitcnt vmcnt(8) lgkmcnt(0)

; #define PG8_MMA(ai, bj, At, Bt) do { __builtin_amdgcn_s_setprio(1); _Pragma("unroll") for (int m = 0; m < 4; ++m) _Pragma("unroll") for (int n = 0; n < 2; ++n) _Pragma("unroll") for (int k = 0; k < 2; ++k) \
;         acc[ai][bj][m][n] = __builtin_amdgcn_mfma_f32_16x16x32_bf16(Bt[n][k], At[m][k], acc[ai][bj][m][n], 0, 0, 0); __builtin_amdgcn_s_setprio(0); } while (0)
; #define PG8_WAIT_V(n) asm volatile("s_waitcnt vmcnt(" #n ")" ::: "memory")
; #define PG8_WAIT_L(n) asm volatile("s_waitcnt lgkmcnt(" #n ")" ::: "memory")
; #define PG8_BAR __builtin_amdgcn_s_barrier()
; #define PG8_SCHED __builtin_amdgcn_sched_barrier(0)
; template <class Epi>
; __device__ __forceinline__ void gemm_phase(LAS unsigned char* lds, const Gemm g, const StaticOrder& S, const Epi& E) {
;     ...
;             PG8_WAIT_V(8); PG8_WAIT_L(0); PG8_BAR; PG8_MMA(0, 0, At, B0); PG8_MMA(0, 1, At, B1); PG8_BAR; PG8_SCHED;
	s_setprio 1
	s_barrier

; #define PG8_MMA(ai, bj, At, Bt) do { __builtin_amdgcn_s_setprio(1); _Pragma("unroll") for (int m = 0; m < 4; ++m) _Pragma("unroll") for (int n = 0; n < 2; ++n) _Pragma("unroll") for (int k = 0; k < 2; ++k) \
;         acc[ai][bj][m][n] = __builtin_amdgcn_mfma_f32_16x16x32_bf16(Bt[n][k], At[m][k], acc[ai][bj][m][n], 0, 0, 0); __builtin_amdgcn_s_setprio(0); } while (0)
; #define PG8_WAIT_V(n) asm volatile("s_waitcnt vmcnt(" #n ")" ::: "memory")
; #define PG8_WAIT_L(n) asm volatile("s_waitcnt lgkmcnt(" #n ")" ::: "memory")
; #define PG8_BAR __builtin_amdgcn_s_barrier()
; #define PG8_SCHED __builtin_amdgcn_sched_barrier(0)
; template <class Epi>
; __device__ __forceinline__ void gemm_phase(LAS unsigned char* lds, const Gemm g, const StaticOrder& S, const Epi& E) {
;     ...
;             PG8_WAIT_V(8); PG8_WAIT_L(0); PG8_BAR; PG8_MMA(0, 0, At, B0); PG8_MMA(0, 1, At, B1); PG8_BAR; PG8_SCHED;
	v_mfma_f32_16x16x32_bf16 v[124:127], v[152:155], v[200:203], v[124:127]
	v_mfma_f32_16x16x32_bf16 v[120:123], v[162:165], v[200:203], v[120:123]
	v_mfma_f32_16x16x32_bf16 v[108:111], v[152:155], v[208:211], v[108:111]
	v_mfma_f32_16x16x32_bf16 v[104:107], v[162:165], v[208:211], v[104:107]
	v_mfma_f32_16x16x32_bf16 v[92:95], v[152:155], v[216:219], v[92:95]
	v_mfma_f32_16x16x32_bf16 v[88:91], v[162:165], v[216:219], v[88:91]
	v_mfma_f32_16x16x32_bf16 v[76:79], v[152:155], v[224:227], v[76:79]
	v_mfma_f32_16x16x32_bf16 v[72:75], v[162:165], v[224:227], v[72:75]
	v_mfma_f32_16x16x32_bf16 v[124:127], v[156:159], v[204:207], v[124:127]
	v_mfma_f32_16x16x32_bf16 v[120:123], v[180:183], v[204:207], v[120:123]
	v_mfma_f32_16x16x32_bf16 v[108:111], v[156:159], v[212:215], v[108:111]
	v_mfma_f32_16x16x32_bf16 v[104:107], v[180:183], v[212:215], v[104:107]
	v_mfma_f32_16x16x32_bf16 v[92:95], v[156:159], v[220:223], v[92:95]
	v_mfma_f32_16x16x32_bf16 v[88:91], v[180:183], v[220:223], v[88:91]
	v_mfma_f32_16x16x32_bf16 v[76:79], v[156:159], v[228:231], v[76:79]
	v_mfma_f32_16x16x32_bf16 v[72:75], v[180:183], v[228:231], v[72:75]


; #define PG8_STAGE(bufoff, gbase, voff) do { _Pragma("unroll") for (int _i = 0; _i < 2; ++_i) \
;         __builtin_amdgcn_global_load_lds((const unsigned*)((const char*)(gbase) + (voff)[_i]), (LAS unsigned*)(lds + (bufoff) + ldsw + _i * 8192), 16, 0, 0); } while (0)
; #define PG8_LDA(dst, b, h) do { _Pragma("unroll") for (int m = 0; m < 4; ++m) _Pragma("unroll") for (int k = 0; k < 2; ++k) dst[m][k] = *(const LAS bf16x8*)(lds + PG8_SA(b, h) + aoff + m * 2048 + k * 1024); } while (0)
; #define PG8_MMA(ai, bj, At, Bt) do { __builtin_amdgcn_s_setprio(1); _Pragma("unroll") for (int m = 0; m < 4; ++m) _Pragma("unroll") for (int n = 0; n < 2; ++n) _Pragma("unroll") for (int k = 0; k < 2; ++k) \
;         acc[ai][bj][m][n] = __builtin_amdgcn_mfma_f32_16x16x32_bf16(Bt[n][k], At[m][k], acc[ai][bj][m][n], 0, 0, 0); __builtin_amdgcn_s_setprio(0); } while (0)
; #define PG8_WAIT_V(n) asm volatile("s_waitcnt vmcnt(" #n ")" ::: "memory")
; #define PG8_WAIT_L(n) asm volatile("s_waitcnt lgkmcnt(" #n ")" ::: "memory")
; #define PG8_BAR __builtin_amdgcn_s_barrier()
; #define PG8_SCHED __builtin_amdgcn_sched_barrier(0)
; template <class Epi>
; __device__ __forceinline__ void gemm_phase(LAS unsigned char* lds, const Gemm g, const StaticOrder& S, const Epi& E) {
;     ...
;             PG8_WAIT_V(8); PG8_WAIT_L(0); PG8_BAR; PG8_MMA(0, 0, At, B0); PG8_MMA(0, 1, At, B1); PG8_BAR; PG8_SCHED;
;             PG8_LDA(At, 1, 1); PG8_STAGE(PG8_SB(1, 0), b3, voffB); PG8_STAGE(PG8_SB(1, 1), b3 + hsB, voffB); PG8_STAGE(PG8_SA(1, 0), a3, voffA);
;             PG8_WAIT_V(8); PG8_WAIT_L(0); PG8_BAR; PG8_MMA(1, 0, At, B0); PG8_MMA(1, 1, At, B1); PG8_BAR; PG8_SCHED;
	v_mfma_f32_16x16x32_bf16 v[116:119], v[184:187], v[200:203], v[116:119]
	v_mfma_f32_16x16x32_bf16 v[112:115], v[192:195], v[200:203], v[112:115]
	v_mfma_f32_16x16x32_bf16 v[100:103], v[184:187], v[208:211], v[100:103]
	v_mfma_f32_16x16x32_bf16 v[96:99], v[192:195], v[208:211], v[96:99]
	v_mfma_f32_16x16x32_bf16 v[84:87], v[184:187], v[216:219], v[84:87]
	v_mfma_f32_16x16x32_bf16 v[80:83], v[192:195], v[216:219], v[80:83]
	v_mfma_f32_16x16x32_bf16 v[68:71], v[184:187], v[224:227], v[68:71]
	v_mfma_f32_16x16x32_bf16 v[64:67], v[192:195], v[224:227], v[64:67]
	v_mfma_f32_16x16x32_bf16 v[116:119], v[188:191], v[204:207], v[116:119]
	v_mfma_f32_16x16x32_bf16 v[112:115], v[196:199], v[204:207], v[112:115]
	v_mfma_f32_16x16x32_bf16 v[100:103], v[188:191], v[212:215], v[100:103]
	v_mfma_f32_16x16x32_bf16 v[96:99], v[196:199], v[212:215], v[96:99]
	v_mfma_f32_16x16x32_bf16 v[84:87], v[188:191], v[220:223], v[84:87]
	v_mfma_f32_16x16x32_bf16 v[80:83], v[196:199], v[220:223], v[80:83]
	v_mfma_f32_16x16x32_bf16 v[68:71], v[188:191], v[228:231], v[68:71]
	v_mfma_f32_16x16x32_bf16 v[64:67], v[196:199], v[228:231], v[64:67]
	s_barrier
	s_setprio 0
	s_add_u32 s98, s12, 0x80
	s_addc_u32 s99, s13, 0
	s_add_u32 s100, s86, 0x80
	s_addc_u32 s101, s87, 0
	s_add_i32 s19, s19, s4
	s_mov_b32 m0, s19
	ds_read_b128 v[200:203], v169 offset:49152
	ds_read_b128 v[204:207], v169 offset:50176
	ds_read_b128 v[208:211], v169 offset:51200
	ds_read_b128 v[212:215], v169 offset:52224
	ds_read_b128 v[216:219], v169 offset:53248
	ds_read_b128 v[220:223], v169 offset:54272
	ds_read_b128 v[224:227], v169 offset:55296
	ds_read_b128 v[228:231], v169 offset:56320
	global_load_lds_dwordx4 v130, s[98:99]
	s_add_i32 m0, s19, 0x2000
	s_add_u32 s12, s12, 0x40080
	s_addc_u32 s13, s13, 0
	s_add_i32 s19, s22, s4
	global_load_lds_dwordx4 v134, s[98:99]
	s_mov_b32 m0, s19
	s_nop 0
	global_load_lds_dwordx4 v130, s[12:13]
	s_add_i32 m0, s19, 0x2000
	s_nop 0
	global_load_lds_dwordx4 v134, s[12:13]
	s_mov_b32 m0, s16
	s_nop 0
	global_load_lds_dwordx4 v128, s[100:101]
	s_mov_b32 m0, s33
	s_nop 0
	global_load_lds_dwordx4 v132, s[100:101]
	s_waitcnt vmcnt(8) lgkmcnt(0)

; #define PG8_MMA(ai, bj, At, Bt) do { __builtin_amdgcn_s_setprio(1); _Pragma("unroll") for (int m = 0; m < 4; ++m) _Pragma("unroll") for (int n = 0; n < 2; ++n) _Pragma("unroll") for (int k = 0; k < 2; ++k) \
;         acc[ai][bj][m][n] = __builtin_amdgcn_mfma_f32_16x16x32_bf16(Bt[n][k], At[m][k], acc[ai][bj][m][n], 0, 0, 0); __builtin_amdgcn_s_setprio(0); } while (0)
; #define PG8_WAIT_V(n) asm volatile("s_waitcnt vmcnt(" #n ")" ::: "memory")
; #define PG8_WAIT_L(n) asm volatile("s_waitcnt lgkmcnt(" #n ")" ::: "memory")
; #define PG8_BAR __builtin_amdgcn_s_barrier()
; #define PG8_SCHED __builtin_amdgcn_sched_barrier(0)
; template <class Epi>
; __device__ __forceinline__ void gemm_phase(LAS unsigned char* lds, const Gemm g, const StaticOrder& S, const Epi& E) {
;     ...
;             PG8_WAIT_V(8); PG8_WAIT_L(0); PG8_BAR; PG8_MMA(1, 0, At, B0); PG8_MMA(1, 1, At, B1); PG8_BAR; PG8_SCHED;
	s_setprio 1
	s_barrier

; #define PG8_MMA(ai, bj, At, Bt) do { __builtin_amdgcn_s_setprio(1); _Pragma("unroll") for (int m = 0; m < 4; ++m) _Pragma("unroll") for (int n = 0; n < 2; ++n) _Pragma("unroll") for (int k = 0; k < 2; ++k) \
;         acc[ai][bj][m][n] = __builtin_amdgcn_mfma_f32_16x16x32_bf16(Bt[n][k], At[m][k], acc[ai][bj][m][n], 0, 0, 0); __builtin_amdgcn_s_setprio(0); } while (0)
; #define PG8_WAIT_V(n) asm volatile("s_waitcnt vmcnt(" #n ")" ::: "memory")
; #define PG8_WAIT_L(n) asm volatile("s_waitcnt lgkmcnt(" #n ")" ::: "memory")
; #define PG8_BAR __builtin_amdgcn_s_barrier()
; #define PG8_SCHED __builtin_amdgcn_sched_barrier(0)
; template <class Epi>
; __device__ __forceinline__ void gemm_phase(LAS unsigned char* lds, const Gemm g, const StaticOrder& S, const Epi& E) {
;     ...
;             PG8_WAIT_V(8); PG8_WAIT_L(0); PG8_BAR; PG8_MMA(1, 0, At, B0); PG8_MMA(1, 1, At, B1); PG8_BAR; PG8_SCHED;
	v_mfma_f32_16x16x32_bf16 v[60:63], v[152:155], v[200:203], v[60:63]
	v_mfma_f32_16x16x32_bf16 v[56:59], v[162:165], v[200:203], v[56:59]
	v_mfma_f32_16x16x32_bf16 v[44:47], v[152:155], v[208:211], v[44:47]
	v_mfma_f32_16x16x32_bf16 v[40:43], v[162:165], v[208:211], v[40:43]
	v_mfma_f32_16x16x32_bf16 v[28:31], v[152:155], v[216:219], v[28:31]
	v_mfma_f32_16x16x32_bf16 v[24:27], v[162:165], v[216:219], v[24:27]
	v_mfma_f32_16x16x32_bf16 v[12:15], v[152:155], v[224:227], v[12:15]
	v_mfma_f32_16x16x32_bf16 v[8:11], v[162:165], v[224:227], v[8:11]
	v_mfma_f32_16x16x32_bf16 v[60:63], v[156:159], v[204:207], v[60:63]
	v_mfma_f32_16x16x32_bf16 v[56:59], v[180:183], v[204:207], v[56:59]
	v_mfma_f32_16x16x32_bf16 v[44:47], v[156:159], v[212:215], v[44:47]
	v_mfma_f32_16x16x32_bf16 v[40:43], v[180:183], v[212:215], v[40:43]
	v_mfma_f32_16x16x32_bf16 v[28:31], v[156:159], v[220:223], v[28:31]
	v_mfma_f32_16x16x32_bf16 v[24:27], v[180:183], v[220:223], v[24:27]
	v_mfma_f32_16x16x32_bf16 v[12:15], v[156:159], v[228:231], v[12:15]
	v_mfma_f32_16x16x32_bf16 v[8:11], v[180:183], v[228:231], v[8:11]


; #define PG8_MMA(ai, bj, At, Bt) do { __builtin_amdgcn_s_setprio(1); _Pragma("unroll") for (int m = 0; m < 4; ++m) _Pragma("unroll") for (int n = 0; n < 2; ++n) _Pragma("unroll") for (int k = 0; k < 2; ++k) \
;         acc[ai][bj][m][n] = __builtin_amdgcn_mfma_f32_16x16x32_bf16(Bt[n][k], At[m][k], acc[ai][bj][m][n], 0, 0, 0); __builtin_amdgcn_s_setprio(0); } while (0)
; #define PG8_WAIT_V(n) asm volatile("s_waitcnt vmcnt(" #n ")" ::: "memory")
; #define PG8_WAIT_L(n) asm volatile("s_waitcnt lgkmcnt(" #n ")" ::: "memory")
; #define PG8_BAR __builtin_amdgcn_s_barrier()
; #define PG8_SCHED __builtin_amdgcn_sched_barrier(0)
; template <class Epi>
; __device__ __forceinline__ void gemm_phase(LAS unsigned char* lds, const Gemm g, const StaticOrder& S, const Epi& E) {
;     ...
;             PG8_WAIT_V(8); PG8_WAIT_L(0); PG8_BAR; PG8_MMA(1, 0, At, B0); PG8_MMA(1, 1, At, B1); PG8_BAR; PG8_SCHED;
;         }
;         if (wr == 0) PG8_BAR;
	v_mfma_f32_16x16x32_bf16 v[52:55], v[184:187], v[200:203], v[52:55]
	v_mfma_f32_16x16x32_bf16 v[48:51], v[192:195], v[200:203], v[48:51]
	v_mfma_f32_16x16x32_bf16 v[36:39], v[184:187], v[208:211], v[36:39]
	v_mfma_f32_16x16x32_bf16 v[32:35], v[192:195], v[208:211], v[32:35]
	v_mfma_f32_16x16x32_bf16 v[20:23], v[184:187], v[216:219], v[20:23]
	v_mfma_f32_16x16x32_bf16 v[16:19], v[192:195], v[216:219], v[16:19]
	v_mfma_f32_16x16x32_bf16 v[4:7], v[184:187], v[224:227], v[4:7]
	v_mfma_f32_16x16x32_bf16 v[0:3], v[192:195], v[224:227], v[0:3]
	v_mfma_f32_16x16x32_bf16 v[52:55], v[188:191], v[204:207], v[52:55]
	v_mfma_f32_16x16x32_bf16 v[48:51], v[196:199], v[204:207], v[48:51]
	v_mfma_f32_16x16x32_bf16 v[36:39], v[188:191], v[212:215], v[36:39]
	v_mfma_f32_16x16x32_bf16 v[32:35], v[196:199], v[212:215], v[32:35]
	v_mfma_f32_16x16x32_bf16 v[20:23], v[188:191], v[220:223], v[20:23]
	v_mfma_f32_16x16x32_bf16 v[16:19], v[196:199], v[220:223], v[16:19]
	v_mfma_f32_16x16x32_bf16 v[4:7], v[188:191], v[228:231], v[4:7]
	v_mfma_f32_16x16x32_bf16 v[0:3], v[196:199], v[228:231], v[0:3]
	s_barrier
	s_setprio 0
	s_add_i32 s17, s17, 2
	s_add_u32 s10, s10, 0x100
	s_addc_u32 s11, s11, 0
	s_add_u32 s7, s7, 0x100
	s_addc_u32 s15, s15, 0
	s_cmp_gt_u32 s17, 13
	s_cbranch_scc0 .LBB0_414
	s_and_b64 vcc, exec, s[58:59]
	s_cbranch_vccz .LBB0_417
	s_barrier

; #define PG8_STAGE(bufoff, gbase, voff) do { _Pragma("unroll") for (int _i = 0; _i < 2; ++_i) \
;         __builtin_amdgcn_global_load_lds((const unsigned*)((const char*)(gbase) + (voff)[_i]), (LAS unsigned*)(lds + (bufoff) + ldsw + _i * 8192), 16, 0, 0); } while (0)
; #define PG8_LDA(dst, b, h) do { _Pragma("unroll") for (int m = 0; m < 4; ++m) _Pragma("unroll") for (int k = 0; k < 2; ++k) dst[m][k] = *(const LAS bf16x8*)(lds + PG8_SA(b, h) + aoff + m * 2048 + k * 1024); } while (0)
; #define PG8_LDB(dst, b, h) do { _Pragma("unroll") for (int n = 0; n < 2; ++n) _Pragma("unroll") for (int k = 0; k < 2; ++k) dst[n][k] = *(const LAS bf16x8*)(lds + PG8_SB(b, h) + boff + n * 2048 + k * 1024); } while (0)
; #define PG8_MMA(ai, bj, At, Bt) do { __builtin_amdgcn_s_setprio(1); _Pragma("unroll") for (int m = 0; m < 4; ++m) _Pragma("unroll") for (int n = 0; n < 2; ++n) _Pragma("unroll") for (int k = 0; k < 2; ++k) \
;         acc[ai][bj][m][n] = __builtin_amdgcn_mfma_f32_16x16x32_bf16(Bt[n][k], At[m][k], acc[ai][bj][m][n], 0, 0, 0); __builtin_amdgcn_s_setprio(0); } while (0)
; #define PG8_WAIT_V(n) asm volatile("s_waitcnt vmcnt(" #n ")" ::: "memory")
; #define PG8_WAIT_L(n) asm volatile("s_waitcnt lgkmcnt(" #n ")" ::: "memory")
; #define PG8_BAR __builtin_amdgcn_s_barrier()
; #define PG8_SCHED __builtin_amdgcn_sched_barrier(0)
; template <class Epi>
; __device__ __forceinline__ void gemm_phase(LAS unsigned char* lds, const Gemm g, const StaticOrder& S, const Epi& E) {
;     ...
;         for (int t = 0; t < nt; t += 2) {
;             const bool last = (t == nt - 2);
;             if constexpr (Epi::HAS_MID) { if (t == nt1) E.mid(acc, cur, wr, wc, fr, fq); }
;             const char* a1 = cA + ((Epi::HAS_MID && t >= nt1) ? dA2 : 0) + (size_t)(t + 1) * kstep;
;             const char* a2 = last ? nA : cA + ((Epi::HAS_MID && t + 2 >= nt1) ? dA2 : 0) + (size_t)(t + 2) * kstep; const char* b2 = last ? nB : cB + ((Epi::HAS_MID && t + 2 >= nt1) ? dB2 : 0) + (size_t)(t + 2) * kstep;
;             const char* a3 = a2 + kstep; const char* b3 = b2 + kstep;
;             PG8_LDB(B0, 0, 0); PG8_LDB(B1, 0, 1); PG8_SCHED; PG8_LDA(At, 0, 0); PG8_STAGE(PG8_SA(1, 1), a1 + hsA, voffA);
;             PG8_WAIT_V(8); PG8_WAIT_L(0); PG8_BAR; PG8_MMA(0, 0, At, B0); PG8_MMA(0, 1, At, B1); PG8_BAR; PG8_SCHED;
.LBB0_720:
	ds_read_b128 v[128:131], v182
	ds_read_b128 v[132:135], v182 offset:1024
	ds_read_b128 v[136:139], v182 offset:2048
	ds_read_b128 v[140:143], v182 offset:3072
	ds_read_b128 v[166:169], v183
	ds_read_b128 v[188:191], v183 offset:1024
	ds_read_b128 v[192:195], v183 offset:2048
	ds_read_b128 v[196:199], v183 offset:3072
	s_add_u32 s39, s62, 0xfffc0080
	s_addc_u32 s40, s63, -1
	s_cmp_eq_u32 s38, 12
	s_cselect_b32 s67, s6, s40
	s_cselect_b32 s66, s7, s39
	s_cselect_b32 s65, s15, s37
	s_cselect_b32 s64, s35, s36
	s_add_i32 m0, s4, 0xc000
	ds_read_b128 v[200:203], v184
	ds_read_b128 v[204:207], v184 offset:1024
	ds_read_b128 v[208:211], v184 offset:2048
	ds_read_b128 v[212:215], v184 offset:3072
	ds_read_b128 v[216:219], v184 offset:4096
	ds_read_b128 v[220:223], v184 offset:5120
	ds_read_b128 v[224:227], v184 offset:6144
	ds_read_b128 v[228:231], v184 offset:7168
	global_load_lds_dwordx4 v156, s[62:63]
	s_add_i32 m0, s4, 0xe000
	s_nop 0
	global_load_lds_dwordx4 v158, s[62:63]
	s_waitcnt vmcnt(8) lgkmcnt(0)

; #define PG8_MMA(ai, bj, At, Bt) do { __builtin_amdgcn_s_setprio(1); _Pragma("unroll") for (int m = 0; m < 4; ++m) _Pragma("unroll") for (int n = 0; n < 2; ++n) _Pragma("unroll") for (int k = 0; k < 2; ++k) \
;         acc[ai][bj][m][n] = __builtin_amdgcn_mfma_f32_16x16x32_bf16(Bt[n][k], At[m][k], acc[ai][bj][m][n], 0, 0, 0); __builtin_amdgcn_s_setprio(0); } while (0)
; #define PG8_WAIT_V(n) asm volatile("s_waitcnt vmcnt(" #n ")" ::: "memory")
; #define PG8_WAIT_L(n) asm volatile("s_waitcnt lgkmcnt(" #n ")" ::: "memory")
; #define PG8_BAR __builtin_amdgcn_s_barrier()
; #define PG8_SCHED __builtin_amdgcn_sched_barrier(0)
; template <class Epi>
; __device__ __forceinline__ void gemm_phase(LAS unsigned char* lds, const Gemm g, const StaticOrder& S, const Epi& E) {
;     ...
;             PG8_WAIT_V(8); PG8_WAIT_L(0); PG8_BAR; PG8_MMA(0, 0, At, B0); PG8_MMA(0, 1, At, B1); PG8_BAR; PG8_SCHED;
	s_setprio 1
	s_barrier

; #define PG8_MMA(ai, bj, At, Bt) do { __builtin_amdgcn_s_setprio(1); _Pragma("unroll") for (int m = 0; m < 4; ++m) _Pragma("unroll") for (int n = 0; n < 2; ++n) _Pragma("unroll") for (int k = 0; k < 2; ++k) \
;         acc[ai][bj][m][n] = __builtin_amdgcn_mfma_f32_16x16x32_bf16(Bt[n][k], At[m][k], acc[ai][bj][m][n], 0, 0, 0); __builtin_amdgcn_s_setprio(0); } while (0)
; #define PG8_WAIT_V(n) asm volatile("s_waitcnt vmcnt(" #n ")" ::: "memory")
; #define PG8_WAIT_L(n) asm volatile("s_waitcnt lgkmcnt(" #n ")" ::: "memory")
; #define PG8_BAR __builtin_amdgcn_s_barrier()
; #define PG8_SCHED __builtin_amdgcn_sched_barrier(0)
; template <class Epi>
; __device__ __forceinline__ void gemm_phase(LAS unsigned char* lds, const Gemm g, const StaticOrder& S, const Epi& E) {
;     ...
;             PG8_WAIT_V(8); PG8_WAIT_L(0); PG8_BAR; PG8_MMA(0, 0, At, B0); PG8_MMA(0, 1, At, B1); PG8_BAR; PG8_SCHED;
	v_mfma_f32_16x16x32_bf16 v[124:127], v[128:131], v[200:203], v[124:127]
	v_mfma_f32_16x16x32_bf16 v[120:123], v[136:139], v[200:203], v[120:123]
	v_mfma_f32_16x16x32_bf16 v[108:111], v[128:131], v[208:211], v[108:111]
	v_mfma_f32_16x16x32_bf16 v[104:107], v[136:139], v[208:211], v[104:107]
	v_mfma_f32_16x16x32_bf16 v[92:95], v[128:131], v[216:219], v[92:95]
	v_mfma_f32_16x16x32_bf16 v[88:91], v[136:139], v[216:219], v[88:91]
	v_mfma_f32_16x16x32_bf16 v[76:79], v[128:131], v[224:227], v[76:79]
	v_mfma_f32_16x16x32_bf16 v[72:75], v[136:139], v[224:227], v[72:75]
	v_mfma_f32_16x16x32_bf16 v[124:127], v[132:135], v[204:207], v[124:127]
	v_mfma_f32_16x16x32_bf16 v[120:123], v[140:143], v[204:207], v[120:123]
	v_mfma_f32_16x16x32_bf16 v[108:111], v[132:135], v[212:215], v[108:111]
	v_mfma_f32_16x16x32_bf16 v[104:107], v[140:143], v[212:215], v[104:107]
	v_mfma_f32_16x16x32_bf16 v[92:95], v[132:135], v[220:223], v[92:95]
	v_mfma_f32_16x16x32_bf16 v[88:91], v[140:143], v[220:223], v[88:91]
	v_mfma_f32_16x16x32_bf16 v[76:79], v[132:135], v[228:231], v[76:79]
	v_mfma_f32_16x16x32_bf16 v[72:75], v[140:143], v[228:231], v[72:75]


; #define PG8_STAGE(bufoff, gbase, voff) do { _Pragma("unroll") for (int _i = 0; _i < 2; ++_i) \
;         __builtin_amdgcn_global_load_lds((const unsigned*)((const char*)(gbase) + (voff)[_i]), (LAS unsigned*)(lds + (bufoff) + ldsw + _i * 8192), 16, 0, 0); } while (0)
; #define PG8_LDA(dst, b, h) do { _Pragma("unroll") for (int m = 0; m < 4; ++m) _Pragma("unroll") for (int k = 0; k < 2; ++k) dst[m][k] = *(const LAS bf16x8*)(lds + PG8_SA(b, h) + aoff + m * 2048 + k * 1024); } while (0)
; #define PG8_MMA(ai, bj, At, Bt) do { __builtin_amdgcn_s_setprio(1); _Pragma("unroll") for (int m = 0; m < 4; ++m) _Pragma("unroll") for (int n = 0; n < 2; ++n) _Pragma("unroll") for (int k = 0; k < 2; ++k) \
;         acc[ai][bj][m][n] = __builtin_amdgcn_mfma_f32_16x16x32_bf16(Bt[n][k], At[m][k], acc[ai][bj][m][n], 0, 0, 0); __builtin_amdgcn_s_setprio(0); } while (0)
; #define PG8_WAIT_V(n) asm volatile("s_waitcnt vmcnt(" #n ")" ::: "memory")
; #define PG8_WAIT_L(n) asm volatile("s_waitcnt lgkmcnt(" #n ")" ::: "memory")
; #define PG8_BAR __builtin_amdgcn_s_barrier()
; #define PG8_SCHED __builtin_amdgcn_sched_barrier(0)
; template <class Epi>
; __device__ __forceinline__ void gemm_phase(LAS unsigned char* lds, const Gemm g, const StaticOrder& S, const Epi& E) {
;     ...
;             PG8_WAIT_V(8); PG8_WAIT_L(0); PG8_BAR; PG8_MMA(0, 0, At, B0); PG8_MMA(0, 1, At, B1); PG8_BAR; PG8_SCHED;
;             PG8_LDA(At, 0, 1); PG8_STAGE(PG8_SB(0, 0), b2, voffB); PG8_STAGE(PG8_SB(0, 1), b2 + hsB, voffB); PG8_STAGE(PG8_SA(0, 0), a2, voffA);
;             PG8_WAIT_V(8); PG8_WAIT_L(0); PG8_BAR; PG8_MMA(1, 0, At, B0); PG8_MMA(1, 1, At, B1); PG8_BAR; PG8_SCHED;
	v_mfma_f32_16x16x32_bf16 v[116:119], v[166:169], v[200:203], v[116:119]
	v_mfma_f32_16x16x32_bf16 v[112:115], v[192:195], v[200:203], v[112:115]
	v_mfma_f32_16x16x32_bf16 v[100:103], v[166:169], v[208:211], v[100:103]
	v_mfma_f32_16x16x32_bf16 v[96:99], v[192:195], v[208:211], v[96:99]
	v_mfma_f32_16x16x32_bf16 v[84:87], v[166:169], v[216:219], v[84:87]
	v_mfma_f32_16x16x32_bf16 v[80:83], v[192:195], v[216:219], v[80:83]
	v_mfma_f32_16x16x32_bf16 v[68:71], v[166:169], v[224:227], v[68:71]
	v_mfma_f32_16x16x32_bf16 v[64:67], v[192:195], v[224:227], v[64:67]
	v_mfma_f32_16x16x32_bf16 v[116:119], v[188:191], v[204:207], v[116:119]
	v_mfma_f32_16x16x32_bf16 v[112:115], v[196:199], v[204:207], v[112:115]
	v_mfma_f32_16x16x32_bf16 v[100:103], v[188:191], v[212:215], v[100:103]
	v_mfma_f32_16x16x32_bf16 v[96:99], v[196:199], v[212:215], v[96:99]
	v_mfma_f32_16x16x32_bf16 v[84:87], v[188:191], v[220:223], v[84:87]
	v_mfma_f32_16x16x32_bf16 v[80:83], v[196:199], v[220:223], v[80:83]
	v_mfma_f32_16x16x32_bf16 v[68:71], v[188:191], v[228:231], v[68:71]
	v_mfma_f32_16x16x32_bf16 v[64:67], v[196:199], v[228:231], v[64:67]
	s_barrier
	s_setprio 0
	s_add_i32 s39, s27, s3
	s_mov_b32 m0, s39
	ds_read_b128 v[200:203], v184 offset:16384
	ds_read_b128 v[204:207], v184 offset:17408
	ds_read_b128 v[208:211], v184 offset:18432
	ds_read_b128 v[212:215], v184 offset:19456
	ds_read_b128 v[216:219], v184 offset:20480
	ds_read_b128 v[220:223], v184 offset:21504
	ds_read_b128 v[224:227], v184 offset:22528
	ds_read_b128 v[228:231], v184 offset:23552
	global_load_lds_dwordx4 v146, s[64:65]
	s_add_i32 m0, s39, 0x2000
	s_add_u32 s40, s64, 0x40000
	s_addc_u32 s41, s65, 0
	s_add_i32 s39, s28, s3
	global_load_lds_dwordx4 v150, s[64:65]
	s_mov_b32 m0, s39
	s_nop 0
	global_load_lds_dwordx4 v146, s[40:41]
	s_add_i32 m0, s39, 0x2000
	s_nop 0
	global_load_lds_dwordx4 v150, s[40:41]
	s_mov_b32 m0, s4
	s_nop 0
	global_load_lds_dwordx4 v144, s[66:67]
	s_mov_b32 m0, s5
	s_nop 0
	global_load_lds_dwordx4 v148, s[66:67]
	s_waitcnt vmcnt(8) lgkmcnt(0)

; #define PG8_MMA(ai, bj, At, Bt) do { __builtin_amdgcn_s_setprio(1); _Pragma("unroll") for (int m = 0; m < 4; ++m) _Pragma("unroll") for (int n = 0; n < 2; ++n) _Pragma("unroll") for (int k = 0; k < 2; ++k) \
;         acc[ai][bj][m][n] = __builtin_amdgcn_mfma_f32_16x16x32_bf16(Bt[n][k], At[m][k], acc[ai][bj][m][n], 0, 0, 0); __builtin_amdgcn_s_setprio(0); } while (0)
; #define PG8_WAIT_V(n) asm volatile("s_waitcnt vmcnt(" #n ")" ::: "memory")
; #define PG8_WAIT_L(n) asm volatile("s_waitcnt lgkmcnt(" #n ")" ::: "memory")
; #define PG8_BAR __builtin_amdgcn_s_barrier()
; #define PG8_SCHED __builtin_amdgcn_sched_barrier(0)
; template <class Epi>
; __device__ __forceinline__ void gemm_phase(LAS unsigned char* lds, const Gemm g, const StaticOrder& S, const Epi& E) {
;     ...
;             PG8_WAIT_V(8); PG8_WAIT_L(0); PG8_BAR; PG8_MMA(1, 0, At, B0); PG8_MMA(1, 1, At, B1); PG8_BAR; PG8_SCHED;
	s_setprio 1
	s_barrier

	v_mfma_f32_16x16x32_bf16 v[60:63], v[128:131], v[200:203], v[60:63]
	v_mfma_f32_16x16x32_bf16 v[56:59], v[136:139], v[200:203], v[56:59]
	v_mfma_f32_16x16x32_bf16 v[44:47], v[128:131], v[208:211], v[44:47]
	v_mfma_f32_16x16x32_bf16 v[40:43], v[136:139], v[208:211], v[40:43]
	v_mfma_f32_16x16x32_bf16 v[28:31], v[128:131], v[216:219], v[28:31]
	v_mfma_f32_16x16x32_bf16 v[24:27], v[136:139], v[216:219], v[24:27]
	v_mfma_f32_16x16x32_bf16 v[12:15], v[128:131], v[224:227], v[12:15]
	v_mfma_f32_16x16x32_bf16 v[8:11], v[136:139], v[224:227], v[8:11]
	v_mfma_f32_16x16x32_bf16 v[60:63], v[132:135], v[204:207], v[60:63]
	v_mfma_f32_16x16x32_bf16 v[56:59], v[140:143], v[204:207], v[56:59]
	v_mfma_f32_16x16x32_bf16 v[44:47], v[132:135], v[212:215], v[44:47]
	v_mfma_f32_16x16x32_bf16 v[40:43], v[140:143], v[212:215], v[40:43]
	v_mfma_f32_16x16x32_bf16 v[28:31], v[132:135], v[220:223], v[28:31]
	v_mfma_f32_16x16x32_bf16 v[24:27], v[140:143], v[220:223], v[24:27]
	v_mfma_f32_16x16x32_bf16 v[12:15], v[132:135], v[228:231], v[12:15]
	v_mfma_f32_16x16x32_bf16 v[8:11], v[140:143], v[228:231], v[8:11]


; #define PG8_STAGE(bufoff, gbase, voff) do { _Pragma("unroll") for (int _i = 0; _i < 2; ++_i) \
;         __builtin_amdgcn_global_load_lds((const unsigned*)((const char*)(gbase) + (voff)[_i]), (LAS unsigned*)(lds + (bufoff) + ldsw + _i * 8192), 16, 0, 0); } while (0)
; #define PG8_LDA(dst, b, h) do { _Pragma("unroll") for (int m = 0; m < 4; ++m) _Pragma("unroll") for (int k = 0; k < 2; ++k) dst[m][k] = *(const LAS bf16x8*)(lds + PG8_SA(b, h) + aoff + m * 2048 + k * 1024); } while (0)
; #define PG8_LDB(dst, b, h) do { _Pragma("unroll") for (int n = 0; n < 2; ++n) _Pragma("unroll") for (int k = 0; k < 2; ++k) dst[n][k] = *(const LAS bf16x8*)(lds + PG8_SB(b, h) + boff + n * 2048 + k * 1024); } while (0)
; #define PG8_SCHED __builtin_amdgcn_sched_barrier(0)
; template <class Epi>
; __device__ __forceinline__ void gemm_phase(LAS unsigned char* lds, const Gemm g, const StaticOrder& S, const Epi& E) {
;     ...
;             PG8_LDB(B0, 1, 0); PG8_LDB(B1, 1, 1); PG8_SCHED; PG8_LDA(At, 1, 0); PG8_STAGE(PG8_SA(0, 1), a2 + hsA, voffA);
	v_mfma_f32_16x16x32_bf16 v[52:55], v[166:169], v[200:203], v[52:55]
	v_mfma_f32_16x16x32_bf16 v[48:51], v[192:195], v[200:203], v[48:51]
	v_mfma_f32_16x16x32_bf16 v[36:39], v[166:169], v[208:211], v[36:39]
	v_mfma_f32_16x16x32_bf16 v[32:35], v[192:195], v[208:211], v[32:35]
	v_mfma_f32_16x16x32_bf16 v[20:23], v[166:169], v[216:219], v[20:23]
	v_mfma_f32_16x16x32_bf16 v[16:19], v[192:195], v[216:219], v[16:19]
	v_mfma_f32_16x16x32_bf16 v[4:7], v[166:169], v[224:227], v[4:7]
	v_mfma_f32_16x16x32_bf16 v[0:3], v[192:195], v[224:227], v[0:3]
	v_mfma_f32_16x16x32_bf16 v[52:55], v[188:191], v[204:207], v[52:55]
	v_mfma_f32_16x16x32_bf16 v[48:51], v[196:199], v[204:207], v[48:51]
	v_mfma_f32_16x16x32_bf16 v[36:39], v[188:191], v[212:215], v[36:39]
	v_mfma_f32_16x16x32_bf16 v[32:35], v[196:199], v[212:215], v[32:35]
	v_mfma_f32_16x16x32_bf16 v[20:23], v[188:191], v[220:223], v[20:23]
	v_mfma_f32_16x16x32_bf16 v[16:19], v[196:199], v[220:223], v[16:19]
	v_mfma_f32_16x16x32_bf16 v[4:7], v[188:191], v[228:231], v[4:7]
	v_mfma_f32_16x16x32_bf16 v[0:3], v[196:199], v[228:231], v[0:3]
	s_barrier
	s_setprio 0
	s_add_i32 s39, 0, 0x18000
	s_add_i32 s42, 0, 0x1c000
	v_add_u32_e32 v140, s39, v173
	v_add_u32_e32 v152, s42, v173
	ds_read_b128 v[128:131], v140
	ds_read_b128 v[132:135], v140 offset:1024
	ds_read_b128 v[136:139], v140 offset:2048
	ds_read_b128 v[140:143], v140 offset:3072
	ds_read_b128 v[166:169], v152
	ds_read_b128 v[188:191], v152 offset:1024
	ds_read_b128 v[192:195], v152 offset:2048
	ds_read_b128 v[196:199], v152 offset:3072
	s_add_u32 s40, s66, 0x40000
	s_addc_u32 s41, s67, 0
	s_mov_b32 m0, s16
	ds_read_b128 v[200:203], v184 offset:32768
	ds_read_b128 v[204:207], v184 offset:33792
	ds_read_b128 v[208:211], v184 offset:34816
	ds_read_b128 v[212:215], v184 offset:35840
	ds_read_b128 v[216:219], v184 offset:36864
	ds_read_b128 v[220:223], v184 offset:37888
	ds_read_b128 v[224:227], v184 offset:38912
	ds_read_b128 v[228:231], v184 offset:39936
	global_load_lds_dwordx4 v144, s[40:41]
	s_mov_b32 m0, s17
	s_nop 0
	global_load_lds_dwordx4 v148, s[40:41]
	s_waitcnt vmcnt(8) lgkmcnt(0)

; #define PG8_MMA(ai, bj, At, Bt) do { __builtin_amdgcn_s_setprio(1); _Pragma("unroll") for (int m = 0; m < 4; ++m) _Pragma("unroll") for (int n = 0; n < 2; ++n) _Pragma("unroll") for (int k = 0; k < 2; ++k) \
;         acc[ai][bj][m][n] = __builtin_amdgcn_mfma_f32_16x16x32_bf16(Bt[n][k], At[m][k], acc[ai][bj][m][n], 0, 0, 0); __builtin_amdgcn_s_setprio(0); } while (0)
; #define PG8_WAIT_V(n) asm volatile("s_waitcnt vmcnt(" #n ")" ::: "memory")
; #define PG8_WAIT_L(n) asm volatile("s_waitcnt lgkmcnt(" #n ")" ::: "memory")
; #define PG8_BAR __builtin_amdgcn_s_barrier()
; #define PG8_SCHED __builtin_amdgcn_sched_barrier(0)
; template <class Epi>
; __device__ __forceinline__ void gemm_phase(LAS unsigned char* lds, const Gemm g, const StaticOrder& S, const Epi& E) {
;     ...
;             PG8_WAIT_V(8); PG8_WAIT_L(0); PG8_BAR; PG8_MMA(0, 0, At, B0); PG8_MMA(0, 1, At, B1); PG8_BAR; PG8_SCHED;
	s_setprio 1
	s_barrier

	v_mfma_f32_16x16x32_bf16 v[124:127], v[128:131], v[200:203], v[124:127]
	v_mfma_f32_16x16x32_bf16 v[120:123], v[136:139], v[200:203], v[120:123]
	v_mfma_f32_16x16x32_bf16 v[108:111], v[128:131], v[208:211], v[108:111]
	v_mfma_f32_16x16x32_bf16 v[104:107], v[136:139], v[208:211], v[104:107]
	v_mfma_f32_16x16x32_bf16 v[92:95], v[128:131], v[216:219], v[92:95]
	v_mfma_f32_16x16x32_bf16 v[88:91], v[136:139], v[216:219], v[88:91]
	v_mfma_f32_16x16x32_bf16 v[76:79], v[128:131], v[224:227], v[76:79]
	v_mfma_f32_16x16x32_bf16 v[72:75], v[136:139], v[224:227], v[72:75]
	v_mfma_f32_16x16x32_bf16 v[124:127], v[132:135], v[204:207], v[124:127]
	v_mfma_f32_16x16x32_bf16 v[120:123], v[140:143], v[204:207], v[120:123]
	v_mfma_f32_16x16x32_bf16 v[108:111], v[132:135], v[212:215], v[108:111]
	v_mfma_f32_16x16x32_bf16 v[104:107], v[140:143], v[212:215], v[104:107]
	v_mfma_f32_16x16x32_bf16 v[92:95], v[132:135], v[220:223], v[92:95]
	v_mfma_f32_16x16x32_bf16 v[88:91], v[140:143], v[220:223], v[88:91]
	v_mfma_f32_16x16x32_bf16 v[76:79], v[132:135], v[228:231], v[76:79]
	v_mfma_f32_16x16x32_bf16 v[72:75], v[140:143], v[228:231], v[72:75]


; #define PG8_STAGE(bufoff, gbase, voff) do { _Pragma("unroll") for (int _i = 0; _i < 2; ++_i) \
;         __builtin_amdgcn_global_load_lds((const unsigned*)((const char*)(gbase) + (voff)[_i]), (LAS unsigned*)(lds + (bufoff) + ldsw + _i * 8192), 16, 0, 0); } while (0)
; #define PG8_LDA(dst, b, h) do { _Pragma("unroll") for (int m = 0; m < 4; ++m) _Pragma("unroll") for (int k = 0; k < 2; ++k) dst[m][k] = *(const LAS bf16x8*)(lds + PG8_SA(b, h) + aoff + m * 2048 + k * 1024); } while (0)
; template <class Epi>
; __device__ __forceinline__ void gemm_phase(LAS unsigned char* lds, const Gemm g, const StaticOrder& S, const Epi& E) {
;     ...
;             PG8_LDA(At, 1, 1); PG8_STAGE(PG8_SB(1, 0), b3, voffB); PG8_STAGE(PG8_SB(1, 1), b3 + hsB, voffB); PG8_STAGE(PG8_SA(1, 0), a3, voffA);
	v_mfma_f32_16x16x32_bf16 v[116:119], v[166:169], v[200:203], v[116:119]
	v_mfma_f32_16x16x32_bf16 v[112:115], v[192:195], v[200:203], v[112:115]
	v_mfma_f32_16x16x32_bf16 v[100:103], v[166:169], v[208:211], v[100:103]
	v_mfma_f32_16x16x32_bf16 v[96:99], v[192:195], v[208:211], v[96:99]
	v_mfma_f32_16x16x32_bf16 v[84:87], v[166:169], v[216:219], v[84:87]
	v_mfma_f32_16x16x32_bf16 v[80:83], v[192:195], v[216:219], v[80:83]
	v_mfma_f32_16x16x32_bf16 v[68:71], v[166:169], v[224:227], v[68:71]
	v_mfma_f32_16x16x32_bf16 v[64:67], v[192:195], v[224:227], v[64:67]
	v_mfma_f32_16x16x32_bf16 v[116:119], v[188:191], v[204:207], v[116:119]
	v_mfma_f32_16x16x32_bf16 v[112:115], v[196:199], v[204:207], v[112:115]
	v_mfma_f32_16x16x32_bf16 v[100:103], v[188:191], v[212:215], v[100:103]
	v_mfma_f32_16x16x32_bf16 v[96:99], v[196:199], v[212:215], v[96:99]
	v_mfma_f32_16x16x32_bf16 v[84:87], v[188:191], v[220:223], v[84:87]
	v_mfma_f32_16x16x32_bf16 v[80:83], v[196:199], v[220:223], v[80:83]
	v_mfma_f32_16x16x32_bf16 v[68:71], v[188:191], v[228:231], v[68:71]
	v_mfma_f32_16x16x32_bf16 v[64:67], v[196:199], v[228:231], v[64:67]
	s_barrier
	s_setprio 0
	s_add_u32 s98, s64, 0x80
	s_addc_u32 s99, s65, 0
	s_add_u32 s100, s66, 0x80
	s_addc_u32 s101, s67, 0
	s_add_i32 s39, s39, s3
	s_mov_b32 m0, s39
	ds_read_b128 v[200:203], v184 offset:49152
	ds_read_b128 v[204:207], v184 offset:50176
	ds_read_b128 v[208:211], v184 offset:51200
	ds_read_b128 v[212:215], v184 offset:52224
	ds_read_b128 v[216:219], v184 offset:53248
	ds_read_b128 v[220:223], v184 offset:54272
	ds_read_b128 v[224:227], v184 offset:55296
	ds_read_b128 v[228:231], v184 offset:56320
	global_load_lds_dwordx4 v146, s[98:99]
	s_add_i32 m0, s39, 0x2000
	s_add_u32 s40, s64, 0x40080
	s_addc_u32 s41, s65, 0
	s_add_i32 s39, s42, s3
	global_load_lds_dwordx4 v150, s[98:99]
	s_mov_b32 m0, s39
	s_nop 0
	global_load_lds_dwordx4 v146, s[40:41]
	s_add_i32 m0, s39, 0x2000
	s_nop 0
	global_load_lds_dwordx4 v150, s[40:41]
	s_mov_b32 m0, s22
	s_nop 0
	global_load_lds_dwordx4 v144, s[100:101]
	s_mov_b32 m0, s23
	s_nop 0
	global_load_lds_dwordx4 v148, s[100:101]
	s_waitcnt vmcnt(8) lgkmcnt(0)

; #define PG8_MMA(ai, bj, At, Bt) do { __builtin_amdgcn_s_setprio(1); _Pragma("unroll") for (int m = 0; m < 4; ++m) _Pragma("unroll") for (int n = 0; n < 2; ++n) _Pragma("unroll") for (int k = 0; k < 2; ++k) \
;         acc[ai][bj][m][n] = __builtin_amdgcn_mfma_f32_16x16x32_bf16(Bt[n][k], At[m][k], acc[ai][bj][m][n], 0, 0, 0); __builtin_amdgcn_s_setprio(0); } while (0)
; #define PG8_WAIT_V(n) asm volatile("s_waitcnt vmcnt(" #n ")" ::: "memory")
; #define PG8_WAIT_L(n) asm volatile("s_waitcnt lgkmcnt(" #n ")" ::: "memory")
; #define PG8_BAR __builtin_amdgcn_s_barrier()
; #define PG8_SCHED __builtin_amdgcn_sched_barrier(0)
; template <class Epi>
; __device__ __forceinline__ void gemm_phase(LAS unsigned char* lds, const Gemm g, const StaticOrder& S, const Epi& E) {
;     ...
;             PG8_WAIT_V(8); PG8_WAIT_L(0); PG8_BAR; PG8_MMA(0, 0, At, B0); PG8_MMA(0, 1, At, B1); PG8_BAR; PG8_SCHED;
	s_setprio 1
	s_barrier

	v_mfma_f32_16x16x32_bf16 v[60:63], v[128:131], v[200:203], v[60:63]
	v_mfma_f32_16x16x32_bf16 v[56:59], v[136:139], v[200:203], v[56:59]
	v_mfma_f32_16x16x32_bf16 v[44:47], v[128:131], v[208:211], v[44:47]
	v_mfma_f32_16x16x32_bf16 v[40:43], v[136:139], v[208:211], v[40:43]
	v_mfma_f32_16x16x32_bf16 v[28:31], v[128:131], v[216:219], v[28:31]
	v_mfma_f32_16x16x32_bf16 v[24:27], v[136:139], v[216:219], v[24:27]
	v_mfma_f32_16x16x32_bf16 v[12:15], v[128:131], v[224:227], v[12:15]
	v_mfma_f32_16x16x32_bf16 v[8:11], v[136:139], v[224:227], v[8:11]
	v_mfma_f32_16x16x32_bf16 v[60:63], v[132:135], v[204:207], v[60:63]
	v_mfma_f32_16x16x32_bf16 v[56:59], v[140:143], v[204:207], v[56:59]
	v_mfma_f32_16x16x32_bf16 v[44:47], v[132:135], v[212:215], v[44:47]
	v_mfma_f32_16x16x32_bf16 v[40:43], v[140:143], v[212:215], v[40:43]
	v_mfma_f32_16x16x32_bf16 v[28:31], v[132:135], v[220:223], v[28:31]
	v_mfma_f32_16x16x32_bf16 v[24:27], v[140:143], v[220:223], v[24:27]
	v_mfma_f32_16x16x32_bf16 v[12:15], v[132:135], v[228:231], v[12:15]
	v_mfma_f32_16x16x32_bf16 v[8:11], v[140:143], v[228:231], v[8:11]


; #define PG8_BAR __builtin_amdgcn_s_barrier()
; template <class Epi>
; __device__ __forceinline__ void gemm_phase(LAS unsigned char* lds, const Gemm g, const StaticOrder& S, const Epi& E) {
;     ...
;         for (int t = 0; t < nt; t += 2) {
;     ...
;         if (wr == 0) PG8_BAR;
	v_mfma_f32_16x16x32_bf16 v[52:55], v[166:169], v[200:203], v[52:55]
	v_mfma_f32_16x16x32_bf16 v[48:51], v[192:195], v[200:203], v[48:51]
	v_mfma_f32_16x16x32_bf16 v[36:39], v[166:169], v[208:211], v[36:39]
	v_mfma_f32_16x16x32_bf16 v[32:35], v[192:195], v[208:211], v[32:35]
	v_mfma_f32_16x16x32_bf16 v[20:23], v[166:169], v[216:219], v[20:23]
	v_mfma_f32_16x16x32_bf16 v[16:19], v[192:195], v[216:219], v[16:19]
	v_mfma_f32_16x16x32_bf16 v[4:7], v[166:169], v[224:227], v[4:7]
	v_mfma_f32_16x16x32_bf16 v[0:3], v[192:195], v[224:227], v[0:3]
	v_mfma_f32_16x16x32_bf16 v[52:55], v[188:191], v[204:207], v[52:55]
	v_mfma_f32_16x16x32_bf16 v[48:51], v[196:199], v[204:207], v[48:51]
	v_mfma_f32_16x16x32_bf16 v[36:39], v[188:191], v[212:215], v[36:39]
	v_mfma_f32_16x16x32_bf16 v[32:35], v[196:199], v[212:215], v[32:35]
	v_mfma_f32_16x16x32_bf16 v[20:23], v[188:191], v[220:223], v[20:23]
	v_mfma_f32_16x16x32_bf16 v[16:19], v[196:199], v[220:223], v[16:19]
	v_mfma_f32_16x16x32_bf16 v[4:7], v[188:191], v[228:231], v[4:7]
	v_mfma_f32_16x16x32_bf16 v[0:3], v[196:199], v[228:231], v[0:3]
	s_barrier
	s_setprio 0
	s_add_i32 s38, s38, 2
	s_add_u32 s62, s62, 0x100
	s_addc_u32 s63, s63, 0
	s_add_u32 s36, s36, 0x100
	s_addc_u32 s37, s37, 0
	s_cmp_gt_u32 s38, 13
	s_cbranch_scc0 .LBB0_720
	s_and_b64 vcc, exec, s[12:13]
	s_cbranch_vccz .LBB0_723
	s_barrier

; #define PG8_STAGE(bufoff, gbase, voff) do { _Pragma("unroll") for (int _i = 0; _i < 2; ++_i) \
;         __builtin_amdgcn_global_load_lds((const unsigned*)((const char*)(gbase) + (voff)[_i]), (LAS unsigned*)(lds + (bufoff) + ldsw + _i * 8192), 16, 0, 0); } while (0)
; #define PG8_LDA(dst, b, h) do { _Pragma("unroll") for (int m = 0; m < 4; ++m) _Pragma("unroll") for (int k = 0; k < 2; ++k) dst[m][k] = *(const LAS bf16x8*)(lds + PG8_SA(b, h) + aoff + m * 2048 + k * 1024); } while (0)
; #define PG8_LDB(dst, b, h) do { _Pragma("unroll") for (int n = 0; n < 2; ++n) _Pragma("unroll") for (int k = 0; k < 2; ++k) dst[n][k] = *(const LAS bf16x8*)(lds + PG8_SB(b, h) + boff + n * 2048 + k * 1024); } while (0)
; #define PG8_SCHED __builtin_amdgcn_sched_barrier(0)
; template <class Epi>
; __device__ __forceinline__ void gemm_phase(LAS unsigned char* lds, const Gemm g, const StaticOrder& S, const Epi& E) {
;     ...
;             const bool last = (t == nt - 2);
;             if constexpr (Epi::HAS_MID) { if (t == nt1) E.mid(acc, cur, wr, wc, fr, fq); }
;             const char* a1 = cA + ((Epi::HAS_MID && t >= nt1) ? dA2 : 0) + (size_t)(t + 1) * kstep;
;             const char* a2 = last ? nA : cA + ((Epi::HAS_MID && t + 2 >= nt1) ? dA2 : 0) + (size_t)(t + 2) * kstep; const char* b2 = last ? nB : cB + ((Epi::HAS_MID && t + 2 >= nt1) ? dB2 : 0) + (size_t)(t + 2) * kstep;
;             const char* a3 = a2 + kstep; const char* b3 = b2 + kstep;
;             PG8_LDB(B0, 0, 0); PG8_LDB(B1, 0, 1); PG8_SCHED; PG8_LDA(At, 0, 0); PG8_STAGE(PG8_SA(1, 1), a1 + hsA, voffA);
.LBB0_1083:
	s_add_i32 s33, s33, 2
	s_add_u32 s0, s52, s54
	s_addc_u32 s1, s53, s55
	s_add_u32 s0, s0, 0x100
	v_add_u32_e32 v153, s74, v171
	s_addc_u32 s1, s1, 0
	ds_read_b128 v[128:131], v153
	ds_read_b128 v[132:135], v153 offset:1024
	ds_read_b128 v[164:167], v153 offset:2048
	ds_read_b128 v[184:187], v153 offset:3072
	v_add_u32_e32 v153, s75, v171
	s_cmp_gt_u32 s33, 13
	ds_read_b128 v[188:191], v153
	ds_read_b128 v[192:195], v153 offset:1024
	ds_read_b128 v[196:199], v153 offset:2048
	ds_read_b128 v[200:203], v153 offset:3072
	s_cselect_b32 s17, 0x1ff800, 0
	s_add_u32 s17, s17, s54
	s_addc_u32 s24, 0, s55
	s_add_u32 s17, s22, s17
	s_addc_u32 s24, s23, s24
	s_cmpk_eq_i32 s54, 0xf00
	s_cselect_b32 s59, s6, s1
	s_cselect_b32 s58, s7, s0
	s_cselect_b32 s57, s16, s24
	s_cselect_b32 s56, s18, s17
	v_lshl_add_u64 v[168:169], v[158:159], 0, s[54:55]
	s_add_i32 m0, s61, 0xc000
	ds_read_b128 v[204:207], v173
	ds_read_b128 v[208:211], v173 offset:1024
	ds_read_b128 v[212:215], v173 offset:2048
	ds_read_b128 v[216:219], v173 offset:3072
	ds_read_b128 v[220:223], v173 offset:4096
	ds_read_b128 v[224:227], v173 offset:5120
	ds_read_b128 v[228:231], v173 offset:6144
	ds_read_b128 v[232:235], v173 offset:7168
	global_load_lds_dwordx4 v[168:169], off
	v_lshl_add_u64 v[168:169], v[162:163], 0, s[54:55]
	s_add_i32 m0, s61, 0xe000
	s_nop 0
	global_load_lds_dwordx4 v[168:169], off
	s_waitcnt vmcnt(8) lgkmcnt(0)

; #define PG8_MMA(ai, bj, At, Bt) do { __builtin_amdgcn_s_setprio(1); _Pragma("unroll") for (int m = 0; m < 4; ++m) _Pragma("unroll") for (int n = 0; n < 2; ++n) _Pragma("unroll") for (int k = 0; k < 2; ++k) \
;         acc[ai][bj][m][n] = __builtin_amdgcn_mfma_f32_16x16x32_bf16(Bt[n][k], At[m][k], acc[ai][bj][m][n], 0, 0, 0); __builtin_amdgcn_s_setprio(0); } while (0)
; #define PG8_WAIT_V(n) asm volatile("s_waitcnt vmcnt(" #n ")" ::: "memory")
; #define PG8_WAIT_L(n) asm volatile("s_waitcnt lgkmcnt(" #n ")" ::: "memory")
; #define PG8_BAR __builtin_amdgcn_s_barrier()
; #define PG8_SCHED __builtin_amdgcn_sched_barrier(0)
; template <class Epi>
; __device__ __forceinline__ void gemm_phase(LAS unsigned char* lds, const Gemm g, const StaticOrder& S, const Epi& E) {
;     ...
;             PG8_WAIT_V(8); PG8_WAIT_L(0); PG8_BAR; PG8_MMA(0, 0, At, B0); PG8_MMA(0, 1, At, B1); PG8_BAR; PG8_SCHED;
	s_setprio 1
	s_barrier

	v_mfma_f32_16x16x32_bf16 v[124:127], v[128:131], v[204:207], v[124:127]
	v_mfma_f32_16x16x32_bf16 v[120:123], v[164:167], v[204:207], v[120:123]
	v_mfma_f32_16x16x32_bf16 v[108:111], v[128:131], v[212:215], v[108:111]
	v_mfma_f32_16x16x32_bf16 v[104:107], v[164:167], v[212:215], v[104:107]
	v_mfma_f32_16x16x32_bf16 v[92:95], v[128:131], v[220:223], v[92:95]
	v_mfma_f32_16x16x32_bf16 v[88:91], v[164:167], v[220:223], v[88:91]
	v_mfma_f32_16x16x32_bf16 v[76:79], v[128:131], v[228:231], v[76:79]
	v_mfma_f32_16x16x32_bf16 v[72:75], v[164:167], v[228:231], v[72:75]
	v_mfma_f32_16x16x32_bf16 v[124:127], v[132:135], v[208:211], v[124:127]
	v_mfma_f32_16x16x32_bf16 v[120:123], v[184:187], v[208:211], v[120:123]
	v_mfma_f32_16x16x32_bf16 v[108:111], v[132:135], v[216:219], v[108:111]
	v_mfma_f32_16x16x32_bf16 v[104:107], v[184:187], v[216:219], v[104:107]
	v_mfma_f32_16x16x32_bf16 v[92:95], v[132:135], v[224:227], v[92:95]
	v_mfma_f32_16x16x32_bf16 v[88:91], v[184:187], v[224:227], v[88:91]
	v_mfma_f32_16x16x32_bf16 v[76:79], v[132:135], v[232:235], v[76:79]
	v_mfma_f32_16x16x32_bf16 v[72:75], v[184:187], v[232:235], v[72:75]


; #define PG8_STAGE(bufoff, gbase, voff) do { _Pragma("unroll") for (int _i = 0; _i < 2; ++_i) \
;         __builtin_amdgcn_global_load_lds((const unsigned*)((const char*)(gbase) + (voff)[_i]), (LAS unsigned*)(lds + (bufoff) + ldsw + _i * 8192), 16, 0, 0); } while (0)
; #define PG8_LDA(dst, b, h) do { _Pragma("unroll") for (int m = 0; m < 4; ++m) _Pragma("unroll") for (int k = 0; k < 2; ++k) dst[m][k] = *(const LAS bf16x8*)(lds + PG8_SA(b, h) + aoff + m * 2048 + k * 1024); } while (0)
; template <class Epi>
; __device__ __forceinline__ void gemm_phase(LAS unsigned char* lds, const Gemm g, const StaticOrder& S, const Epi& E) {
;     ...
;             PG8_LDA(At, 0, 1); PG8_STAGE(PG8_SB(0, 0), b2, voffB); PG8_STAGE(PG8_SB(0, 1), b2 + hsB, voffB); PG8_STAGE(PG8_SA(0, 0), a2, voffA);
	v_mfma_f32_16x16x32_bf16 v[116:119], v[188:191], v[204:207], v[116:119]
	v_mfma_f32_16x16x32_bf16 v[112:115], v[196:199], v[204:207], v[112:115]
	v_mfma_f32_16x16x32_bf16 v[100:103], v[188:191], v[212:215], v[100:103]
	v_mfma_f32_16x16x32_bf16 v[96:99], v[196:199], v[212:215], v[96:99]
	v_mfma_f32_16x16x32_bf16 v[84:87], v[188:191], v[220:223], v[84:87]
	v_mfma_f32_16x16x32_bf16 v[80:83], v[196:199], v[220:223], v[80:83]
	v_mfma_f32_16x16x32_bf16 v[68:71], v[188:191], v[228:231], v[68:71]
	v_mfma_f32_16x16x32_bf16 v[64:67], v[196:199], v[228:231], v[64:67]
	v_mfma_f32_16x16x32_bf16 v[116:119], v[192:195], v[208:211], v[116:119]
	v_mfma_f32_16x16x32_bf16 v[112:115], v[200:203], v[208:211], v[112:115]
	v_mfma_f32_16x16x32_bf16 v[100:103], v[192:195], v[216:219], v[100:103]
	v_mfma_f32_16x16x32_bf16 v[96:99], v[200:203], v[216:219], v[96:99]
	v_mfma_f32_16x16x32_bf16 v[84:87], v[192:195], v[224:227], v[84:87]
	v_mfma_f32_16x16x32_bf16 v[80:83], v[200:203], v[224:227], v[80:83]
	v_mfma_f32_16x16x32_bf16 v[68:71], v[192:195], v[232:235], v[68:71]
	v_mfma_f32_16x16x32_bf16 v[64:67], v[200:203], v[232:235], v[64:67]
	s_barrier
	s_setprio 0
	s_add_i32 s0, s74, s60
	v_lshl_add_u64 v[168:169], s[56:57], 0, v[138:139]
	s_mov_b32 m0, s0
	ds_read_b128 v[204:207], v173 offset:16384
	ds_read_b128 v[208:211], v173 offset:17408
	ds_read_b128 v[212:215], v173 offset:18432
	ds_read_b128 v[216:219], v173 offset:19456
	ds_read_b128 v[220:223], v173 offset:20480
	ds_read_b128 v[224:227], v173 offset:21504
	ds_read_b128 v[228:231], v173 offset:22528
	ds_read_b128 v[232:235], v173 offset:23552
	global_load_lds_dwordx4 v[168:169], off
	s_add_i32 m0, s0, 0x2000
	s_add_u32 s0, s56, 0x40000
	v_lshl_add_u64 v[236:237], s[56:57], 0, v[142:143]
	s_addc_u32 s1, s57, 0
	s_add_i32 s17, s75, s60
	global_load_lds_dwordx4 v[236:237], off
	v_lshl_add_u64 v[238:239], s[0:1], 0, v[138:139]
	s_mov_b32 m0, s17
	v_lshl_add_u64 v[240:241], s[58:59], 0, v[140:141]
	global_load_lds_dwordx4 v[238:239], off
	v_lshl_add_u64 v[238:239], s[0:1], 0, v[142:143]
	s_add_i32 m0, s17, 0x2000
	s_nop 0
	global_load_lds_dwordx4 v[238:239], off
	v_lshl_add_u64 v[238:239], s[58:59], 0, v[136:137]
	s_mov_b32 m0, s61
	s_nop 0
	global_load_lds_dwordx4 v[238:239], off
	s_mov_b32 m0, s4
	s_nop 0
	global_load_lds_dwordx4 v[240:241], off
	s_waitcnt vmcnt(8) lgkmcnt(0)

; #define PG8_MMA(ai, bj, At, Bt) do { __builtin_amdgcn_s_setprio(1); _Pragma("unroll") for (int m = 0; m < 4; ++m) _Pragma("unroll") for (int n = 0; n < 2; ++n) _Pragma("unroll") for (int k = 0; k < 2; ++k) \
;         acc[ai][bj][m][n] = __builtin_amdgcn_mfma_f32_16x16x32_bf16(Bt[n][k], At[m][k], acc[ai][bj][m][n], 0, 0, 0); __builtin_amdgcn_s_setprio(0); } while (0)
; #define PG8_WAIT_V(n) asm volatile("s_waitcnt vmcnt(" #n ")" ::: "memory")
; #define PG8_WAIT_L(n) asm volatile("s_waitcnt lgkmcnt(" #n ")" ::: "memory")
; #define PG8_BAR __builtin_amdgcn_s_barrier()
; #define PG8_SCHED __builtin_amdgcn_sched_barrier(0)
; template <class Epi>
; __device__ __forceinline__ void gemm_phase(LAS unsigned char* lds, const Gemm g, const StaticOrder& S, const Epi& E) {
;     ...
;             PG8_WAIT_V(8); PG8_WAIT_L(0); PG8_BAR; PG8_MMA(1, 0, At, B0); PG8_MMA(1, 1, At, B1); PG8_BAR; PG8_SCHED;
	s_setprio 1
	s_barrier

	v_mfma_f32_16x16x32_bf16 v[60:63], v[128:131], v[204:207], v[60:63]
	v_mfma_f32_16x16x32_bf16 v[56:59], v[164:167], v[204:207], v[56:59]
	v_mfma_f32_16x16x32_bf16 v[44:47], v[128:131], v[212:215], v[44:47]
	v_mfma_f32_16x16x32_bf16 v[40:43], v[164:167], v[212:215], v[40:43]
	v_mfma_f32_16x16x32_bf16 v[28:31], v[128:131], v[220:223], v[28:31]
	v_mfma_f32_16x16x32_bf16 v[24:27], v[164:167], v[220:223], v[24:27]
	v_mfma_f32_16x16x32_bf16 v[12:15], v[128:131], v[228:231], v[12:15]
	v_mfma_f32_16x16x32_bf16 v[8:11], v[164:167], v[228:231], v[8:11]
	v_mfma_f32_16x16x32_bf16 v[60:63], v[132:135], v[208:211], v[60:63]
	v_mfma_f32_16x16x32_bf16 v[56:59], v[184:187], v[208:211], v[56:59]
	v_mfma_f32_16x16x32_bf16 v[44:47], v[132:135], v[216:219], v[44:47]
	v_mfma_f32_16x16x32_bf16 v[40:43], v[184:187], v[216:219], v[40:43]
	v_mfma_f32_16x16x32_bf16 v[28:31], v[132:135], v[224:227], v[28:31]
	v_mfma_f32_16x16x32_bf16 v[24:27], v[184:187], v[224:227], v[24:27]
	v_mfma_f32_16x16x32_bf16 v[12:15], v[132:135], v[232:235], v[12:15]
	v_mfma_f32_16x16x32_bf16 v[8:11], v[184:187], v[232:235], v[8:11]


; #define PG8_STAGE(bufoff, gbase, voff) do { _Pragma("unroll") for (int _i = 0; _i < 2; ++_i) \
;         __builtin_amdgcn_global_load_lds((const unsigned*)((const char*)(gbase) + (voff)[_i]), (LAS unsigned*)(lds + (bufoff) + ldsw + _i * 8192), 16, 0, 0); } while (0)
; #define PG8_LDA(dst, b, h) do { _Pragma("unroll") for (int m = 0; m < 4; ++m) _Pragma("unroll") for (int k = 0; k < 2; ++k) dst[m][k] = *(const LAS bf16x8*)(lds + PG8_SA(b, h) + aoff + m * 2048 + k * 1024); } while (0)
; #define PG8_LDB(dst, b, h) do { _Pragma("unroll") for (int n = 0; n < 2; ++n) _Pragma("unroll") for (int k = 0; k < 2; ++k) dst[n][k] = *(const LAS bf16x8*)(lds + PG8_SB(b, h) + boff + n * 2048 + k * 1024); } while (0)
; #define PG8_SCHED __builtin_amdgcn_sched_barrier(0)
; template <class Epi>
; __device__ __forceinline__ void gemm_phase(LAS unsigned char* lds, const Gemm g, const StaticOrder& S, const Epi& E) {
;     ...
;             PG8_LDB(B0, 1, 0); PG8_LDB(B1, 1, 1); PG8_SCHED; PG8_LDA(At, 1, 0); PG8_STAGE(PG8_SA(0, 1), a2 + hsA, voffA);
	v_mfma_f32_16x16x32_bf16 v[52:55], v[188:191], v[204:207], v[52:55]
	v_mfma_f32_16x16x32_bf16 v[48:51], v[196:199], v[204:207], v[48:51]
	v_mfma_f32_16x16x32_bf16 v[36:39], v[188:191], v[212:215], v[36:39]
	v_mfma_f32_16x16x32_bf16 v[32:35], v[196:199], v[212:215], v[32:35]
	v_mfma_f32_16x16x32_bf16 v[20:23], v[188:191], v[220:223], v[20:23]
	v_mfma_f32_16x16x32_bf16 v[16:19], v[196:199], v[220:223], v[16:19]
	v_mfma_f32_16x16x32_bf16 v[4:7], v[188:191], v[228:231], v[4:7]
	v_mfma_f32_16x16x32_bf16 v[0:3], v[196:199], v[228:231], v[0:3]
	v_mfma_f32_16x16x32_bf16 v[52:55], v[192:195], v[208:211], v[52:55]
	v_mfma_f32_16x16x32_bf16 v[48:51], v[200:203], v[208:211], v[48:51]
	v_mfma_f32_16x16x32_bf16 v[36:39], v[192:195], v[216:219], v[36:39]
	v_mfma_f32_16x16x32_bf16 v[32:35], v[200:203], v[216:219], v[32:35]
	v_mfma_f32_16x16x32_bf16 v[20:23], v[192:195], v[224:227], v[20:23]
	v_mfma_f32_16x16x32_bf16 v[16:19], v[200:203], v[224:227], v[16:19]
	v_mfma_f32_16x16x32_bf16 v[4:7], v[192:195], v[232:235], v[4:7]
	v_mfma_f32_16x16x32_bf16 v[0:3], v[200:203], v[232:235], v[0:3]
	s_barrier
	s_setprio 0
	s_add_i32 s17, 0, 0x18000
	v_add_u32_e32 v153, s17, v171
	s_add_i32 s24, 0, 0x1c000
	ds_read_b128 v[128:131], v153
	ds_read_b128 v[132:135], v153 offset:1024
	ds_read_b128 v[164:167], v153 offset:2048
	ds_read_b128 v[184:187], v153 offset:3072
	v_add_u32_e32 v153, s24, v171
	ds_read_b128 v[188:191], v153
	ds_read_b128 v[192:195], v153 offset:1024
	ds_read_b128 v[196:199], v153 offset:2048
	ds_read_b128 v[200:203], v153 offset:3072
	s_add_u32 s0, s58, 0x100000
	s_addc_u32 s1, s59, 0
	s_mov_b32 m0, s5
	v_lshl_add_u64 v[242:243], s[0:1], 0, v[136:137]
	ds_read_b128 v[204:207], v173 offset:32768
	ds_read_b128 v[208:211], v173 offset:33792
	ds_read_b128 v[212:215], v173 offset:34816
	ds_read_b128 v[216:219], v173 offset:35840
	ds_read_b128 v[220:223], v173 offset:36864
	ds_read_b128 v[224:227], v173 offset:37888
	ds_read_b128 v[228:231], v173 offset:38912
	ds_read_b128 v[232:235], v173 offset:39936
	global_load_lds_dwordx4 v[242:243], off
	v_lshl_add_u64 v[242:243], s[0:1], 0, v[140:141]
	s_mov_b32 m0, s62
	s_nop 0
	global_load_lds_dwordx4 v[242:243], off
	s_waitcnt vmcnt(8) lgkmcnt(0)

; #define PG8_MMA(ai, bj, At, Bt) do { __builtin_amdgcn_s_setprio(1); _Pragma("unroll") for (int m = 0; m < 4; ++m) _Pragma("unroll") for (int n = 0; n < 2; ++n) _Pragma("unroll") for (int k = 0; k < 2; ++k) \
;         acc[ai][bj][m][n] = __builtin_amdgcn_mfma_f32_16x16x32_bf16(Bt[n][k], At[m][k], acc[ai][bj][m][n], 0, 0, 0); __builtin_amdgcn_s_setprio(0); } while (0)
; #define PG8_WAIT_V(n) asm volatile("s_waitcnt vmcnt(" #n ")" ::: "memory")
; #define PG8_WAIT_L(n) asm volatile("s_waitcnt lgkmcnt(" #n ")" ::: "memory")
; #define PG8_BAR __builtin_amdgcn_s_barrier()
; #define PG8_SCHED __builtin_amdgcn_sched_barrier(0)
; template <class Epi>
; __device__ __forceinline__ void gemm_phase(LAS unsigned char* lds, const Gemm g, const StaticOrder& S, const Epi& E) {
;     ...
;             PG8_WAIT_V(8); PG8_WAIT_L(0); PG8_BAR; PG8_MMA(0, 0, At, B0); PG8_MMA(0, 1, At, B1); PG8_BAR; PG8_SCHED;
	s_setprio 1
	s_barrier

	v_mfma_f32_16x16x32_bf16 v[124:127], v[128:131], v[204:207], v[124:127]
	v_mfma_f32_16x16x32_bf16 v[120:123], v[164:167], v[204:207], v[120:123]
	v_mfma_f32_16x16x32_bf16 v[108:111], v[128:131], v[212:215], v[108:111]
	v_mfma_f32_16x16x32_bf16 v[104:107], v[164:167], v[212:215], v[104:107]
	v_mfma_f32_16x16x32_bf16 v[92:95], v[128:131], v[220:223], v[92:95]
	v_mfma_f32_16x16x32_bf16 v[88:91], v[164:167], v[220:223], v[88:91]
	v_mfma_f32_16x16x32_bf16 v[76:79], v[128:131], v[228:231], v[76:79]
	v_mfma_f32_16x16x32_bf16 v[72:75], v[164:167], v[228:231], v[72:75]
	v_mfma_f32_16x16x32_bf16 v[124:127], v[132:135], v[208:211], v[124:127]
	v_mfma_f32_16x16x32_bf16 v[120:123], v[184:187], v[208:211], v[120:123]
	v_mfma_f32_16x16x32_bf16 v[108:111], v[132:135], v[216:219], v[108:111]
	v_mfma_f32_16x16x32_bf16 v[104:107], v[184:187], v[216:219], v[104:107]
	v_mfma_f32_16x16x32_bf16 v[92:95], v[132:135], v[224:227], v[92:95]
	v_mfma_f32_16x16x32_bf16 v[88:91], v[184:187], v[224:227], v[88:91]
	v_mfma_f32_16x16x32_bf16 v[76:79], v[132:135], v[232:235], v[76:79]
	v_mfma_f32_16x16x32_bf16 v[72:75], v[184:187], v[232:235], v[72:75]


; #define PG8_STAGE(bufoff, gbase, voff) do { _Pragma("unroll") for (int _i = 0; _i < 2; ++_i) \
;         __builtin_amdgcn_global_load_lds((const unsigned*)((const char*)(gbase) + (voff)[_i]), (LAS unsigned*)(lds + (bufoff) + ldsw + _i * 8192), 16, 0, 0); } while (0)
; #define PG8_LDA(dst, b, h) do { _Pragma("unroll") for (int m = 0; m < 4; ++m) _Pragma("unroll") for (int k = 0; k < 2; ++k) dst[m][k] = *(const LAS bf16x8*)(lds + PG8_SA(b, h) + aoff + m * 2048 + k * 1024); } while (0)
; template <class Epi>
; __device__ __forceinline__ void gemm_phase(LAS unsigned char* lds, const Gemm g, const StaticOrder& S, const Epi& E) {
;     ...
;             PG8_LDA(At, 1, 1); PG8_STAGE(PG8_SB(1, 0), b3, voffB); PG8_STAGE(PG8_SB(1, 1), b3 + hsB, voffB); PG8_STAGE(PG8_SA(1, 0), a3, voffA);
	v_mfma_f32_16x16x32_bf16 v[116:119], v[188:191], v[204:207], v[116:119]
	v_mfma_f32_16x16x32_bf16 v[112:115], v[196:199], v[204:207], v[112:115]
	v_mfma_f32_16x16x32_bf16 v[100:103], v[188:191], v[212:215], v[100:103]
	v_mfma_f32_16x16x32_bf16 v[96:99], v[196:199], v[212:215], v[96:99]
	v_mfma_f32_16x16x32_bf16 v[84:87], v[188:191], v[220:223], v[84:87]
	v_mfma_f32_16x16x32_bf16 v[80:83], v[196:199], v[220:223], v[80:83]
	v_mfma_f32_16x16x32_bf16 v[68:71], v[188:191], v[228:231], v[68:71]
	v_mfma_f32_16x16x32_bf16 v[64:67], v[196:199], v[228:231], v[64:67]
	v_mfma_f32_16x16x32_bf16 v[116:119], v[192:195], v[208:211], v[116:119]
	v_mfma_f32_16x16x32_bf16 v[112:115], v[200:203], v[208:211], v[112:115]
	v_mfma_f32_16x16x32_bf16 v[100:103], v[192:195], v[216:219], v[100:103]
	v_mfma_f32_16x16x32_bf16 v[96:99], v[200:203], v[216:219], v[96:99]
	v_mfma_f32_16x16x32_bf16 v[84:87], v[192:195], v[224:227], v[84:87]
	v_mfma_f32_16x16x32_bf16 v[80:83], v[200:203], v[224:227], v[80:83]
	v_mfma_f32_16x16x32_bf16 v[68:71], v[192:195], v[232:235], v[68:71]
	v_mfma_f32_16x16x32_bf16 v[64:67], v[200:203], v[232:235], v[64:67]
	s_barrier
	s_setprio 0
	s_add_i32 s0, s17, s60
	v_lshl_add_u64 v[168:169], v[168:169], 0, s[10:11]
	s_mov_b32 m0, s0
	ds_read_b128 v[204:207], v173 offset:49152
	ds_read_b128 v[208:211], v173 offset:50176
	ds_read_b128 v[212:215], v173 offset:51200
	ds_read_b128 v[216:219], v173 offset:52224
	ds_read_b128 v[220:223], v173 offset:53248
	ds_read_b128 v[224:227], v173 offset:54272
	ds_read_b128 v[228:231], v173 offset:55296
	ds_read_b128 v[232:235], v173 offset:56320
	global_load_lds_dwordx4 v[168:169], off
	s_add_i32 m0, s0, 0x2000
	s_add_u32 s0, s56, 0x40080
	v_lshl_add_u64 v[168:169], v[236:237], 0, s[10:11]
	s_addc_u32 s1, s57, 0
	s_add_i32 s17, s24, s60
	global_load_lds_dwordx4 v[168:169], off
	v_lshl_add_u64 v[168:169], s[0:1], 0, v[138:139]
	s_mov_b32 m0, s17
	s_nop 0
	global_load_lds_dwordx4 v[168:169], off
	v_lshl_add_u64 v[168:169], s[0:1], 0, v[142:143]
	s_add_i32 m0, s17, 0x2000
	s_nop 0
	global_load_lds_dwordx4 v[168:169], off
	v_lshl_add_u64 v[168:169], v[238:239], 0, s[10:11]
	s_mov_b32 m0, s64
	s_nop 0
	global_load_lds_dwordx4 v[168:169], off
	v_lshl_add_u64 v[168:169], v[240:241], 0, s[10:11]
	s_mov_b32 m0, s65
	s_nop 0
	global_load_lds_dwordx4 v[168:169], off
	s_waitcnt vmcnt(8) lgkmcnt(0)

; #define PG8_MMA(ai, bj, At, Bt) do { __builtin_amdgcn_s_setprio(1); _Pragma("unroll") for (int m = 0; m < 4; ++m) _Pragma("unroll") for (int n = 0; n < 2; ++n) _Pragma("unroll") for (int k = 0; k < 2; ++k) \
;         acc[ai][bj][m][n] = __builtin_amdgcn_mfma_f32_16x16x32_bf16(Bt[n][k], At[m][k], acc[ai][bj][m][n], 0, 0, 0); __builtin_amdgcn_s_setprio(0); } while (0)
; #define PG8_WAIT_V(n) asm volatile("s_waitcnt vmcnt(" #n ")" ::: "memory")
; #define PG8_WAIT_L(n) asm volatile("s_waitcnt lgkmcnt(" #n ")" ::: "memory")
; #define PG8_BAR __builtin_amdgcn_s_barrier()
; #define PG8_SCHED __builtin_amdgcn_sched_barrier(0)
; template <class Epi>
; __device__ __forceinline__ void gemm_phase(LAS unsigned char* lds, const Gemm g, const StaticOrder& S, const Epi& E) {
;     ...
;             PG8_WAIT_V(8); PG8_WAIT_L(0); PG8_BAR; PG8_MMA(1, 0, At, B0); PG8_MMA(1, 1, At, B1); PG8_BAR; PG8_SCHED;
	s_setprio 1
	s_barrier

	v_mfma_f32_16x16x32_bf16 v[60:63], v[128:131], v[204:207], v[60:63]
	v_mfma_f32_16x16x32_bf16 v[56:59], v[164:167], v[204:207], v[56:59]
	v_mfma_f32_16x16x32_bf16 v[44:47], v[128:131], v[212:215], v[44:47]
	v_mfma_f32_16x16x32_bf16 v[40:43], v[164:167], v[212:215], v[40:43]
	v_mfma_f32_16x16x32_bf16 v[28:31], v[128:131], v[220:223], v[28:31]
	v_mfma_f32_16x16x32_bf16 v[24:27], v[164:167], v[220:223], v[24:27]
	v_mfma_f32_16x16x32_bf16 v[12:15], v[128:131], v[228:231], v[12:15]
	v_mfma_f32_16x16x32_bf16 v[8:11], v[164:167], v[228:231], v[8:11]
	v_mfma_f32_16x16x32_bf16 v[60:63], v[132:135], v[208:211], v[60:63]
	v_mfma_f32_16x16x32_bf16 v[56:59], v[184:187], v[208:211], v[56:59]
	v_mfma_f32_16x16x32_bf16 v[44:47], v[132:135], v[216:219], v[44:47]
	v_mfma_f32_16x16x32_bf16 v[40:43], v[184:187], v[216:219], v[40:43]
	v_mfma_f32_16x16x32_bf16 v[28:31], v[132:135], v[224:227], v[28:31]
	v_mfma_f32_16x16x32_bf16 v[24:27], v[184:187], v[224:227], v[24:27]
	v_mfma_f32_16x16x32_bf16 v[12:15], v[132:135], v[232:235], v[12:15]
	v_mfma_f32_16x16x32_bf16 v[8:11], v[184:187], v[232:235], v[8:11]


; template <class Epi>
; __device__ __forceinline__ void gemm_phase(LAS unsigned char* lds, const Gemm g, const StaticOrder& S, const Epi& E) {
;     ...
;         for (int t = 0; t < nt; t += 2) {
	v_mfma_f32_16x16x32_bf16 v[52:55], v[188:191], v[204:207], v[52:55]
	v_mfma_f32_16x16x32_bf16 v[48:51], v[196:199], v[204:207], v[48:51]
	v_mfma_f32_16x16x32_bf16 v[36:39], v[188:191], v[212:215], v[36:39]
	v_mfma_f32_16x16x32_bf16 v[32:35], v[196:199], v[212:215], v[32:35]
	v_mfma_f32_16x16x32_bf16 v[20:23], v[188:191], v[220:223], v[20:23]
	v_mfma_f32_16x16x32_bf16 v[16:19], v[196:199], v[220:223], v[16:19]
	v_mfma_f32_16x16x32_bf16 v[4:7], v[188:191], v[228:231], v[4:7]
	v_mfma_f32_16x16x32_bf16 v[0:3], v[196:199], v[228:231], v[0:3]
	v_mfma_f32_16x16x32_bf16 v[52:55], v[192:195], v[208:211], v[52:55]
	v_mfma_f32_16x16x32_bf16 v[48:51], v[200:203], v[208:211], v[48:51]
	v_mfma_f32_16x16x32_bf16 v[36:39], v[192:195], v[216:219], v[36:39]
	v_mfma_f32_16x16x32_bf16 v[32:35], v[200:203], v[216:219], v[32:35]
	v_mfma_f32_16x16x32_bf16 v[20:23], v[192:195], v[224:227], v[20:23]
	v_mfma_f32_16x16x32_bf16 v[16:19], v[200:203], v[224:227], v[16:19]
	v_mfma_f32_16x16x32_bf16 v[4:7], v[192:195], v[232:235], v[4:7]
	v_mfma_f32_16x16x32_bf16 v[0:3], v[200:203], v[232:235], v[0:3]
	s_barrier
	s_setprio 0
	s_add_u32 s54, s54, 0x100
	s_addc_u32 s55, 0, s55
	s_cmp_gt_u32 s33, 29
	s_cbranch_scc1 .LBB0_1086

; #define PG8_STAGE(bufoff, gbase, voff) do { _Pragma("unroll") for (int _i = 0; _i < 2; ++_i) \
;         __builtin_amdgcn_global_load_lds((const unsigned*)((const char*)(gbase) + (voff)[_i]), (LAS unsigned*)(lds + (bufoff) + ldsw + _i * 8192), 16, 0, 0); } while (0)
; #define PG8_LDA(dst, b, h) do { _Pragma("unroll") for (int m = 0; m < 4; ++m) _Pragma("unroll") for (int k = 0; k < 2; ++k) dst[m][k] = *(const LAS bf16x8*)(lds + PG8_SA(b, h) + aoff + m * 2048 + k * 1024); } while (0)
; #define PG8_LDB(dst, b, h) do { _Pragma("unroll") for (int n = 0; n < 2; ++n) _Pragma("unroll") for (int k = 0; k < 2; ++k) dst[n][k] = *(const LAS bf16x8*)(lds + PG8_SB(b, h) + boff + n * 2048 + k * 1024); } while (0)
; #define PG8_SCHED __builtin_amdgcn_sched_barrier(0)
; template <class Epi>
; __device__ __forceinline__ void gemm_phase(LAS unsigned char* lds, const Gemm g, const StaticOrder& S, const Epi& E) {
;     ...
;             const bool last = (t == nt - 2);
;             if constexpr (Epi::HAS_MID) { if (t == nt1) E.mid(acc, cur, wr, wc, fr, fq); }
;             const char* a1 = cA + ((Epi::HAS_MID && t >= nt1) ? dA2 : 0) + (size_t)(t + 1) * kstep;
;             const char* a2 = last ? nA : cA + ((Epi::HAS_MID && t + 2 >= nt1) ? dA2 : 0) + (size_t)(t + 2) * kstep; const char* b2 = last ? nB : cB + ((Epi::HAS_MID && t + 2 >= nt1) ? dB2 : 0) + (size_t)(t + 2) * kstep;
;             const char* a3 = a2 + kstep; const char* b3 = b2 + kstep;
;             PG8_LDB(B0, 0, 0); PG8_LDB(B1, 0, 1); PG8_SCHED; PG8_LDA(At, 0, 0); PG8_STAGE(PG8_SA(1, 1), a1 + hsA, voffA);
.LBB0_1234:
	ds_read_b128 v[144:147], v155
	ds_read_b128 v[148:151], v155 offset:1024
	ds_read_b128 v[162:165], v155 offset:2048
	ds_read_b128 v[166:169], v155 offset:3072
	ds_read_b128 v[170:173], v156
	ds_read_b128 v[174:177], v156 offset:1024
	ds_read_b128 v[184:187], v156 offset:2048
	ds_read_b128 v[188:191], v156 offset:3072
	s_add_u32 s39, s48, 0xfffc0080
	s_addc_u32 s41, s49, -1
	s_cmp_eq_u32 s35, 12
	s_cselect_b32 s53, s0, s41
	s_cselect_b32 s52, s1, s39
	s_cselect_b32 s51, s6, s34
	s_cselect_b32 s50, s7, s13
	s_add_i32 m0, s5, 0xc000
	ds_read_b128 v[192:195], v157
	ds_read_b128 v[196:199], v157 offset:1024
	ds_read_b128 v[200:203], v157 offset:2048
	ds_read_b128 v[204:207], v157 offset:3072
	ds_read_b128 v[208:211], v157 offset:4096
	ds_read_b128 v[212:215], v157 offset:5120
	ds_read_b128 v[216:219], v157 offset:6144
	ds_read_b128 v[220:223], v157 offset:7168
	global_load_lds_dwordx4 v136, s[48:49]
	s_add_i32 m0, s5, 0xe000
	s_nop 0
	global_load_lds_dwordx4 v138, s[48:49]
	s_waitcnt vmcnt(8) lgkmcnt(0)

; #define PG8_MMA(ai, bj, At, Bt) do { __builtin_amdgcn_s_setprio(1); _Pragma("unroll") for (int m = 0; m < 4; ++m) _Pragma("unroll") for (int n = 0; n < 2; ++n) _Pragma("unroll") for (int k = 0; k < 2; ++k) \
;         acc[ai][bj][m][n] = __builtin_amdgcn_mfma_f32_16x16x32_bf16(Bt[n][k], At[m][k], acc[ai][bj][m][n], 0, 0, 0); __builtin_amdgcn_s_setprio(0); } while (0)
; #define PG8_WAIT_V(n) asm volatile("s_waitcnt vmcnt(" #n ")" ::: "memory")
; #define PG8_WAIT_L(n) asm volatile("s_waitcnt lgkmcnt(" #n ")" ::: "memory")
; #define PG8_BAR __builtin_amdgcn_s_barrier()
; #define PG8_SCHED __builtin_amdgcn_sched_barrier(0)
; template <class Epi>
; __device__ __forceinline__ void gemm_phase(LAS unsigned char* lds, const Gemm g, const StaticOrder& S, const Epi& E) {
;     ...
;             PG8_WAIT_V(8); PG8_WAIT_L(0); PG8_BAR; PG8_MMA(0, 0, At, B0); PG8_MMA(0, 1, At, B1); PG8_BAR; PG8_SCHED;
	s_setprio 1
	s_barrier

	v_mfma_f32_16x16x32_bf16 v[124:127], v[144:147], v[192:195], v[124:127]
	v_mfma_f32_16x16x32_bf16 v[120:123], v[162:165], v[192:195], v[120:123]
	v_mfma_f32_16x16x32_bf16 v[108:111], v[144:147], v[200:203], v[108:111]
	v_mfma_f32_16x16x32_bf16 v[104:107], v[162:165], v[200:203], v[104:107]
	v_mfma_f32_16x16x32_bf16 v[92:95], v[144:147], v[208:211], v[92:95]
	v_mfma_f32_16x16x32_bf16 v[88:91], v[162:165], v[208:211], v[88:91]
	v_mfma_f32_16x16x32_bf16 v[76:79], v[144:147], v[216:219], v[76:79]
	v_mfma_f32_16x16x32_bf16 v[72:75], v[162:165], v[216:219], v[72:75]
	v_mfma_f32_16x16x32_bf16 v[124:127], v[148:151], v[196:199], v[124:127]
	v_mfma_f32_16x16x32_bf16 v[120:123], v[166:169], v[196:199], v[120:123]
	v_mfma_f32_16x16x32_bf16 v[108:111], v[148:151], v[204:207], v[108:111]
	v_mfma_f32_16x16x32_bf16 v[104:107], v[166:169], v[204:207], v[104:107]
	v_mfma_f32_16x16x32_bf16 v[92:95], v[148:151], v[212:215], v[92:95]
	v_mfma_f32_16x16x32_bf16 v[88:91], v[166:169], v[212:215], v[88:91]
	v_mfma_f32_16x16x32_bf16 v[76:79], v[148:151], v[220:223], v[76:79]
	v_mfma_f32_16x16x32_bf16 v[72:75], v[166:169], v[220:223], v[72:75]


; #define PG8_STAGE(bufoff, gbase, voff) do { _Pragma("unroll") for (int _i = 0; _i < 2; ++_i) \
;         __builtin_amdgcn_global_load_lds((const unsigned*)((const char*)(gbase) + (voff)[_i]), (LAS unsigned*)(lds + (bufoff) + ldsw + _i * 8192), 16, 0, 0); } while (0)
; #define PG8_LDA(dst, b, h) do { _Pragma("unroll") for (int m = 0; m < 4; ++m) _Pragma("unroll") for (int k = 0; k < 2; ++k) dst[m][k] = *(const LAS bf16x8*)(lds + PG8_SA(b, h) + aoff + m * 2048 + k * 1024); } while (0)
; template <class Epi>
; __device__ __forceinline__ void gemm_phase(LAS unsigned char* lds, const Gemm g, const StaticOrder& S, const Epi& E) {
;     ...
;             PG8_LDA(At, 0, 1); PG8_STAGE(PG8_SB(0, 0), b2, voffB); PG8_STAGE(PG8_SB(0, 1), b2 + hsB, voffB); PG8_STAGE(PG8_SA(0, 0), a2, voffA);
	v_mfma_f32_16x16x32_bf16 v[116:119], v[170:173], v[192:195], v[116:119]
	v_mfma_f32_16x16x32_bf16 v[112:115], v[184:187], v[192:195], v[112:115]
	v_mfma_f32_16x16x32_bf16 v[100:103], v[170:173], v[200:203], v[100:103]
	v_mfma_f32_16x16x32_bf16 v[96:99], v[184:187], v[200:203], v[96:99]
	v_mfma_f32_16x16x32_bf16 v[84:87], v[170:173], v[208:211], v[84:87]
	v_mfma_f32_16x16x32_bf16 v[80:83], v[184:187], v[208:211], v[80:83]
	v_mfma_f32_16x16x32_bf16 v[68:71], v[170:173], v[216:219], v[68:71]
	v_mfma_f32_16x16x32_bf16 v[64:67], v[184:187], v[216:219], v[64:67]
	v_mfma_f32_16x16x32_bf16 v[116:119], v[174:177], v[196:199], v[116:119]
	v_mfma_f32_16x16x32_bf16 v[112:115], v[188:191], v[196:199], v[112:115]
	v_mfma_f32_16x16x32_bf16 v[100:103], v[174:177], v[204:207], v[100:103]
	v_mfma_f32_16x16x32_bf16 v[96:99], v[188:191], v[204:207], v[96:99]
	v_mfma_f32_16x16x32_bf16 v[84:87], v[174:177], v[212:215], v[84:87]
	v_mfma_f32_16x16x32_bf16 v[80:83], v[188:191], v[212:215], v[80:83]
	v_mfma_f32_16x16x32_bf16 v[68:71], v[174:177], v[220:223], v[68:71]
	v_mfma_f32_16x16x32_bf16 v[64:67], v[188:191], v[220:223], v[64:67]
	s_barrier
	s_setprio 0
	s_add_i32 s39, s31, s4
	s_mov_b32 m0, s39
	ds_read_b128 v[192:195], v157 offset:16384
	ds_read_b128 v[196:199], v157 offset:17408
	ds_read_b128 v[200:203], v157 offset:18432
	ds_read_b128 v[204:207], v157 offset:19456
	ds_read_b128 v[208:211], v157 offset:20480
	ds_read_b128 v[212:215], v157 offset:21504
	ds_read_b128 v[216:219], v157 offset:22528
	ds_read_b128 v[220:223], v157 offset:23552
	global_load_lds_dwordx4 v130, s[50:51]
	s_add_i32 m0, s39, 0x2000
	s_add_u32 s54, s50, 0x40000
	s_addc_u32 s55, s51, 0
	s_add_i32 s39, s33, s4
	global_load_lds_dwordx4 v134, s[50:51]
	s_mov_b32 m0, s39
	s_nop 0
	global_load_lds_dwordx4 v130, s[54:55]
	s_add_i32 m0, s39, 0x2000
	s_nop 0
	global_load_lds_dwordx4 v134, s[54:55]
	s_mov_b32 m0, s5
	s_nop 0
	global_load_lds_dwordx4 v128, s[52:53]
	s_mov_b32 m0, s16
	s_nop 0
	global_load_lds_dwordx4 v132, s[52:53]
	s_waitcnt vmcnt(8) lgkmcnt(0)

; #define PG8_MMA(ai, bj, At, Bt) do { __builtin_amdgcn_s_setprio(1); _Pragma("unroll") for (int m = 0; m < 4; ++m) _Pragma("unroll") for (int n = 0; n < 2; ++n) _Pragma("unroll") for (int k = 0; k < 2; ++k) \
;         acc[ai][bj][m][n] = __builtin_amdgcn_mfma_f32_16x16x32_bf16(Bt[n][k], At[m][k], acc[ai][bj][m][n], 0, 0, 0); __builtin_amdgcn_s_setprio(0); } while (0)
; #define PG8_WAIT_V(n) asm volatile("s_waitcnt vmcnt(" #n ")" ::: "memory")
; #define PG8_WAIT_L(n) asm volatile("s_waitcnt lgkmcnt(" #n ")" ::: "memory")
; #define PG8_BAR __builtin_amdgcn_s_barrier()
; #define PG8_SCHED __builtin_amdgcn_sched_barrier(0)
; template <class Epi>
; __device__ __forceinline__ void gemm_phase(LAS unsigned char* lds, const Gemm g, const StaticOrder& S, const Epi& E) {
;     ...
;             PG8_WAIT_V(8); PG8_WAIT_L(0); PG8_BAR; PG8_MMA(1, 0, At, B0); PG8_MMA(1, 1, At, B1); PG8_BAR; PG8_SCHED;
	s_setprio 1
	s_barrier

	v_mfma_f32_16x16x32_bf16 v[60:63], v[144:147], v[192:195], v[60:63]
	v_mfma_f32_16x16x32_bf16 v[56:59], v[162:165], v[192:195], v[56:59]
	v_mfma_f32_16x16x32_bf16 v[44:47], v[144:147], v[200:203], v[44:47]
	v_mfma_f32_16x16x32_bf16 v[40:43], v[162:165], v[200:203], v[40:43]
	v_mfma_f32_16x16x32_bf16 v[28:31], v[144:147], v[208:211], v[28:31]
	v_mfma_f32_16x16x32_bf16 v[24:27], v[162:165], v[208:211], v[24:27]
	v_mfma_f32_16x16x32_bf16 v[12:15], v[144:147], v[216:219], v[12:15]
	v_mfma_f32_16x16x32_bf16 v[8:11], v[162:165], v[216:219], v[8:11]
	v_mfma_f32_16x16x32_bf16 v[60:63], v[148:151], v[196:199], v[60:63]
	v_mfma_f32_16x16x32_bf16 v[56:59], v[166:169], v[196:199], v[56:59]
	v_mfma_f32_16x16x32_bf16 v[44:47], v[148:151], v[204:207], v[44:47]
	v_mfma_f32_16x16x32_bf16 v[40:43], v[166:169], v[204:207], v[40:43]
	v_mfma_f32_16x16x32_bf16 v[28:31], v[148:151], v[212:215], v[28:31]
	v_mfma_f32_16x16x32_bf16 v[24:27], v[166:169], v[212:215], v[24:27]
	v_mfma_f32_16x16x32_bf16 v[12:15], v[148:151], v[220:223], v[12:15]
	v_mfma_f32_16x16x32_bf16 v[8:11], v[166:169], v[220:223], v[8:11]


; #define PG8_STAGE(bufoff, gbase, voff) do { _Pragma("unroll") for (int _i = 0; _i < 2; ++_i) \
;         __builtin_amdgcn_global_load_lds((const unsigned*)((const char*)(gbase) + (voff)[_i]), (LAS unsigned*)(lds + (bufoff) + ldsw + _i * 8192), 16, 0, 0); } while (0)
; #define PG8_LDA(dst, b, h) do { _Pragma("unroll") for (int m = 0; m < 4; ++m) _Pragma("unroll") for (int k = 0; k < 2; ++k) dst[m][k] = *(const LAS bf16x8*)(lds + PG8_SA(b, h) + aoff + m * 2048 + k * 1024); } while (0)
; #define PG8_LDB(dst, b, h) do { _Pragma("unroll") for (int n = 0; n < 2; ++n) _Pragma("unroll") for (int k = 0; k < 2; ++k) dst[n][k] = *(const LAS bf16x8*)(lds + PG8_SB(b, h) + boff + n * 2048 + k * 1024); } while (0)
; #define PG8_SCHED __builtin_amdgcn_sched_barrier(0)
; template <class Epi>
; __device__ __forceinline__ void gemm_phase(LAS unsigned char* lds, const Gemm g, const StaticOrder& S, const Epi& E) {
;     ...
;             PG8_LDB(B0, 1, 0); PG8_LDB(B1, 1, 1); PG8_SCHED; PG8_LDA(At, 1, 0); PG8_STAGE(PG8_SA(0, 1), a2 + hsA, voffA);
	v_mfma_f32_16x16x32_bf16 v[52:55], v[170:173], v[192:195], v[52:55]
	v_mfma_f32_16x16x32_bf16 v[48:51], v[184:187], v[192:195], v[48:51]
	v_mfma_f32_16x16x32_bf16 v[36:39], v[170:173], v[200:203], v[36:39]
	v_mfma_f32_16x16x32_bf16 v[32:35], v[184:187], v[200:203], v[32:35]
	v_mfma_f32_16x16x32_bf16 v[20:23], v[170:173], v[208:211], v[20:23]
	v_mfma_f32_16x16x32_bf16 v[16:19], v[184:187], v[208:211], v[16:19]
	v_mfma_f32_16x16x32_bf16 v[4:7], v[170:173], v[216:219], v[4:7]
	v_mfma_f32_16x16x32_bf16 v[0:3], v[184:187], v[216:219], v[0:3]
	v_mfma_f32_16x16x32_bf16 v[52:55], v[174:177], v[196:199], v[52:55]
	v_mfma_f32_16x16x32_bf16 v[48:51], v[188:191], v[196:199], v[48:51]
	v_mfma_f32_16x16x32_bf16 v[36:39], v[174:177], v[204:207], v[36:39]
	v_mfma_f32_16x16x32_bf16 v[32:35], v[188:191], v[204:207], v[32:35]
	v_mfma_f32_16x16x32_bf16 v[20:23], v[174:177], v[212:215], v[20:23]
	v_mfma_f32_16x16x32_bf16 v[16:19], v[188:191], v[212:215], v[16:19]
	v_mfma_f32_16x16x32_bf16 v[4:7], v[174:177], v[220:223], v[4:7]
	v_mfma_f32_16x16x32_bf16 v[0:3], v[188:191], v[220:223], v[0:3]
	s_barrier
	s_setprio 0
	s_add_i32 s39, 0, 0x18000
	v_add_u32_e32 v160, s39, v153
	s_add_i32 s41, 0, 0x1c000
	ds_read_b128 v[144:147], v160
	ds_read_b128 v[148:151], v160 offset:1024
	ds_read_b128 v[162:165], v160 offset:2048
	ds_read_b128 v[166:169], v160 offset:3072
	v_add_u32_e32 v160, s41, v153
	ds_read_b128 v[170:173], v160
	ds_read_b128 v[174:177], v160 offset:1024
	ds_read_b128 v[184:187], v160 offset:2048
	ds_read_b128 v[188:191], v160 offset:3072
	s_add_u32 s52, s52, 0x40000
	s_addc_u32 s53, s53, 0
	s_mov_b32 m0, s17
	ds_read_b128 v[192:195], v157 offset:32768
	ds_read_b128 v[196:199], v157 offset:33792
	ds_read_b128 v[200:203], v157 offset:34816
	ds_read_b128 v[204:207], v157 offset:35840
	ds_read_b128 v[208:211], v157 offset:36864
	ds_read_b128 v[212:215], v157 offset:37888
	ds_read_b128 v[216:219], v157 offset:38912
	ds_read_b128 v[220:223], v157 offset:39936
	global_load_lds_dwordx4 v128, s[52:53]
	s_mov_b32 m0, s18
	s_nop 0
	global_load_lds_dwordx4 v132, s[52:53]
	s_waitcnt vmcnt(8) lgkmcnt(0)

; #define PG8_MMA(ai, bj, At, Bt) do { __builtin_amdgcn_s_setprio(1); _Pragma("unroll") for (int m = 0; m < 4; ++m) _Pragma("unroll") for (int n = 0; n < 2; ++n) _Pragma("unroll") for (int k = 0; k < 2; ++k) \
;         acc[ai][bj][m][n] = __builtin_amdgcn_mfma_f32_16x16x32_bf16(Bt[n][k], At[m][k], acc[ai][bj][m][n], 0, 0, 0); __builtin_amdgcn_s_setprio(0); } while (0)
; #define PG8_WAIT_V(n) asm volatile("s_waitcnt vmcnt(" #n ")" ::: "memory")
; #define PG8_WAIT_L(n) asm volatile("s_waitcnt lgkmcnt(" #n ")" ::: "memory")
; #define PG8_BAR __builtin_amdgcn_s_barrier()
; #define PG8_SCHED __builtin_amdgcn_sched_barrier(0)
; template <class Epi>
; __device__ __forceinline__ void gemm_phase(LAS unsigned char* lds, const Gemm g, const StaticOrder& S, const Epi& E) {
;     ...
;             PG8_WAIT_V(8); PG8_WAIT_L(0); PG8_BAR; PG8_MMA(0, 0, At, B0); PG8_MMA(0, 1, At, B1); PG8_BAR; PG8_SCHED;
	s_setprio 1
	s_barrier

	v_mfma_f32_16x16x32_bf16 v[124:127], v[144:147], v[192:195], v[124:127]
	v_mfma_f32_16x16x32_bf16 v[120:123], v[162:165], v[192:195], v[120:123]
	v_mfma_f32_16x16x32_bf16 v[108:111], v[144:147], v[200:203], v[108:111]
	v_mfma_f32_16x16x32_bf16 v[104:107], v[162:165], v[200:203], v[104:107]
	v_mfma_f32_16x16x32_bf16 v[92:95], v[144:147], v[208:211], v[92:95]
	v_mfma_f32_16x16x32_bf16 v[88:91], v[162:165], v[208:211], v[88:91]
	v_mfma_f32_16x16x32_bf16 v[76:79], v[144:147], v[216:219], v[76:79]
	v_mfma_f32_16x16x32_bf16 v[72:75], v[162:165], v[216:219], v[72:75]
	v_mfma_f32_16x16x32_bf16 v[124:127], v[148:151], v[196:199], v[124:127]
	v_mfma_f32_16x16x32_bf16 v[120:123], v[166:169], v[196:199], v[120:123]
	v_mfma_f32_16x16x32_bf16 v[108:111], v[148:151], v[204:207], v[108:111]
	v_mfma_f32_16x16x32_bf16 v[104:107], v[166:169], v[204:207], v[104:107]
	v_mfma_f32_16x16x32_bf16 v[92:95], v[148:151], v[212:215], v[92:95]
	v_mfma_f32_16x16x32_bf16 v[88:91], v[166:169], v[212:215], v[88:91]
	v_mfma_f32_16x16x32_bf16 v[76:79], v[148:151], v[220:223], v[76:79]
	v_mfma_f32_16x16x32_bf16 v[72:75], v[166:169], v[220:223], v[72:75]


; #define PG8_STAGE(bufoff, gbase, voff) do { _Pragma("unroll") for (int _i = 0; _i < 2; ++_i) \
;         __builtin_amdgcn_global_load_lds((const unsigned*)((const char*)(gbase) + (voff)[_i]), (LAS unsigned*)(lds + (bufoff) + ldsw + _i * 8192), 16, 0, 0); } while (0)
; #define PG8_LDA(dst, b, h) do { _Pragma("unroll") for (int m = 0; m < 4; ++m) _Pragma("unroll") for (int k = 0; k < 2; ++k) dst[m][k] = *(const LAS bf16x8*)(lds + PG8_SA(b, h) + aoff + m * 2048 + k * 1024); } while (0)
; template <class Epi>
; __device__ __forceinline__ void gemm_phase(LAS unsigned char* lds, const Gemm g, const StaticOrder& S, const Epi& E) {
;     ...
;             PG8_LDA(At, 1, 1); PG8_STAGE(PG8_SB(1, 0), b3, voffB); PG8_STAGE(PG8_SB(1, 1), b3 + hsB, voffB); PG8_STAGE(PG8_SA(1, 0), a3, voffA);
	v_mfma_f32_16x16x32_bf16 v[116:119], v[170:173], v[192:195], v[116:119]
	v_mfma_f32_16x16x32_bf16 v[112:115], v[184:187], v[192:195], v[112:115]
	v_mfma_f32_16x16x32_bf16 v[100:103], v[170:173], v[200:203], v[100:103]
	v_mfma_f32_16x16x32_bf16 v[96:99], v[184:187], v[200:203], v[96:99]
	v_mfma_f32_16x16x32_bf16 v[84:87], v[170:173], v[208:211], v[84:87]
	v_mfma_f32_16x16x32_bf16 v[80:83], v[184:187], v[208:211], v[80:83]
	v_mfma_f32_16x16x32_bf16 v[68:71], v[170:173], v[216:219], v[68:71]
	v_mfma_f32_16x16x32_bf16 v[64:67], v[184:187], v[216:219], v[64:67]
	v_mfma_f32_16x16x32_bf16 v[116:119], v[174:177], v[196:199], v[116:119]
	v_mfma_f32_16x16x32_bf16 v[112:115], v[188:191], v[196:199], v[112:115]
	v_mfma_f32_16x16x32_bf16 v[100:103], v[174:177], v[204:207], v[100:103]
	v_mfma_f32_16x16x32_bf16 v[96:99], v[188:191], v[204:207], v[96:99]
	v_mfma_f32_16x16x32_bf16 v[84:87], v[174:177], v[212:215], v[84:87]
	v_mfma_f32_16x16x32_bf16 v[80:83], v[188:191], v[212:215], v[80:83]
	v_mfma_f32_16x16x32_bf16 v[68:71], v[174:177], v[220:223], v[68:71]
	v_mfma_f32_16x16x32_bf16 v[64:67], v[188:191], v[220:223], v[64:67]
	s_barrier
	s_setprio 0
	s_add_u32 s98, s50, 0x80
	s_addc_u32 s99, s51, 0
	s_add_u32 s100, s52, 0xfffc0080
	s_addc_u32 s101, s53, -1
	s_add_i32 s39, s39, s4
	s_mov_b32 m0, s39
	ds_read_b128 v[192:195], v157 offset:49152
	ds_read_b128 v[196:199], v157 offset:50176
	ds_read_b128 v[200:203], v157 offset:51200
	ds_read_b128 v[204:207], v157 offset:52224
	ds_read_b128 v[208:211], v157 offset:53248
	ds_read_b128 v[212:215], v157 offset:54272
	ds_read_b128 v[216:219], v157 offset:55296
	ds_read_b128 v[220:223], v157 offset:56320
	global_load_lds_dwordx4 v130, s[98:99]
	s_add_i32 m0, s39, 0x2000
	s_add_u32 s50, s50, 0x40080
	s_addc_u32 s51, s51, 0
	s_add_i32 s39, s41, s4
	global_load_lds_dwordx4 v134, s[98:99]
	s_mov_b32 m0, s39
	s_nop 0
	global_load_lds_dwordx4 v130, s[50:51]
	s_add_i32 m0, s39, 0x2000
	s_nop 0
	global_load_lds_dwordx4 v134, s[50:51]
	s_mov_b32 m0, s22
	s_nop 0
	global_load_lds_dwordx4 v128, s[100:101]
	s_mov_b32 m0, s23
	s_nop 0
	global_load_lds_dwordx4 v132, s[100:101]
	s_waitcnt vmcnt(8) lgkmcnt(0)

; #define PG8_MMA(ai, bj, At, Bt) do { __builtin_amdgcn_s_setprio(1); _Pragma("unroll") for (int m = 0; m < 4; ++m) _Pragma("unroll") for (int n = 0; n < 2; ++n) _Pragma("unroll") for (int k = 0; k < 2; ++k) \
;         acc[ai][bj][m][n] = __builtin_amdgcn_mfma_f32_16x16x32_bf16(Bt[n][k], At[m][k], acc[ai][bj][m][n], 0, 0, 0); __builtin_amdgcn_s_setprio(0); } while (0)
; #define PG8_WAIT_V(n) asm volatile("s_waitcnt vmcnt(" #n ")" ::: "memory")
; #define PG8_WAIT_L(n) asm volatile("s_waitcnt lgkmcnt(" #n ")" ::: "memory")
; #define PG8_BAR __builtin_amdgcn_s_barrier()
; #define PG8_SCHED __builtin_amdgcn_sched_barrier(0)
; template <class Epi>
; __device__ __forceinline__ void gemm_phase(LAS unsigned char* lds, const Gemm g, const StaticOrder& S, const Epi& E) {
;     ...
;             PG8_WAIT_V(8); PG8_WAIT_L(0); PG8_BAR; PG8_MMA(1, 0, At, B0); PG8_MMA(1, 1, At, B1); PG8_BAR; PG8_SCHED;
	s_setprio 1
	s_barrier

	v_mfma_f32_16x16x32_bf16 v[60:63], v[144:147], v[192:195], v[60:63]
	v_mfma_f32_16x16x32_bf16 v[56:59], v[162:165], v[192:195], v[56:59]
	v_mfma_f32_16x16x32_bf16 v[44:47], v[144:147], v[200:203], v[44:47]
	v_mfma_f32_16x16x32_bf16 v[40:43], v[162:165], v[200:203], v[40:43]
	v_mfma_f32_16x16x32_bf16 v[28:31], v[144:147], v[208:211], v[28:31]
	v_mfma_f32_16x16x32_bf16 v[24:27], v[162:165], v[208:211], v[24:27]
	v_mfma_f32_16x16x32_bf16 v[12:15], v[144:147], v[216:219], v[12:15]
	v_mfma_f32_16x16x32_bf16 v[8:11], v[162:165], v[216:219], v[8:11]
	v_mfma_f32_16x16x32_bf16 v[60:63], v[148:151], v[196:199], v[60:63]
	v_mfma_f32_16x16x32_bf16 v[56:59], v[166:169], v[196:199], v[56:59]
	v_mfma_f32_16x16x32_bf16 v[44:47], v[148:151], v[204:207], v[44:47]
	v_mfma_f32_16x16x32_bf16 v[40:43], v[166:169], v[204:207], v[40:43]
	v_mfma_f32_16x16x32_bf16 v[28:31], v[148:151], v[212:215], v[28:31]
	v_mfma_f32_16x16x32_bf16 v[24:27], v[166:169], v[212:215], v[24:27]
	v_mfma_f32_16x16x32_bf16 v[12:15], v[148:151], v[220:223], v[12:15]
	v_mfma_f32_16x16x32_bf16 v[8:11], v[166:169], v[220:223], v[8:11]


; #define PG8_BAR __builtin_amdgcn_s_barrier()
; template <class Epi>
; __device__ __forceinline__ void gemm_phase(LAS unsigned char* lds, const Gemm g, const StaticOrder& S, const Epi& E) {
;     ...
;         for (int t = 0; t < nt; t += 2) {
;     ...
;         if (wr == 0) PG8_BAR;
	v_mfma_f32_16x16x32_bf16 v[52:55], v[170:173], v[192:195], v[52:55]
	v_mfma_f32_16x16x32_bf16 v[48:51], v[184:187], v[192:195], v[48:51]
	v_mfma_f32_16x16x32_bf16 v[36:39], v[170:173], v[200:203], v[36:39]
	v_mfma_f32_16x16x32_bf16 v[32:35], v[184:187], v[200:203], v[32:35]
	v_mfma_f32_16x16x32_bf16 v[20:23], v[170:173], v[208:211], v[20:23]
	v_mfma_f32_16x16x32_bf16 v[16:19], v[184:187], v[208:211], v[16:19]
	v_mfma_f32_16x16x32_bf16 v[4:7], v[170:173], v[216:219], v[4:7]
	v_mfma_f32_16x16x32_bf16 v[0:3], v[184:187], v[216:219], v[0:3]
	v_mfma_f32_16x16x32_bf16 v[52:55], v[174:177], v[196:199], v[52:55]
	v_mfma_f32_16x16x32_bf16 v[48:51], v[188:191], v[196:199], v[48:51]
	v_mfma_f32_16x16x32_bf16 v[36:39], v[174:177], v[204:207], v[36:39]
	v_mfma_f32_16x16x32_bf16 v[32:35], v[188:191], v[204:207], v[32:35]
	v_mfma_f32_16x16x32_bf16 v[20:23], v[174:177], v[212:215], v[20:23]
	v_mfma_f32_16x16x32_bf16 v[16:19], v[188:191], v[212:215], v[16:19]
	v_mfma_f32_16x16x32_bf16 v[4:7], v[174:177], v[220:223], v[4:7]
	v_mfma_f32_16x16x32_bf16 v[0:3], v[188:191], v[220:223], v[0:3]
	s_barrier
	s_setprio 0
	s_add_i32 s35, s35, 2
	s_add_u32 s48, s48, 0x100
	s_addc_u32 s49, s49, 0
	s_add_u32 s13, s13, 0x100
	s_addc_u32 s34, s34, 0
	s_cmp_gt_u32 s35, 13
	s_cbranch_scc0 .LBB0_1234
	s_and_b64 vcc, exec, s[26:27]
	s_cbranch_vccz .LBB0_1237
	s_barrier

; #define PG8_STAGE(bufoff, gbase, voff) do { _Pragma("unroll") for (int _i = 0; _i < 2; ++_i) \
;         __builtin_amdgcn_global_load_lds((const unsigned*)((const char*)(gbase) + (voff)[_i]), (LAS unsigned*)(lds + (bufoff) + ldsw + _i * 8192), 16, 0, 0); } while (0)
; #define PG8_LDA(dst, b, h) do { _Pragma("unroll") for (int m = 0; m < 4; ++m) _Pragma("unroll") for (int k = 0; k < 2; ++k) dst[m][k] = *(const LAS bf16x8*)(lds + PG8_SA(b, h) + aoff + m * 2048 + k * 1024); } while (0)
; #define PG8_LDB(dst, b, h) do { _Pragma("unroll") for (int n = 0; n < 2; ++n) _Pragma("unroll") for (int k = 0; k < 2; ++k) dst[n][k] = *(const LAS bf16x8*)(lds + PG8_SB(b, h) + boff + n * 2048 + k * 1024); } while (0)
; #define PG8_SCHED __builtin_amdgcn_sched_barrier(0)
; template <class Epi>
; __device__ __forceinline__ void gemm_phase(LAS unsigned char* lds, const Gemm g, const StaticOrder& S, const Epi& E) {
;     ...
;             const bool last = (t == nt - 2);
;             if constexpr (Epi::HAS_MID) { if (t == nt1) E.mid(acc, cur, wr, wc, fr, fq); }
;             const char* a1 = cA + ((Epi::HAS_MID && t >= nt1) ? dA2 : 0) + (size_t)(t + 1) * kstep;
;             const char* a2 = last ? nA : cA + ((Epi::HAS_MID && t + 2 >= nt1) ? dA2 : 0) + (size_t)(t + 2) * kstep; const char* b2 = last ? nB : cB + ((Epi::HAS_MID && t + 2 >= nt1) ? dB2 : 0) + (size_t)(t + 2) * kstep;
;             const char* a3 = a2 + kstep; const char* b3 = b2 + kstep;
;             PG8_LDB(B0, 0, 0); PG8_LDB(B1, 0, 1); PG8_SCHED; PG8_LDA(At, 0, 0); PG8_STAGE(PG8_SA(1, 1), a1 + hsA, voffA);
.LBB0_1350:
	ds_read_b128 v[144:147], v155
	ds_read_b128 v[148:151], v155 offset:1024
	ds_read_b128 v[162:165], v155 offset:2048
	ds_read_b128 v[166:169], v155 offset:3072
	ds_read_b128 v[170:173], v156
	ds_read_b128 v[174:177], v156 offset:1024
	ds_read_b128 v[184:187], v156 offset:2048
	ds_read_b128 v[188:191], v156 offset:3072
	s_add_u32 s40, s38, 0xfffc0080
	s_addc_u32 s41, s39, -1
	s_cmp_eq_u32 s48, 12
	s_cselect_b32 s43, s25, s41
	s_cselect_b32 s42, s44, s40
	s_cselect_b32 s41, s15, s47
	s_cselect_b32 s40, s45, s46
	s_add_i32 m0, s17, 0xc000
	ds_read_b128 v[192:195], v157
	ds_read_b128 v[196:199], v157 offset:1024
	ds_read_b128 v[200:203], v157 offset:2048
	ds_read_b128 v[204:207], v157 offset:3072
	ds_read_b128 v[208:211], v157 offset:4096
	ds_read_b128 v[212:215], v157 offset:5120
	ds_read_b128 v[216:219], v157 offset:6144
	ds_read_b128 v[220:223], v157 offset:7168
	global_load_lds_dwordx4 v136, s[38:39]
	s_add_i32 m0, s17, 0xe000
	s_nop 0
	global_load_lds_dwordx4 v138, s[38:39]
	s_waitcnt vmcnt(8) lgkmcnt(0)

; #define PG8_MMA(ai, bj, At, Bt) do { __builtin_amdgcn_s_setprio(1); _Pragma("unroll") for (int m = 0; m < 4; ++m) _Pragma("unroll") for (int n = 0; n < 2; ++n) _Pragma("unroll") for (int k = 0; k < 2; ++k) \
;         acc[ai][bj][m][n] = __builtin_amdgcn_mfma_f32_16x16x32_bf16(Bt[n][k], At[m][k], acc[ai][bj][m][n], 0, 0, 0); __builtin_amdgcn_s_setprio(0); } while (0)
; #define PG8_WAIT_V(n) asm volatile("s_waitcnt vmcnt(" #n ")" ::: "memory")
; #define PG8_WAIT_L(n) asm volatile("s_waitcnt lgkmcnt(" #n ")" ::: "memory")
; #define PG8_BAR __builtin_amdgcn_s_barrier()
; #define PG8_SCHED __builtin_amdgcn_sched_barrier(0)
; template <class Epi>
; __device__ __forceinline__ void gemm_phase(LAS unsigned char* lds, const Gemm g, const StaticOrder& S, const Epi& E) {
;     ...
;             PG8_WAIT_V(8); PG8_WAIT_L(0); PG8_BAR; PG8_MMA(0, 0, At, B0); PG8_MMA(0, 1, At, B1); PG8_BAR; PG8_SCHED;
	s_setprio 1
	s_barrier

	v_mfma_f32_16x16x32_bf16 v[124:127], v[144:147], v[192:195], v[124:127]
	v_mfma_f32_16x16x32_bf16 v[120:123], v[162:165], v[192:195], v[120:123]
	v_mfma_f32_16x16x32_bf16 v[108:111], v[144:147], v[200:203], v[108:111]
	v_mfma_f32_16x16x32_bf16 v[104:107], v[162:165], v[200:203], v[104:107]
	v_mfma_f32_16x16x32_bf16 v[92:95], v[144:147], v[208:211], v[92:95]
	v_mfma_f32_16x16x32_bf16 v[88:91], v[162:165], v[208:211], v[88:91]
	v_mfma_f32_16x16x32_bf16 v[76:79], v[144:147], v[216:219], v[76:79]
	v_mfma_f32_16x16x32_bf16 v[72:75], v[162:165], v[216:219], v[72:75]
	v_mfma_f32_16x16x32_bf16 v[124:127], v[148:151], v[196:199], v[124:127]
	v_mfma_f32_16x16x32_bf16 v[120:123], v[166:169], v[196:199], v[120:123]
	v_mfma_f32_16x16x32_bf16 v[108:111], v[148:151], v[204:207], v[108:111]
	v_mfma_f32_16x16x32_bf16 v[104:107], v[166:169], v[204:207], v[104:107]
	v_mfma_f32_16x16x32_bf16 v[92:95], v[148:151], v[212:215], v[92:95]
	v_mfma_f32_16x16x32_bf16 v[88:91], v[166:169], v[212:215], v[88:91]
	v_mfma_f32_16x16x32_bf16 v[76:79], v[148:151], v[220:223], v[76:79]
	v_mfma_f32_16x16x32_bf16 v[72:75], v[166:169], v[220:223], v[72:75]


; #define PG8_STAGE(bufoff, gbase, voff) do { _Pragma("unroll") for (int _i = 0; _i < 2; ++_i) \
;         __builtin_amdgcn_global_load_lds((const unsigned*)((const char*)(gbase) + (voff)[_i]), (LAS unsigned*)(lds + (bufoff) + ldsw + _i * 8192), 16, 0, 0); } while (0)
; #define PG8_LDA(dst, b, h) do { _Pragma("unroll") for (int m = 0; m < 4; ++m) _Pragma("unroll") for (int k = 0; k < 2; ++k) dst[m][k] = *(const LAS bf16x8*)(lds + PG8_SA(b, h) + aoff + m * 2048 + k * 1024); } while (0)
; template <class Epi>
; __device__ __forceinline__ void gemm_phase(LAS unsigned char* lds, const Gemm g, const StaticOrder& S, const Epi& E) {
;     ...
;             PG8_LDA(At, 0, 1); PG8_STAGE(PG8_SB(0, 0), b2, voffB); PG8_STAGE(PG8_SB(0, 1), b2 + hsB, voffB); PG8_STAGE(PG8_SA(0, 0), a2, voffA);
	v_mfma_f32_16x16x32_bf16 v[116:119], v[170:173], v[192:195], v[116:119]
	v_mfma_f32_16x16x32_bf16 v[112:115], v[184:187], v[192:195], v[112:115]
	v_mfma_f32_16x16x32_bf16 v[100:103], v[170:173], v[200:203], v[100:103]
	v_mfma_f32_16x16x32_bf16 v[96:99], v[184:187], v[200:203], v[96:99]
	v_mfma_f32_16x16x32_bf16 v[84:87], v[170:173], v[208:211], v[84:87]
	v_mfma_f32_16x16x32_bf16 v[80:83], v[184:187], v[208:211], v[80:83]
	v_mfma_f32_16x16x32_bf16 v[68:71], v[170:173], v[216:219], v[68:71]
	v_mfma_f32_16x16x32_bf16 v[64:67], v[184:187], v[216:219], v[64:67]
	v_mfma_f32_16x16x32_bf16 v[116:119], v[174:177], v[196:199], v[116:119]
	v_mfma_f32_16x16x32_bf16 v[112:115], v[188:191], v[196:199], v[112:115]
	v_mfma_f32_16x16x32_bf16 v[100:103], v[174:177], v[204:207], v[100:103]
	v_mfma_f32_16x16x32_bf16 v[96:99], v[188:191], v[204:207], v[96:99]
	v_mfma_f32_16x16x32_bf16 v[84:87], v[174:177], v[212:215], v[84:87]
	v_mfma_f32_16x16x32_bf16 v[80:83], v[188:191], v[212:215], v[80:83]
	v_mfma_f32_16x16x32_bf16 v[68:71], v[174:177], v[220:223], v[68:71]
	v_mfma_f32_16x16x32_bf16 v[64:67], v[188:191], v[220:223], v[64:67]
	s_barrier
	s_setprio 0
	s_add_i32 s49, s30, s4
	s_mov_b32 m0, s49
	ds_read_b128 v[192:195], v157 offset:16384
	ds_read_b128 v[196:199], v157 offset:17408
	ds_read_b128 v[200:203], v157 offset:18432
	ds_read_b128 v[204:207], v157 offset:19456
	ds_read_b128 v[208:211], v157 offset:20480
	ds_read_b128 v[212:215], v157 offset:21504
	ds_read_b128 v[216:219], v157 offset:22528
	ds_read_b128 v[220:223], v157 offset:23552
	global_load_lds_dwordx4 v132, s[40:41]
	s_add_i32 m0, s49, 0x2000
	s_add_u32 s50, s40, 0x40000
	s_addc_u32 s51, s41, 0
	s_add_i32 s49, s31, s4
	global_load_lds_dwordx4 v128, s[40:41]
	s_mov_b32 m0, s49
	s_nop 0
	global_load_lds_dwordx4 v132, s[50:51]
	s_add_i32 m0, s49, 0x2000
	s_nop 0
	global_load_lds_dwordx4 v128, s[50:51]
	s_mov_b32 m0, s17
	s_nop 0
	global_load_lds_dwordx4 v134, s[42:43]
	s_mov_b32 m0, s18
	s_nop 0
	global_load_lds_dwordx4 v130, s[42:43]
	s_waitcnt vmcnt(8) lgkmcnt(0)

; #define PG8_MMA(ai, bj, At, Bt) do { __builtin_amdgcn_s_setprio(1); _Pragma("unroll") for (int m = 0; m < 4; ++m) _Pragma("unroll") for (int n = 0; n < 2; ++n) _Pragma("unroll") for (int k = 0; k < 2; ++k) \
;         acc[ai][bj][m][n] = __builtin_amdgcn_mfma_f32_16x16x32_bf16(Bt[n][k], At[m][k], acc[ai][bj][m][n], 0, 0, 0); __builtin_amdgcn_s_setprio(0); } while (0)
; #define PG8_WAIT_V(n) asm volatile("s_waitcnt vmcnt(" #n ")" ::: "memory")
; #define PG8_WAIT_L(n) asm volatile("s_waitcnt lgkmcnt(" #n ")" ::: "memory")
; #define PG8_BAR __builtin_amdgcn_s_barrier()
; #define PG8_SCHED __builtin_amdgcn_sched_barrier(0)
; template <class Epi>
; __device__ __forceinline__ void gemm_phase(LAS unsigned char* lds, const Gemm g, const StaticOrder& S, const Epi& E) {
;     ...
;             PG8_WAIT_V(8); PG8_WAIT_L(0); PG8_BAR; PG8_MMA(1, 0, At, B0); PG8_MMA(1, 1, At, B1); PG8_BAR; PG8_SCHED;
	s_setprio 1
	s_barrier

	v_mfma_f32_16x16x32_bf16 v[60:63], v[144:147], v[192:195], v[60:63]
	v_mfma_f32_16x16x32_bf16 v[56:59], v[162:165], v[192:195], v[56:59]
	v_mfma_f32_16x16x32_bf16 v[44:47], v[144:147], v[200:203], v[44:47]
	v_mfma_f32_16x16x32_bf16 v[40:43], v[162:165], v[200:203], v[40:43]
	v_mfma_f32_16x16x32_bf16 v[28:31], v[144:147], v[208:211], v[28:31]
	v_mfma_f32_16x16x32_bf16 v[24:27], v[162:165], v[208:211], v[24:27]
	v_mfma_f32_16x16x32_bf16 v[12:15], v[144:147], v[216:219], v[12:15]
	v_mfma_f32_16x16x32_bf16 v[8:11], v[162:165], v[216:219], v[8:11]
	v_mfma_f32_16x16x32_bf16 v[60:63], v[148:151], v[196:199], v[60:63]
	v_mfma_f32_16x16x32_bf16 v[56:59], v[166:169], v[196:199], v[56:59]
	v_mfma_f32_16x16x32_bf16 v[44:47], v[148:151], v[204:207], v[44:47]
	v_mfma_f32_16x16x32_bf16 v[40:43], v[166:169], v[204:207], v[40:43]
	v_mfma_f32_16x16x32_bf16 v[28:31], v[148:151], v[212:215], v[28:31]
	v_mfma_f32_16x16x32_bf16 v[24:27], v[166:169], v[212:215], v[24:27]
	v_mfma_f32_16x16x32_bf16 v[12:15], v[148:151], v[220:223], v[12:15]
	v_mfma_f32_16x16x32_bf16 v[8:11], v[166:169], v[220:223], v[8:11]


; #define PG8_STAGE(bufoff, gbase, voff) do { _Pragma("unroll") for (int _i = 0; _i < 2; ++_i) \
;         __builtin_amdgcn_global_load_lds((const unsigned*)((const char*)(gbase) + (voff)[_i]), (LAS unsigned*)(lds + (bufoff) + ldsw + _i * 8192), 16, 0, 0); } while (0)
; #define PG8_LDA(dst, b, h) do { _Pragma("unroll") for (int m = 0; m < 4; ++m) _Pragma("unroll") for (int k = 0; k < 2; ++k) dst[m][k] = *(const LAS bf16x8*)(lds + PG8_SA(b, h) + aoff + m * 2048 + k * 1024); } while (0)
; #define PG8_LDB(dst, b, h) do { _Pragma("unroll") for (int n = 0; n < 2; ++n) _Pragma("unroll") for (int k = 0; k < 2; ++k) dst[n][k] = *(const LAS bf16x8*)(lds + PG8_SB(b, h) + boff + n * 2048 + k * 1024); } while (0)
; #define PG8_SCHED __builtin_amdgcn_sched_barrier(0)
; template <class Epi>
; __device__ __forceinline__ void gemm_phase(LAS unsigned char* lds, const Gemm g, const StaticOrder& S, const Epi& E) {
;     ...
;             PG8_LDB(B0, 1, 0); PG8_LDB(B1, 1, 1); PG8_SCHED; PG8_LDA(At, 1, 0); PG8_STAGE(PG8_SA(0, 1), a2 + hsA, voffA);
	v_mfma_f32_16x16x32_bf16 v[52:55], v[170:173], v[192:195], v[52:55]
	v_mfma_f32_16x16x32_bf16 v[48:51], v[184:187], v[192:195], v[48:51]
	v_mfma_f32_16x16x32_bf16 v[36:39], v[170:173], v[200:203], v[36:39]
	v_mfma_f32_16x16x32_bf16 v[32:35], v[184:187], v[200:203], v[32:35]
	v_mfma_f32_16x16x32_bf16 v[20:23], v[170:173], v[208:211], v[20:23]
	v_mfma_f32_16x16x32_bf16 v[16:19], v[184:187], v[208:211], v[16:19]
	v_mfma_f32_16x16x32_bf16 v[4:7], v[170:173], v[216:219], v[4:7]
	v_mfma_f32_16x16x32_bf16 v[0:3], v[184:187], v[216:219], v[0:3]
	v_mfma_f32_16x16x32_bf16 v[52:55], v[174:177], v[196:199], v[52:55]
	v_mfma_f32_16x16x32_bf16 v[48:51], v[188:191], v[196:199], v[48:51]
	v_mfma_f32_16x16x32_bf16 v[36:39], v[174:177], v[204:207], v[36:39]
	v_mfma_f32_16x16x32_bf16 v[32:35], v[188:191], v[204:207], v[32:35]
	v_mfma_f32_16x16x32_bf16 v[20:23], v[174:177], v[212:215], v[20:23]
	v_mfma_f32_16x16x32_bf16 v[16:19], v[188:191], v[212:215], v[16:19]
	v_mfma_f32_16x16x32_bf16 v[4:7], v[174:177], v[220:223], v[4:7]
	v_mfma_f32_16x16x32_bf16 v[0:3], v[188:191], v[220:223], v[0:3]
	s_barrier
	s_setprio 0
	s_add_i32 s49, 0, 0x18000
	v_add_u32_e32 v159, s49, v153
	s_add_i32 s50, 0, 0x1c000
	ds_read_b128 v[144:147], v159
	ds_read_b128 v[148:151], v159 offset:1024
	ds_read_b128 v[162:165], v159 offset:2048
	ds_read_b128 v[166:169], v159 offset:3072
	v_add_u32_e32 v159, s50, v153
	ds_read_b128 v[170:173], v159
	ds_read_b128 v[174:177], v159 offset:1024
	ds_read_b128 v[184:187], v159 offset:2048
	ds_read_b128 v[188:191], v159 offset:3072
	s_add_u32 s42, s42, 0x40000
	s_addc_u32 s43, s43, 0
	s_mov_b32 m0, s19
	ds_read_b128 v[192:195], v157 offset:32768
	ds_read_b128 v[196:199], v157 offset:33792
	ds_read_b128 v[200:203], v157 offset:34816
	ds_read_b128 v[204:207], v157 offset:35840
	ds_read_b128 v[208:211], v157 offset:36864
	ds_read_b128 v[212:215], v157 offset:37888
	ds_read_b128 v[216:219], v157 offset:38912
	ds_read_b128 v[220:223], v157 offset:39936
	global_load_lds_dwordx4 v134, s[42:43]
	s_mov_b32 m0, s22
	s_nop 0
	global_load_lds_dwordx4 v130, s[42:43]
	s_waitcnt vmcnt(8) lgkmcnt(0)

; #define PG8_MMA(ai, bj, At, Bt) do { __builtin_amdgcn_s_setprio(1); _Pragma("unroll") for (int m = 0; m < 4; ++m) _Pragma("unroll") for (int n = 0; n < 2; ++n) _Pragma("unroll") for (int k = 0; k < 2; ++k) \
;         acc[ai][bj][m][n] = __builtin_amdgcn_mfma_f32_16x16x32_bf16(Bt[n][k], At[m][k], acc[ai][bj][m][n], 0, 0, 0); __builtin_amdgcn_s_setprio(0); } while (0)
; #define PG8_WAIT_V(n) asm volatile("s_waitcnt vmcnt(" #n ")" ::: "memory")
; #define PG8_WAIT_L(n) asm volatile("s_waitcnt lgkmcnt(" #n ")" ::: "memory")
; #define PG8_BAR __builtin_amdgcn_s_barrier()
; #define PG8_SCHED __builtin_amdgcn_sched_barrier(0)
; template <class Epi>
; __device__ __forceinline__ void gemm_phase(LAS unsigned char* lds, const Gemm g, const StaticOrder& S, const Epi& E) {
;     ...
;             PG8_WAIT_V(8); PG8_WAIT_L(0); PG8_BAR; PG8_MMA(0, 0, At, B0); PG8_MMA(0, 1, At, B1); PG8_BAR; PG8_SCHED;
	s_setprio 1
	s_barrier

	v_mfma_f32_16x16x32_bf16 v[124:127], v[144:147], v[192:195], v[124:127]
	v_mfma_f32_16x16x32_bf16 v[120:123], v[162:165], v[192:195], v[120:123]
	v_mfma_f32_16x16x32_bf16 v[108:111], v[144:147], v[200:203], v[108:111]
	v_mfma_f32_16x16x32_bf16 v[104:107], v[162:165], v[200:203], v[104:107]
	v_mfma_f32_16x16x32_bf16 v[92:95], v[144:147], v[208:211], v[92:95]
	v_mfma_f32_16x16x32_bf16 v[88:91], v[162:165], v[208:211], v[88:91]
	v_mfma_f32_16x16x32_bf16 v[76:79], v[144:147], v[216:219], v[76:79]
	v_mfma_f32_16x16x32_bf16 v[72:75], v[162:165], v[216:219], v[72:75]
	v_mfma_f32_16x16x32_bf16 v[124:127], v[148:151], v[196:199], v[124:127]
	v_mfma_f32_16x16x32_bf16 v[120:123], v[166:169], v[196:199], v[120:123]
	v_mfma_f32_16x16x32_bf16 v[108:111], v[148:151], v[204:207], v[108:111]
	v_mfma_f32_16x16x32_bf16 v[104:107], v[166:169], v[204:207], v[104:107]
	v_mfma_f32_16x16x32_bf16 v[92:95], v[148:151], v[212:215], v[92:95]
	v_mfma_f32_16x16x32_bf16 v[88:91], v[166:169], v[212:215], v[88:91]
	v_mfma_f32_16x16x32_bf16 v[76:79], v[148:151], v[220:223], v[76:79]
	v_mfma_f32_16x16x32_bf16 v[72:75], v[166:169], v[220:223], v[72:75]


; #define PG8_STAGE(bufoff, gbase, voff) do { _Pragma("unroll") for (int _i = 0; _i < 2; ++_i) \
;         __builtin_amdgcn_global_load_lds((const unsigned*)((const char*)(gbase) + (voff)[_i]), (LAS unsigned*)(lds + (bufoff) + ldsw + _i * 8192), 16, 0, 0); } while (0)
; #define PG8_LDA(dst, b, h) do { _Pragma("unroll") for (int m = 0; m < 4; ++m) _Pragma("unroll") for (int k = 0; k < 2; ++k) dst[m][k] = *(const LAS bf16x8*)(lds + PG8_SA(b, h) + aoff + m * 2048 + k * 1024); } while (0)
; template <class Epi>
; __device__ __forceinline__ void gemm_phase(LAS unsigned char* lds, const Gemm g, const StaticOrder& S, const Epi& E) {
;     ...
;             PG8_LDA(At, 1, 1); PG8_STAGE(PG8_SB(1, 0), b3, voffB); PG8_STAGE(PG8_SB(1, 1), b3 + hsB, voffB); PG8_STAGE(PG8_SA(1, 0), a3, voffA);
	v_mfma_f32_16x16x32_bf16 v[116:119], v[170:173], v[192:195], v[116:119]
	v_mfma_f32_16x16x32_bf16 v[112:115], v[184:187], v[192:195], v[112:115]
	v_mfma_f32_16x16x32_bf16 v[100:103], v[170:173], v[200:203], v[100:103]
	v_mfma_f32_16x16x32_bf16 v[96:99], v[184:187], v[200:203], v[96:99]
	v_mfma_f32_16x16x32_bf16 v[84:87], v[170:173], v[208:211], v[84:87]
	v_mfma_f32_16x16x32_bf16 v[80:83], v[184:187], v[208:211], v[80:83]
	v_mfma_f32_16x16x32_bf16 v[68:71], v[170:173], v[216:219], v[68:71]
	v_mfma_f32_16x16x32_bf16 v[64:67], v[184:187], v[216:219], v[64:67]
	v_mfma_f32_16x16x32_bf16 v[116:119], v[174:177], v[196:199], v[116:119]
	v_mfma_f32_16x16x32_bf16 v[112:115], v[188:191], v[196:199], v[112:115]
	v_mfma_f32_16x16x32_bf16 v[100:103], v[174:177], v[204:207], v[100:103]
	v_mfma_f32_16x16x32_bf16 v[96:99], v[188:191], v[204:207], v[96:99]
	v_mfma_f32_16x16x32_bf16 v[84:87], v[174:177], v[212:215], v[84:87]
	v_mfma_f32_16x16x32_bf16 v[80:83], v[188:191], v[212:215], v[80:83]
	v_mfma_f32_16x16x32_bf16 v[68:71], v[174:177], v[220:223], v[68:71]
	v_mfma_f32_16x16x32_bf16 v[64:67], v[188:191], v[220:223], v[64:67]
	s_barrier
	s_setprio 0
	s_add_u32 s98, s40, 0x80
	s_addc_u32 s99, s41, 0
	s_add_u32 s100, s42, 0xfffc0080
	s_addc_u32 s101, s43, -1
	s_add_i32 s42, s49, s4
	s_mov_b32 m0, s42
	ds_read_b128 v[192:195], v157 offset:49152
	ds_read_b128 v[196:199], v157 offset:50176
	ds_read_b128 v[200:203], v157 offset:51200
	ds_read_b128 v[204:207], v157 offset:52224
	ds_read_b128 v[208:211], v157 offset:53248
	ds_read_b128 v[212:215], v157 offset:54272
	ds_read_b128 v[216:219], v157 offset:55296
	ds_read_b128 v[220:223], v157 offset:56320
	global_load_lds_dwordx4 v132, s[98:99]
	s_add_i32 m0, s42, 0x2000
	s_add_u32 s40, s40, 0x40080
	s_addc_u32 s41, s41, 0
	s_add_i32 s42, s50, s4
	global_load_lds_dwordx4 v128, s[98:99]
	s_mov_b32 m0, s42
	s_nop 0
	global_load_lds_dwordx4 v132, s[40:41]
	s_add_i32 m0, s42, 0x2000
	s_nop 0
	global_load_lds_dwordx4 v128, s[40:41]
	s_mov_b32 m0, s0
	s_nop 0
	global_load_lds_dwordx4 v134, s[100:101]
	s_mov_b32 m0, s1
	s_nop 0
	global_load_lds_dwordx4 v130, s[100:101]
	s_waitcnt vmcnt(8) lgkmcnt(0)

; #define PG8_MMA(ai, bj, At, Bt) do { __builtin_amdgcn_s_setprio(1); _Pragma("unroll") for (int m = 0; m < 4; ++m) _Pragma("unroll") for (int n = 0; n < 2; ++n) _Pragma("unroll") for (int k = 0; k < 2; ++k) \
;         acc[ai][bj][m][n] = __builtin_amdgcn_mfma_f32_16x16x32_bf16(Bt[n][k], At[m][k], acc[ai][bj][m][n], 0, 0, 0); __builtin_amdgcn_s_setprio(0); } while (0)
; #define PG8_WAIT_V(n) asm volatile("s_waitcnt vmcnt(" #n ")" ::: "memory")
; #define PG8_WAIT_L(n) asm volatile("s_waitcnt lgkmcnt(" #n ")" ::: "memory")
; #define PG8_BAR __builtin_amdgcn_s_barrier()
; #define PG8_SCHED __builtin_amdgcn_sched_barrier(0)
; template <class Epi>
; __device__ __forceinline__ void gemm_phase(LAS unsigned char* lds, const Gemm g, const StaticOrder& S, const Epi& E) {
;     ...
;             PG8_WAIT_V(8); PG8_WAIT_L(0); PG8_BAR; PG8_MMA(1, 0, At, B0); PG8_MMA(1, 1, At, B1); PG8_BAR; PG8_SCHED;
	s_setprio 1
	s_barrier

	v_mfma_f32_16x16x32_bf16 v[60:63], v[144:147], v[192:195], v[60:63]
	v_mfma_f32_16x16x32_bf16 v[56:59], v[162:165], v[192:195], v[56:59]
	v_mfma_f32_16x16x32_bf16 v[44:47], v[144:147], v[200:203], v[44:47]
	v_mfma_f32_16x16x32_bf16 v[40:43], v[162:165], v[200:203], v[40:43]
	v_mfma_f32_16x16x32_bf16 v[28:31], v[144:147], v[208:211], v[28:31]
	v_mfma_f32_16x16x32_bf16 v[24:27], v[162:165], v[208:211], v[24:27]
	v_mfma_f32_16x16x32_bf16 v[12:15], v[144:147], v[216:219], v[12:15]
	v_mfma_f32_16x16x32_bf16 v[8:11], v[162:165], v[216:219], v[8:11]
	v_mfma_f32_16x16x32_bf16 v[60:63], v[148:151], v[196:199], v[60:63]
	v_mfma_f32_16x16x32_bf16 v[56:59], v[166:169], v[196:199], v[56:59]
	v_mfma_f32_16x16x32_bf16 v[44:47], v[148:151], v[204:207], v[44:47]
	v_mfma_f32_16x16x32_bf16 v[40:43], v[166:169], v[204:207], v[40:43]
	v_mfma_f32_16x16x32_bf16 v[28:31], v[148:151], v[212:215], v[28:31]
	v_mfma_f32_16x16x32_bf16 v[24:27], v[166:169], v[212:215], v[24:27]
	v_mfma_f32_16x16x32_bf16 v[12:15], v[148:151], v[220:223], v[12:15]
	v_mfma_f32_16x16x32_bf16 v[8:11], v[166:169], v[220:223], v[8:11]


; #define PG8_BAR __builtin_amdgcn_s_barrier()
; template <class Epi>
; __device__ __forceinline__ void gemm_phase(LAS unsigned char* lds, const Gemm g, const StaticOrder& S, const Epi& E) {
;     ...
;         for (int t = 0; t < nt; t += 2) {
;     ...
;         if (wr == 0) PG8_BAR;
	v_mfma_f32_16x16x32_bf16 v[52:55], v[170:173], v[192:195], v[52:55]
	v_mfma_f32_16x16x32_bf16 v[48:51], v[184:187], v[192:195], v[48:51]
	v_mfma_f32_16x16x32_bf16 v[36:39], v[170:173], v[200:203], v[36:39]
	v_mfma_f32_16x16x32_bf16 v[32:35], v[184:187], v[200:203], v[32:35]
	v_mfma_f32_16x16x32_bf16 v[20:23], v[170:173], v[208:211], v[20:23]
	v_mfma_f32_16x16x32_bf16 v[16:19], v[184:187], v[208:211], v[16:19]
	v_mfma_f32_16x16x32_bf16 v[4:7], v[170:173], v[216:219], v[4:7]
	v_mfma_f32_16x16x32_bf16 v[0:3], v[184:187], v[216:219], v[0:3]
	v_mfma_f32_16x16x32_bf16 v[52:55], v[174:177], v[196:199], v[52:55]
	v_mfma_f32_16x16x32_bf16 v[48:51], v[188:191], v[196:199], v[48:51]
	v_mfma_f32_16x16x32_bf16 v[36:39], v[174:177], v[204:207], v[36:39]
	v_mfma_f32_16x16x32_bf16 v[32:35], v[188:191], v[204:207], v[32:35]
	v_mfma_f32_16x16x32_bf16 v[20:23], v[174:177], v[212:215], v[20:23]
	v_mfma_f32_16x16x32_bf16 v[16:19], v[188:191], v[212:215], v[16:19]
	v_mfma_f32_16x16x32_bf16 v[4:7], v[174:177], v[220:223], v[4:7]
	v_mfma_f32_16x16x32_bf16 v[0:3], v[188:191], v[220:223], v[0:3]
	s_barrier
	s_setprio 0
	s_add_i32 s48, s48, 2
	s_add_u32 s38, s38, 0x100
	s_addc_u32 s39, s39, 0
	s_add_u32 s46, s46, 0x100
	s_addc_u32 s47, s47, 0
	s_cmp_gt_u32 s48, 13
	s_cbranch_scc0 .LBB0_1350
	s_and_b64 vcc, exec, s[12:13]
	s_cbranch_vccz .LBB0_1353
	s_barrier

; #define PG8_STAGE(bufoff, gbase, voff) do { _Pragma("unroll") for (int _i = 0; _i < 2; ++_i) \
;         __builtin_amdgcn_global_load_lds((const unsigned*)((const char*)(gbase) + (voff)[_i]), (LAS unsigned*)(lds + (bufoff) + ldsw + _i * 8192), 16, 0, 0); } while (0)
; #define PG8_LDA(dst, b, h) do { _Pragma("unroll") for (int m = 0; m < 4; ++m) _Pragma("unroll") for (int k = 0; k < 2; ++k) dst[m][k] = *(const LAS bf16x8*)(lds + PG8_SA(b, h) + aoff + m * 2048 + k * 1024); } while (0)
; #define PG8_LDB(dst, b, h) do { _Pragma("unroll") for (int n = 0; n < 2; ++n) _Pragma("unroll") for (int k = 0; k < 2; ++k) dst[n][k] = *(const LAS bf16x8*)(lds + PG8_SB(b, h) + boff + n * 2048 + k * 1024); } while (0)
; #define PG8_SCHED __builtin_amdgcn_sched_barrier(0)
; template <class Epi>
; __device__ __forceinline__ void gemm_phase(LAS unsigned char* lds, const Gemm g, const StaticOrder& S, const Epi& E) {
;     ...
;             const bool last = (t == nt - 2);
;             if constexpr (Epi::HAS_MID) { if (t == nt1) E.mid(acc, cur, wr, wc, fr, fq); }
;             const char* a1 = cA + ((Epi::HAS_MID && t >= nt1) ? dA2 : 0) + (size_t)(t + 1) * kstep;
;             const char* a2 = last ? nA : cA + ((Epi::HAS_MID && t + 2 >= nt1) ? dA2 : 0) + (size_t)(t + 2) * kstep; const char* b2 = last ? nB : cB + ((Epi::HAS_MID && t + 2 >= nt1) ? dB2 : 0) + (size_t)(t + 2) * kstep;
;             const char* a3 = a2 + kstep; const char* b3 = b2 + kstep;
;             PG8_LDB(B0, 0, 0); PG8_LDB(B1, 0, 1); PG8_SCHED; PG8_LDA(At, 0, 0); PG8_STAGE(PG8_SA(1, 1), a1 + hsA, voffA);
.LBB0_1433:
	ds_read_b128 v[144:147], v202
	ds_read_b128 v[148:151], v202 offset:1024
	ds_read_b128 v[152:155], v202 offset:2048
	ds_read_b128 v[156:159], v202 offset:3072
	ds_read_b128 v[160:163], v203
	ds_read_b128 v[164:167], v203 offset:1024
	ds_read_b128 v[168:171], v203 offset:2048
	ds_read_b128 v[172:175], v203 offset:3072
	s_add_u32 s34, s26, 0x100
	s_addc_u32 s35, s27, 0
	s_cmp_eq_u32 s51, 40
	s_cselect_b32 s39, s1, s35
	s_cselect_b32 s38, s0, s34
	s_cselect_b32 s37, s23, s50
	s_cselect_b32 s36, s22, s25
	s_add_i32 m0, s17, 0xc000
	ds_read_b128 v[216:219], v204
	ds_read_b128 v[220:223], v204 offset:1024
	ds_read_b128 v[224:227], v204 offset:2048
	ds_read_b128 v[228:231], v204 offset:3072
	ds_read_b128 v[232:235], v204 offset:4096
	ds_read_b128 v[236:239], v204 offset:5120
	ds_read_b128 v[240:243], v204 offset:6144
	ds_read_b128 v[244:247], v204 offset:7168
	global_load_lds_dwordx4 v136, s[26:27]
	s_add_i32 m0, s17, 0xe000
	s_nop 0
	global_load_lds_dwordx4 v138, s[26:27]
	s_waitcnt vmcnt(8) lgkmcnt(0)

; #define PG8_MMA(ai, bj, At, Bt) do { __builtin_amdgcn_s_setprio(1); _Pragma("unroll") for (int m = 0; m < 4; ++m) _Pragma("unroll") for (int n = 0; n < 2; ++n) _Pragma("unroll") for (int k = 0; k < 2; ++k) \
;         acc[ai][bj][m][n] = __builtin_amdgcn_mfma_f32_16x16x32_bf16(Bt[n][k], At[m][k], acc[ai][bj][m][n], 0, 0, 0); __builtin_amdgcn_s_setprio(0); } while (0)
; #define PG8_WAIT_V(n) asm volatile("s_waitcnt vmcnt(" #n ")" ::: "memory")
; #define PG8_WAIT_L(n) asm volatile("s_waitcnt lgkmcnt(" #n ")" ::: "memory")
; #define PG8_BAR __builtin_amdgcn_s_barrier()
; #define PG8_SCHED __builtin_amdgcn_sched_barrier(0)
; template <class Epi>
; __device__ __forceinline__ void gemm_phase(LAS unsigned char* lds, const Gemm g, const StaticOrder& S, const Epi& E) {
;     ...
;             PG8_WAIT_V(8); PG8_WAIT_L(0); PG8_BAR; PG8_MMA(0, 0, At, B0); PG8_MMA(0, 1, At, B1); PG8_BAR; PG8_SCHED;
	s_setprio 1
	s_barrier

	v_mfma_f32_16x16x32_bf16 v[124:127], v[144:147], v[216:219], v[124:127]
	v_mfma_f32_16x16x32_bf16 v[120:123], v[152:155], v[216:219], v[120:123]
	v_mfma_f32_16x16x32_bf16 v[108:111], v[144:147], v[224:227], v[108:111]
	v_mfma_f32_16x16x32_bf16 v[104:107], v[152:155], v[224:227], v[104:107]
	v_mfma_f32_16x16x32_bf16 v[92:95], v[144:147], v[232:235], v[92:95]
	v_mfma_f32_16x16x32_bf16 v[88:91], v[152:155], v[232:235], v[88:91]
	v_mfma_f32_16x16x32_bf16 v[76:79], v[144:147], v[240:243], v[76:79]
	v_mfma_f32_16x16x32_bf16 v[72:75], v[152:155], v[240:243], v[72:75]
	v_mfma_f32_16x16x32_bf16 v[124:127], v[148:151], v[220:223], v[124:127]
	v_mfma_f32_16x16x32_bf16 v[120:123], v[156:159], v[220:223], v[120:123]
	v_mfma_f32_16x16x32_bf16 v[108:111], v[148:151], v[228:231], v[108:111]
	v_mfma_f32_16x16x32_bf16 v[104:107], v[156:159], v[228:231], v[104:107]
	v_mfma_f32_16x16x32_bf16 v[92:95], v[148:151], v[236:239], v[92:95]
	v_mfma_f32_16x16x32_bf16 v[88:91], v[156:159], v[236:239], v[88:91]
	v_mfma_f32_16x16x32_bf16 v[76:79], v[148:151], v[244:247], v[76:79]
	v_mfma_f32_16x16x32_bf16 v[72:75], v[156:159], v[244:247], v[72:75]


; #define PG8_STAGE(bufoff, gbase, voff) do { _Pragma("unroll") for (int _i = 0; _i < 2; ++_i) \
;         __builtin_amdgcn_global_load_lds((const unsigned*)((const char*)(gbase) + (voff)[_i]), (LAS unsigned*)(lds + (bufoff) + ldsw + _i * 8192), 16, 0, 0); } while (0)
; #define PG8_LDA(dst, b, h) do { _Pragma("unroll") for (int m = 0; m < 4; ++m) _Pragma("unroll") for (int k = 0; k < 2; ++k) dst[m][k] = *(const LAS bf16x8*)(lds + PG8_SA(b, h) + aoff + m * 2048 + k * 1024); } while (0)
; template <class Epi>
; __device__ __forceinline__ void gemm_phase(LAS unsigned char* lds, const Gemm g, const StaticOrder& S, const Epi& E) {
;     ...
;             PG8_LDA(At, 0, 1); PG8_STAGE(PG8_SB(0, 0), b2, voffB); PG8_STAGE(PG8_SB(0, 1), b2 + hsB, voffB); PG8_STAGE(PG8_SA(0, 0), a2, voffA);
	v_mfma_f32_16x16x32_bf16 v[116:119], v[160:163], v[216:219], v[116:119]
	v_mfma_f32_16x16x32_bf16 v[112:115], v[168:171], v[216:219], v[112:115]
	v_mfma_f32_16x16x32_bf16 v[100:103], v[160:163], v[224:227], v[100:103]
	v_mfma_f32_16x16x32_bf16 v[96:99], v[168:171], v[224:227], v[96:99]
	v_mfma_f32_16x16x32_bf16 v[84:87], v[160:163], v[232:235], v[84:87]
	v_mfma_f32_16x16x32_bf16 v[80:83], v[168:171], v[232:235], v[80:83]
	v_mfma_f32_16x16x32_bf16 v[68:71], v[160:163], v[240:243], v[68:71]
	v_mfma_f32_16x16x32_bf16 v[64:67], v[168:171], v[240:243], v[64:67]
	v_mfma_f32_16x16x32_bf16 v[116:119], v[164:167], v[220:223], v[116:119]
	v_mfma_f32_16x16x32_bf16 v[112:115], v[172:175], v[220:223], v[112:115]
	v_mfma_f32_16x16x32_bf16 v[100:103], v[164:167], v[228:231], v[100:103]
	v_mfma_f32_16x16x32_bf16 v[96:99], v[172:175], v[228:231], v[96:99]
	v_mfma_f32_16x16x32_bf16 v[84:87], v[164:167], v[236:239], v[84:87]
	v_mfma_f32_16x16x32_bf16 v[80:83], v[172:175], v[236:239], v[80:83]
	v_mfma_f32_16x16x32_bf16 v[68:71], v[164:167], v[244:247], v[68:71]
	v_mfma_f32_16x16x32_bf16 v[64:67], v[172:175], v[244:247], v[64:67]
	s_barrier
	s_setprio 0
	s_add_i32 s26, s45, s16
	s_mov_b32 m0, s26
	ds_read_b128 v[216:219], v204 offset:16384
	ds_read_b128 v[220:223], v204 offset:17408
	ds_read_b128 v[224:227], v204 offset:18432
	ds_read_b128 v[228:231], v204 offset:19456
	ds_read_b128 v[232:235], v204 offset:20480
	ds_read_b128 v[236:239], v204 offset:21504
	ds_read_b128 v[240:243], v204 offset:22528
	ds_read_b128 v[244:247], v204 offset:23552
	global_load_lds_dwordx4 v130, s[36:37]
	s_add_i32 m0, s26, 0x2000
	s_add_u32 s26, s36, 0xb0000
	s_addc_u32 s27, s37, 0
	s_add_i32 s52, s46, s16
	global_load_lds_dwordx4 v134, s[36:37]
	s_mov_b32 m0, s52
	s_nop 0
	global_load_lds_dwordx4 v130, s[26:27]
	s_add_i32 m0, s52, 0x2000
	s_nop 0
	global_load_lds_dwordx4 v134, s[26:27]
	s_mov_b32 m0, s17
	s_nop 0
	global_load_lds_dwordx4 v128, s[38:39]
	s_mov_b32 m0, s28
	s_nop 0
	global_load_lds_dwordx4 v132, s[38:39]
	s_waitcnt vmcnt(8) lgkmcnt(0)

; #define PG8_MMA(ai, bj, At, Bt) do { __builtin_amdgcn_s_setprio(1); _Pragma("unroll") for (int m = 0; m < 4; ++m) _Pragma("unroll") for (int n = 0; n < 2; ++n) _Pragma("unroll") for (int k = 0; k < 2; ++k) \
;         acc[ai][bj][m][n] = __builtin_amdgcn_mfma_f32_16x16x32_bf16(Bt[n][k], At[m][k], acc[ai][bj][m][n], 0, 0, 0); __builtin_amdgcn_s_setprio(0); } while (0)
; #define PG8_WAIT_V(n) asm volatile("s_waitcnt vmcnt(" #n ")" ::: "memory")
; #define PG8_WAIT_L(n) asm volatile("s_waitcnt lgkmcnt(" #n ")" ::: "memory")
; #define PG8_BAR __builtin_amdgcn_s_barrier()
; #define PG8_SCHED __builtin_amdgcn_sched_barrier(0)
; template <class Epi>
; __device__ __forceinline__ void gemm_phase(LAS unsigned char* lds, const Gemm g, const StaticOrder& S, const Epi& E) {
;     ...
;             PG8_WAIT_V(8); PG8_WAIT_L(0); PG8_BAR; PG8_MMA(1, 0, At, B0); PG8_MMA(1, 1, At, B1); PG8_BAR; PG8_SCHED;
	s_setprio 1
	s_barrier

	v_mfma_f32_16x16x32_bf16 v[60:63], v[144:147], v[216:219], v[60:63]
	v_mfma_f32_16x16x32_bf16 v[56:59], v[152:155], v[216:219], v[56:59]
	v_mfma_f32_16x16x32_bf16 v[44:47], v[144:147], v[224:227], v[44:47]
	v_mfma_f32_16x16x32_bf16 v[40:43], v[152:155], v[224:227], v[40:43]
	v_mfma_f32_16x16x32_bf16 v[28:31], v[144:147], v[232:235], v[28:31]
	v_mfma_f32_16x16x32_bf16 v[24:27], v[152:155], v[232:235], v[24:27]
	v_mfma_f32_16x16x32_bf16 v[12:15], v[144:147], v[240:243], v[12:15]
	v_mfma_f32_16x16x32_bf16 v[8:11], v[152:155], v[240:243], v[8:11]
	v_mfma_f32_16x16x32_bf16 v[60:63], v[148:151], v[220:223], v[60:63]
	v_mfma_f32_16x16x32_bf16 v[56:59], v[156:159], v[220:223], v[56:59]
	v_mfma_f32_16x16x32_bf16 v[44:47], v[148:151], v[228:231], v[44:47]
	v_mfma_f32_16x16x32_bf16 v[40:43], v[156:159], v[228:231], v[40:43]
	v_mfma_f32_16x16x32_bf16 v[28:31], v[148:151], v[236:239], v[28:31]
	v_mfma_f32_16x16x32_bf16 v[24:27], v[156:159], v[236:239], v[24:27]
	v_mfma_f32_16x16x32_bf16 v[12:15], v[148:151], v[244:247], v[12:15]
	v_mfma_f32_16x16x32_bf16 v[8:11], v[156:159], v[244:247], v[8:11]


; #define PG8_STAGE(bufoff, gbase, voff) do { _Pragma("unroll") for (int _i = 0; _i < 2; ++_i) \
;         __builtin_amdgcn_global_load_lds((const unsigned*)((const char*)(gbase) + (voff)[_i]), (LAS unsigned*)(lds + (bufoff) + ldsw + _i * 8192), 16, 0, 0); } while (0)
; #define PG8_LDA(dst, b, h) do { _Pragma("unroll") for (int m = 0; m < 4; ++m) _Pragma("unroll") for (int k = 0; k < 2; ++k) dst[m][k] = *(const LAS bf16x8*)(lds + PG8_SA(b, h) + aoff + m * 2048 + k * 1024); } while (0)
; #define PG8_LDB(dst, b, h) do { _Pragma("unroll") for (int n = 0; n < 2; ++n) _Pragma("unroll") for (int k = 0; k < 2; ++k) dst[n][k] = *(const LAS bf16x8*)(lds + PG8_SB(b, h) + boff + n * 2048 + k * 1024); } while (0)
; #define PG8_SCHED __builtin_amdgcn_sched_barrier(0)
; template <class Epi>
; __device__ __forceinline__ void gemm_phase(LAS unsigned char* lds, const Gemm g, const StaticOrder& S, const Epi& E) {
;     ...
;             PG8_LDB(B0, 1, 0); PG8_LDB(B1, 1, 1); PG8_SCHED; PG8_LDA(At, 1, 0); PG8_STAGE(PG8_SA(0, 1), a2 + hsA, voffA);
	v_mfma_f32_16x16x32_bf16 v[52:55], v[160:163], v[216:219], v[52:55]
	v_mfma_f32_16x16x32_bf16 v[48:51], v[168:171], v[216:219], v[48:51]
	v_mfma_f32_16x16x32_bf16 v[36:39], v[160:163], v[224:227], v[36:39]
	v_mfma_f32_16x16x32_bf16 v[32:35], v[168:171], v[224:227], v[32:35]
	v_mfma_f32_16x16x32_bf16 v[20:23], v[160:163], v[232:235], v[20:23]
	v_mfma_f32_16x16x32_bf16 v[16:19], v[168:171], v[232:235], v[16:19]
	v_mfma_f32_16x16x32_bf16 v[4:7], v[160:163], v[240:243], v[4:7]
	v_mfma_f32_16x16x32_bf16 v[0:3], v[168:171], v[240:243], v[0:3]
	v_mfma_f32_16x16x32_bf16 v[52:55], v[164:167], v[220:223], v[52:55]
	v_mfma_f32_16x16x32_bf16 v[48:51], v[172:175], v[220:223], v[48:51]
	v_mfma_f32_16x16x32_bf16 v[36:39], v[164:167], v[228:231], v[36:39]
	v_mfma_f32_16x16x32_bf16 v[32:35], v[172:175], v[228:231], v[32:35]
	v_mfma_f32_16x16x32_bf16 v[20:23], v[164:167], v[236:239], v[20:23]
	v_mfma_f32_16x16x32_bf16 v[16:19], v[172:175], v[236:239], v[16:19]
	v_mfma_f32_16x16x32_bf16 v[4:7], v[164:167], v[244:247], v[4:7]
	v_mfma_f32_16x16x32_bf16 v[0:3], v[172:175], v[244:247], v[0:3]
	s_barrier
	s_setprio 0
	s_add_i32 s52, 0, 0x18000
	s_add_i32 s53, 0, 0x1c000
	v_add_u32_e32 v156, s52, v184
	v_add_u32_e32 v172, s53, v184
	ds_read_b128 v[144:147], v156
	ds_read_b128 v[148:151], v156 offset:1024
	ds_read_b128 v[152:155], v156 offset:2048
	ds_read_b128 v[156:159], v156 offset:3072
	ds_read_b128 v[160:163], v172
	ds_read_b128 v[164:167], v172 offset:1024
	ds_read_b128 v[168:171], v172 offset:2048
	ds_read_b128 v[172:175], v172 offset:3072
	s_add_u32 s26, s38, 0xb0000
	s_addc_u32 s27, s39, 0
	s_mov_b32 m0, s29
	ds_read_b128 v[216:219], v204 offset:32768
	ds_read_b128 v[220:223], v204 offset:33792
	ds_read_b128 v[224:227], v204 offset:34816
	ds_read_b128 v[228:231], v204 offset:35840
	ds_read_b128 v[232:235], v204 offset:36864
	ds_read_b128 v[236:239], v204 offset:37888
	ds_read_b128 v[240:243], v204 offset:38912
	ds_read_b128 v[244:247], v204 offset:39936
	global_load_lds_dwordx4 v128, s[26:27]
	s_mov_b32 m0, s30
	s_nop 0
	global_load_lds_dwordx4 v132, s[26:27]
	s_waitcnt vmcnt(8) lgkmcnt(0)

; #define PG8_MMA(ai, bj, At, Bt) do { __builtin_amdgcn_s_setprio(1); _Pragma("unroll") for (int m = 0; m < 4; ++m) _Pragma("unroll") for (int n = 0; n < 2; ++n) _Pragma("unroll") for (int k = 0; k < 2; ++k) \
;         acc[ai][bj][m][n] = __builtin_amdgcn_mfma_f32_16x16x32_bf16(Bt[n][k], At[m][k], acc[ai][bj][m][n], 0, 0, 0); __builtin_amdgcn_s_setprio(0); } while (0)
; #define PG8_WAIT_V(n) asm volatile("s_waitcnt vmcnt(" #n ")" ::: "memory")
; #define PG8_WAIT_L(n) asm volatile("s_waitcnt lgkmcnt(" #n ")" ::: "memory")
; #define PG8_BAR __builtin_amdgcn_s_barrier()
; #define PG8_SCHED __builtin_amdgcn_sched_barrier(0)
; template <class Epi>
; __device__ __forceinline__ void gemm_phase(LAS unsigned char* lds, const Gemm g, const StaticOrder& S, const Epi& E) {
;     ...
;             PG8_WAIT_V(8); PG8_WAIT_L(0); PG8_BAR; PG8_MMA(0, 0, At, B0); PG8_MMA(0, 1, At, B1); PG8_BAR; PG8_SCHED;
	s_setprio 1
	s_barrier

	v_mfma_f32_16x16x32_bf16 v[124:127], v[144:147], v[216:219], v[124:127]
	v_mfma_f32_16x16x32_bf16 v[120:123], v[152:155], v[216:219], v[120:123]
	v_mfma_f32_16x16x32_bf16 v[108:111], v[144:147], v[224:227], v[108:111]
	v_mfma_f32_16x16x32_bf16 v[104:107], v[152:155], v[224:227], v[104:107]
	v_mfma_f32_16x16x32_bf16 v[92:95], v[144:147], v[232:235], v[92:95]
	v_mfma_f32_16x16x32_bf16 v[88:91], v[152:155], v[232:235], v[88:91]
	v_mfma_f32_16x16x32_bf16 v[76:79], v[144:147], v[240:243], v[76:79]
	v_mfma_f32_16x16x32_bf16 v[72:75], v[152:155], v[240:243], v[72:75]
	v_mfma_f32_16x16x32_bf16 v[124:127], v[148:151], v[220:223], v[124:127]
	v_mfma_f32_16x16x32_bf16 v[120:123], v[156:159], v[220:223], v[120:123]
	v_mfma_f32_16x16x32_bf16 v[108:111], v[148:151], v[228:231], v[108:111]
	v_mfma_f32_16x16x32_bf16 v[104:107], v[156:159], v[228:231], v[104:107]
	v_mfma_f32_16x16x32_bf16 v[92:95], v[148:151], v[236:239], v[92:95]
	v_mfma_f32_16x16x32_bf16 v[88:91], v[156:159], v[236:239], v[88:91]
	v_mfma_f32_16x16x32_bf16 v[76:79], v[148:151], v[244:247], v[76:79]
	v_mfma_f32_16x16x32_bf16 v[72:75], v[156:159], v[244:247], v[72:75]


; #define PG8_STAGE(bufoff, gbase, voff) do { _Pragma("unroll") for (int _i = 0; _i < 2; ++_i) \
;         __builtin_amdgcn_global_load_lds((const unsigned*)((const char*)(gbase) + (voff)[_i]), (LAS unsigned*)(lds + (bufoff) + ldsw + _i * 8192), 16, 0, 0); } while (0)
; #define PG8_LDA(dst, b, h) do { _Pragma("unroll") for (int m = 0; m < 4; ++m) _Pragma("unroll") for (int k = 0; k < 2; ++k) dst[m][k] = *(const LAS bf16x8*)(lds + PG8_SA(b, h) + aoff + m * 2048 + k * 1024); } while (0)
; template <class Epi>
; __device__ __forceinline__ void gemm_phase(LAS unsigned char* lds, const Gemm g, const StaticOrder& S, const Epi& E) {
;     ...
;             PG8_LDA(At, 1, 1); PG8_STAGE(PG8_SB(1, 0), b3, voffB); PG8_STAGE(PG8_SB(1, 1), b3 + hsB, voffB); PG8_STAGE(PG8_SA(1, 0), a3, voffA);
	v_mfma_f32_16x16x32_bf16 v[116:119], v[160:163], v[216:219], v[116:119]
	v_mfma_f32_16x16x32_bf16 v[112:115], v[168:171], v[216:219], v[112:115]
	v_mfma_f32_16x16x32_bf16 v[100:103], v[160:163], v[224:227], v[100:103]
	v_mfma_f32_16x16x32_bf16 v[96:99], v[168:171], v[224:227], v[96:99]
	v_mfma_f32_16x16x32_bf16 v[84:87], v[160:163], v[232:235], v[84:87]
	v_mfma_f32_16x16x32_bf16 v[80:83], v[168:171], v[232:235], v[80:83]
	v_mfma_f32_16x16x32_bf16 v[68:71], v[160:163], v[240:243], v[68:71]
	v_mfma_f32_16x16x32_bf16 v[64:67], v[168:171], v[240:243], v[64:67]
	v_mfma_f32_16x16x32_bf16 v[116:119], v[164:167], v[220:223], v[116:119]
	v_mfma_f32_16x16x32_bf16 v[112:115], v[172:175], v[220:223], v[112:115]
	v_mfma_f32_16x16x32_bf16 v[100:103], v[164:167], v[228:231], v[100:103]
	v_mfma_f32_16x16x32_bf16 v[96:99], v[172:175], v[228:231], v[96:99]
	v_mfma_f32_16x16x32_bf16 v[84:87], v[164:167], v[236:239], v[84:87]
	v_mfma_f32_16x16x32_bf16 v[80:83], v[172:175], v[236:239], v[80:83]
	v_mfma_f32_16x16x32_bf16 v[68:71], v[164:167], v[244:247], v[68:71]
	v_mfma_f32_16x16x32_bf16 v[64:67], v[172:175], v[244:247], v[64:67]
	s_barrier
	s_setprio 0
	s_add_u32 s98, s36, 0x80
	s_addc_u32 s99, s37, 0
	s_add_u32 s100, s38, 0x80
	s_addc_u32 s101, s39, 0
	s_add_i32 s26, s52, s16
	s_mov_b32 m0, s26
	ds_read_b128 v[216:219], v204 offset:49152
	ds_read_b128 v[220:223], v204 offset:50176
	ds_read_b128 v[224:227], v204 offset:51200
	ds_read_b128 v[228:231], v204 offset:52224
	ds_read_b128 v[232:235], v204 offset:53248
	ds_read_b128 v[236:239], v204 offset:54272
	ds_read_b128 v[240:243], v204 offset:55296
	ds_read_b128 v[244:247], v204 offset:56320
	global_load_lds_dwordx4 v130, s[98:99]
	s_add_i32 m0, s26, 0x2000
	s_add_u32 s26, s36, 0xb0080
	s_addc_u32 s27, s37, 0
	s_add_i32 s36, s53, s16
	global_load_lds_dwordx4 v134, s[98:99]
	s_mov_b32 m0, s36
	s_nop 0
	global_load_lds_dwordx4 v130, s[26:27]
	s_add_i32 m0, s36, 0x2000
	s_nop 0
	global_load_lds_dwordx4 v134, s[26:27]
	s_mov_b32 m0, s41
	s_nop 0
	global_load_lds_dwordx4 v128, s[100:101]
	s_mov_b32 m0, s42
	s_nop 0
	global_load_lds_dwordx4 v132, s[100:101]
	s_waitcnt vmcnt(8) lgkmcnt(0)

; #define PG8_MMA(ai, bj, At, Bt) do { __builtin_amdgcn_s_setprio(1); _Pragma("unroll") for (int m = 0; m < 4; ++m) _Pragma("unroll") for (int n = 0; n < 2; ++n) _Pragma("unroll") for (int k = 0; k < 2; ++k) \
;         acc[ai][bj][m][n] = __builtin_amdgcn_mfma_f32_16x16x32_bf16(Bt[n][k], At[m][k], acc[ai][bj][m][n], 0, 0, 0); __builtin_amdgcn_s_setprio(0); } while (0)
; #define PG8_WAIT_V(n) asm volatile("s_waitcnt vmcnt(" #n ")" ::: "memory")
; #define PG8_WAIT_L(n) asm volatile("s_waitcnt lgkmcnt(" #n ")" ::: "memory")
; #define PG8_BAR __builtin_amdgcn_s_barrier()
; #define PG8_SCHED __builtin_amdgcn_sched_barrier(0)
; template <class Epi>
; __device__ __forceinline__ void gemm_phase(LAS unsigned char* lds, const Gemm g, const StaticOrder& S, const Epi& E) {
;     ...
;             PG8_WAIT_V(8); PG8_WAIT_L(0); PG8_BAR; PG8_MMA(1, 0, At, B0); PG8_MMA(1, 1, At, B1); PG8_BAR; PG8_SCHED;
	s_setprio 1
	s_barrier

	v_mfma_f32_16x16x32_bf16 v[60:63], v[144:147], v[216:219], v[60:63]
	v_mfma_f32_16x16x32_bf16 v[56:59], v[152:155], v[216:219], v[56:59]
	v_mfma_f32_16x16x32_bf16 v[44:47], v[144:147], v[224:227], v[44:47]
	v_mfma_f32_16x16x32_bf16 v[40:43], v[152:155], v[224:227], v[40:43]
	v_mfma_f32_16x16x32_bf16 v[28:31], v[144:147], v[232:235], v[28:31]
	v_mfma_f32_16x16x32_bf16 v[24:27], v[152:155], v[232:235], v[24:27]
	v_mfma_f32_16x16x32_bf16 v[12:15], v[144:147], v[240:243], v[12:15]
	v_mfma_f32_16x16x32_bf16 v[8:11], v[152:155], v[240:243], v[8:11]
	v_mfma_f32_16x16x32_bf16 v[60:63], v[148:151], v[220:223], v[60:63]
	v_mfma_f32_16x16x32_bf16 v[56:59], v[156:159], v[220:223], v[56:59]
	v_mfma_f32_16x16x32_bf16 v[44:47], v[148:151], v[228:231], v[44:47]
	v_mfma_f32_16x16x32_bf16 v[40:43], v[156:159], v[228:231], v[40:43]
	v_mfma_f32_16x16x32_bf16 v[28:31], v[148:151], v[236:239], v[28:31]
	v_mfma_f32_16x16x32_bf16 v[24:27], v[156:159], v[236:239], v[24:27]
	v_mfma_f32_16x16x32_bf16 v[12:15], v[148:151], v[244:247], v[12:15]
	v_mfma_f32_16x16x32_bf16 v[8:11], v[156:159], v[244:247], v[8:11]


; #define PG8_BAR __builtin_amdgcn_s_barrier()
; template <class Epi>
; __device__ __forceinline__ void gemm_phase(LAS unsigned char* lds, const Gemm g, const StaticOrder& S, const Epi& E) {
;     ...
;         for (int t = 0; t < nt; t += 2) {
;     ...
;         if (wr == 0) PG8_BAR;
	v_mfma_f32_16x16x32_bf16 v[52:55], v[160:163], v[216:219], v[52:55]
	v_mfma_f32_16x16x32_bf16 v[48:51], v[168:171], v[216:219], v[48:51]
	v_mfma_f32_16x16x32_bf16 v[36:39], v[160:163], v[224:227], v[36:39]
	v_mfma_f32_16x16x32_bf16 v[32:35], v[168:171], v[224:227], v[32:35]
	v_mfma_f32_16x16x32_bf16 v[20:23], v[160:163], v[232:235], v[20:23]
	v_mfma_f32_16x16x32_bf16 v[16:19], v[168:171], v[232:235], v[16:19]
	v_mfma_f32_16x16x32_bf16 v[4:7], v[160:163], v[240:243], v[4:7]
	v_mfma_f32_16x16x32_bf16 v[0:3], v[168:171], v[240:243], v[0:3]
	v_mfma_f32_16x16x32_bf16 v[52:55], v[164:167], v[220:223], v[52:55]
	v_mfma_f32_16x16x32_bf16 v[48:51], v[172:175], v[220:223], v[48:51]
	v_mfma_f32_16x16x32_bf16 v[36:39], v[164:167], v[228:231], v[36:39]
	v_mfma_f32_16x16x32_bf16 v[32:35], v[172:175], v[228:231], v[32:35]
	v_mfma_f32_16x16x32_bf16 v[20:23], v[164:167], v[236:239], v[20:23]
	v_mfma_f32_16x16x32_bf16 v[16:19], v[172:175], v[236:239], v[16:19]
	v_mfma_f32_16x16x32_bf16 v[4:7], v[164:167], v[244:247], v[4:7]
	v_mfma_f32_16x16x32_bf16 v[0:3], v[172:175], v[244:247], v[0:3]
	s_barrier
	s_setprio 0
	s_add_i32 s51, s51, 2
	s_add_u32 s25, s25, 0x100
	s_addc_u32 s50, s50, 0
	s_cmp_gt_u32 s51, 41
	s_mov_b64 s[26:27], s[34:35]
	s_cbranch_scc0 .LBB0_1433
	s_and_b64 vcc, exec, s[18:19]
	s_cbranch_vccz .LBB0_1436
	s_barrier
